# v28 with the required s_nop 0 pads restored between M0 writes and LDS-DMA loads (12 sites)
# speedup vs baseline: 1.0008x; 1.0008x over previous
; #define PG8_STAGE(bufoff, gbase, voff) do { _Pragma("unroll") for (int _i = 0; _i < 2; ++_i) \
;         __builtin_amdgcn_global_load_lds((const unsigned*)((const char*)(gbase) + (voff)[_i]), (LAS unsigned*)(lds + (bufoff) + ldsw + _i * 8192), 16, 0, 0); } while (0)
; #define PG8_LDA(dst, b, h) do { _Pragma("unroll") for (int m = 0; m < 4; ++m) _Pragma("unroll") for (int k = 0; k < 2; ++k) dst[m][k] = *(const LAS bf16x8*)(lds + PG8_SA(b, h) + aoff + m * 2048 + k * 1024); } while (0)
; #define PG8_LDB(dst, b, h) do { _Pragma("unroll") for (int n = 0; n < 2; ++n) _Pragma("unroll") for (int k = 0; k < 2; ++k) dst[n][k] = *(const LAS bf16x8*)(lds + PG8_SB(b, h) + boff + n * 2048 + k * 1024); } while (0)
; #define PG8_MMA(ai, bj, At, Bt) do { __builtin_amdgcn_s_setprio(1); _Pragma("unroll") for (int m = 0; m < 4; ++m) _Pragma("unroll") for (int n = 0; n < 2; ++n) _Pragma("unroll") for (int k = 0; k < 2; ++k) \
;         acc[ai][bj][m][n] = __builtin_amdgcn_mfma_f32_16x16x32_bf16(Bt[n][k], At[m][k], acc[ai][bj][m][n], 0, 0, 0); __builtin_amdgcn_s_setprio(0); } while (0)
; #define PG8_WAIT_V(n) asm volatile("s_waitcnt vmcnt(" #n ")" ::: "memory")
; #define PG8_WAIT_L(n) asm volatile("s_waitcnt lgkmcnt(" #n ")" ::: "memory")
; #define PG8_BAR __builtin_amdgcn_s_barrier()
; template <class Epi, class Sched, bool ALIGN_EPI = false, bool SP2 = false>
; __device__ __forceinline__ void gemm_phase(LAS unsigned char* lds, const Gemm g, const Sched& S, const Epi& E) {
;     ...
;             const bool last = (t == nt - 2);
;             const char* a1 = cA + (size_t)(t + 1) * kstep;
;             const char* a2 = last ? nA : cA + (size_t)(t + 2) * kstep; const char* b2 = last ? nB : cB + (size_t)(t + 2) * kstep;
;             const char* a3 = a2 + kstep; const char* b3 = b2 + kstep;
;             if (last && has_next) S.a_ready(nxt);
;             if constexpr (SP2) {
;             PG8_LDB(B0, 0, 0); PG8_LDB(B1, 0, 1); PG8_SCHED; PG8_LDA(At, 0, 0); PG8_STAGE(PG8_SA(1, 1), a1 + hstep, voffA);
;             PG8_WAIT_V(8); PG8_WAIT_L(0); PG8_BAR; PG8_MMA(0, 0, At, B0); PG8_MMA(0, 1, At, B1); PG8_BAR; PG8_SCHED;
;             PG8_LDA(At, 0, 1); PG8_STAGE(PG8_SB(0, 0), b2, voffB); PG8_STAGE(PG8_SB(0, 1), b2 + hstepB, voffB); PG8_STAGE(PG8_SA(0, 0), a2, voffA);
;             PG8_WAIT_V(8); PG8_WAIT_L(0); PG8_BAR; PG8_MMA(1, 0, At, B0); PG8_MMA(1, 1, At, B1); PG8_BAR; PG8_SCHED;
.Lprio_188:
	ds_read_b128 v[66:69], v174
	ds_read_b128 v[70:73], v174 offset:1024
	ds_read_b128 v[74:77], v174 offset:2048
	ds_read_b128 v[78:81], v174 offset:3072
	ds_read_b128 v[162:165], v175
	ds_read_b128 v[182:185], v175 offset:1024
	ds_read_b128 v[186:189], v175 offset:2048
	ds_read_b128 v[190:193], v175 offset:3072
	s_add_u32 s20, s16, 0xfff80080
	s_addc_u32 s21, s17, -1
	s_cmp_eq_u32 s19, 28
	s_cselect_b32 s53, s3, s21
	s_cselect_b32 s52, s12, s20
	s_cselect_b32 s51, s13, s18
	s_cselect_b32 s50, s14, s15
	s_add_i32 m0, s33, 0xc000
	ds_read_b128 v[194:197], v176
	ds_read_b128 v[198:201], v176 offset:1024
	ds_read_b128 v[202:205], v176 offset:2048
	ds_read_b128 v[206:209], v176 offset:3072
	ds_read_b128 v[210:213], v176 offset:4096
	ds_read_b128 v[214:217], v176 offset:5120
	ds_read_b128 v[218:221], v176 offset:6144
	ds_read_b128 v[222:225], v176 offset:7168
	global_load_lds_dwordx4 v154, s[16:17]
	s_add_i32 m0, s33, 0xe000
	s_nop 0
	global_load_lds_dwordx4 v156, s[16:17]
	s_waitcnt lgkmcnt(0)
	s_barrier
	s_waitcnt lgkmcnt(0)
	v_mfma_f32_16x16x32_bf16 v[142:145], v[66:69], v[194:197], 0
	v_mfma_f32_16x16x32_bf16 v[138:141], v[74:77], v[194:197], 0
	v_mfma_f32_16x16x32_bf16 v[126:129], v[66:69], v[202:205], 0
	v_mfma_f32_16x16x32_bf16 v[122:125], v[74:77], v[202:205], 0
	v_mfma_f32_16x16x32_bf16 v[110:113], v[66:69], v[210:213], 0
	v_mfma_f32_16x16x32_bf16 v[106:109], v[74:77], v[210:213], 0
	v_mfma_f32_16x16x32_bf16 v[94:97], v[66:69], v[218:221], 0
	v_mfma_f32_16x16x32_bf16 v[90:93], v[74:77], v[218:221], 0
	v_mfma_f32_16x16x32_bf16 v[142:145], v[70:73], v[198:201], v[142:145]
	v_mfma_f32_16x16x32_bf16 v[138:141], v[78:81], v[198:201], v[138:141]
	v_mfma_f32_16x16x32_bf16 v[126:129], v[70:73], v[206:209], v[126:129]
	v_mfma_f32_16x16x32_bf16 v[122:125], v[78:81], v[206:209], v[122:125]
	v_mfma_f32_16x16x32_bf16 v[110:113], v[70:73], v[214:217], v[110:113]
	v_mfma_f32_16x16x32_bf16 v[106:109], v[78:81], v[214:217], v[106:109]
	v_mfma_f32_16x16x32_bf16 v[94:97], v[70:73], v[222:225], v[94:97]
	v_mfma_f32_16x16x32_bf16 v[90:93], v[78:81], v[222:225], v[90:93]
	v_mfma_f32_16x16x32_bf16 v[134:137], v[162:165], v[194:197], 0
	v_mfma_f32_16x16x32_bf16 v[130:133], v[186:189], v[194:197], 0
	v_mfma_f32_16x16x32_bf16 v[118:121], v[162:165], v[202:205], 0
	v_mfma_f32_16x16x32_bf16 v[114:117], v[186:189], v[202:205], 0
	v_mfma_f32_16x16x32_bf16 v[102:105], v[162:165], v[210:213], 0
	v_mfma_f32_16x16x32_bf16 v[98:101], v[186:189], v[210:213], 0
	v_mfma_f32_16x16x32_bf16 v[86:89], v[162:165], v[218:221], 0
	v_mfma_f32_16x16x32_bf16 v[82:85], v[186:189], v[218:221], 0
	v_mfma_f32_16x16x32_bf16 v[134:137], v[182:185], v[198:201], v[134:137]
	v_mfma_f32_16x16x32_bf16 v[130:133], v[190:193], v[198:201], v[130:133]
	v_mfma_f32_16x16x32_bf16 v[118:121], v[182:185], v[206:209], v[118:121]
	v_mfma_f32_16x16x32_bf16 v[114:117], v[190:193], v[206:209], v[114:117]
	v_mfma_f32_16x16x32_bf16 v[102:105], v[182:185], v[214:217], v[102:105]
	v_mfma_f32_16x16x32_bf16 v[98:101], v[190:193], v[214:217], v[98:101]
	v_mfma_f32_16x16x32_bf16 v[86:89], v[182:185], v[222:225], v[86:89]
	v_mfma_f32_16x16x32_bf16 v[82:85], v[190:193], v[222:225], v[82:85]
	s_barrier
	s_add_i32 s20, s57, s27
	s_mov_b32 m0, s20
	ds_read_b128 v[194:197], v176 offset:16384
	ds_read_b128 v[198:201], v176 offset:17408
	ds_read_b128 v[202:205], v176 offset:18432
	ds_read_b128 v[206:209], v176 offset:19456
	ds_read_b128 v[210:213], v176 offset:20480
	ds_read_b128 v[214:217], v176 offset:21504
	ds_read_b128 v[218:221], v176 offset:22528
	ds_read_b128 v[222:225], v176 offset:23552
	global_load_lds_dwordx4 v150, s[50:51]
	s_add_i32 m0, s20, 0x2000
	s_add_u32 s20, s50, 0x80000
	s_addc_u32 s21, s51, 0
	s_add_i32 s22, s58, s27
	global_load_lds_dwordx4 v146, s[50:51]
	s_mov_b32 m0, s22
	s_nop 0
	global_load_lds_dwordx4 v150, s[20:21]
	s_add_i32 m0, s22, 0x2000
	s_nop 0
	global_load_lds_dwordx4 v146, s[20:21]
	s_mov_b32 m0, s33
	s_nop 0
	global_load_lds_dwordx4 v152, s[52:53]
	s_mov_b32 m0, s34
	s_nop 0
	global_load_lds_dwordx4 v148, s[52:53]
	s_waitcnt lgkmcnt(0)
	s_barrier
	s_waitcnt lgkmcnt(0)
	v_mfma_f32_16x16x32_bf16 v[62:65], v[66:69], v[194:197], 0
	v_mfma_f32_16x16x32_bf16 v[58:61], v[74:77], v[194:197], 0
	v_mfma_f32_16x16x32_bf16 v[46:49], v[66:69], v[202:205], 0
	v_mfma_f32_16x16x32_bf16 v[42:45], v[74:77], v[202:205], 0
	v_mfma_f32_16x16x32_bf16 v[30:33], v[66:69], v[210:213], 0
	v_mfma_f32_16x16x32_bf16 v[26:29], v[74:77], v[210:213], 0
	v_mfma_f32_16x16x32_bf16 v[14:17], v[66:69], v[218:221], 0
	v_mfma_f32_16x16x32_bf16 v[10:13], v[74:77], v[218:221], 0
	v_mfma_f32_16x16x32_bf16 v[62:65], v[70:73], v[198:201], v[62:65]
	v_mfma_f32_16x16x32_bf16 v[58:61], v[78:81], v[198:201], v[58:61]
	v_mfma_f32_16x16x32_bf16 v[46:49], v[70:73], v[206:209], v[46:49]
	v_mfma_f32_16x16x32_bf16 v[42:45], v[78:81], v[206:209], v[42:45]
	v_mfma_f32_16x16x32_bf16 v[30:33], v[70:73], v[214:217], v[30:33]
	v_mfma_f32_16x16x32_bf16 v[26:29], v[78:81], v[214:217], v[26:29]
	v_mfma_f32_16x16x32_bf16 v[14:17], v[70:73], v[222:225], v[14:17]
	v_mfma_f32_16x16x32_bf16 v[10:13], v[78:81], v[222:225], v[10:13]
	v_mfma_f32_16x16x32_bf16 v[54:57], v[162:165], v[194:197], 0
	v_mfma_f32_16x16x32_bf16 v[50:53], v[186:189], v[194:197], 0
	v_mfma_f32_16x16x32_bf16 v[38:41], v[162:165], v[202:205], 0
	v_mfma_f32_16x16x32_bf16 v[34:37], v[186:189], v[202:205], 0
	v_mfma_f32_16x16x32_bf16 v[22:25], v[162:165], v[210:213], 0
	v_mfma_f32_16x16x32_bf16 v[18:21], v[186:189], v[210:213], 0
	v_mfma_f32_16x16x32_bf16 v[6:9], v[162:165], v[218:221], 0
	v_mfma_f32_16x16x32_bf16 v[2:5], v[186:189], v[218:221], 0
	v_mfma_f32_16x16x32_bf16 v[54:57], v[182:185], v[198:201], v[54:57]
	v_mfma_f32_16x16x32_bf16 v[50:53], v[190:193], v[198:201], v[50:53]
	v_mfma_f32_16x16x32_bf16 v[38:41], v[182:185], v[206:209], v[38:41]
	v_mfma_f32_16x16x32_bf16 v[34:37], v[190:193], v[206:209], v[34:37]
	v_mfma_f32_16x16x32_bf16 v[22:25], v[182:185], v[214:217], v[22:25]
	v_mfma_f32_16x16x32_bf16 v[18:21], v[190:193], v[214:217], v[18:21]
	v_mfma_f32_16x16x32_bf16 v[6:9], v[182:185], v[222:225], v[6:9]
	v_mfma_f32_16x16x32_bf16 v[2:5], v[190:193], v[222:225], v[2:5]
	s_barrier
; #define PG8_STAGE(bufoff, gbase, voff) do { _Pragma("unroll") for (int _i = 0; _i < 2; ++_i) \
;         __builtin_amdgcn_global_load_lds((const unsigned*)((const char*)(gbase) + (voff)[_i]), (LAS unsigned*)(lds + (bufoff) + ldsw + _i * 8192), 16, 0, 0); } while (0)
; #define PG8_LDA(dst, b, h) do { _Pragma("unroll") for (int m = 0; m < 4; ++m) _Pragma("unroll") for (int k = 0; k < 2; ++k) dst[m][k] = *(const LAS bf16x8*)(lds + PG8_SA(b, h) + aoff + m * 2048 + k * 1024); } while (0)
; #define PG8_LDB(dst, b, h) do { _Pragma("unroll") for (int n = 0; n < 2; ++n) _Pragma("unroll") for (int k = 0; k < 2; ++k) dst[n][k] = *(const LAS bf16x8*)(lds + PG8_SB(b, h) + boff + n * 2048 + k * 1024); } while (0)
; #define PG8_MMA(ai, bj, At, Bt) do { __builtin_amdgcn_s_setprio(1); _Pragma("unroll") for (int m = 0; m < 4; ++m) _Pragma("unroll") for (int n = 0; n < 2; ++n) _Pragma("unroll") for (int k = 0; k < 2; ++k) \
;         acc[ai][bj][m][n] = __builtin_amdgcn_mfma_f32_16x16x32_bf16(Bt[n][k], At[m][k], acc[ai][bj][m][n], 0, 0, 0); __builtin_amdgcn_s_setprio(0); } while (0)
; #define PG8_WAIT_V(n) asm volatile("s_waitcnt vmcnt(" #n ")" ::: "memory")
; #define PG8_WAIT_L(n) asm volatile("s_waitcnt lgkmcnt(" #n ")" ::: "memory")
; #define PG8_BAR __builtin_amdgcn_s_barrier()
; #define PG8_SCHED __builtin_amdgcn_sched_barrier(0)
; template <class Epi, class Sched, bool ALIGN_EPI = false, bool SP2 = false>
; __device__ __forceinline__ void gemm_phase(LAS unsigned char* lds, const Gemm g, const Sched& S, const Epi& E) {
;     ...
;             PG8_LDB(B0, 1, 0); PG8_LDB(B1, 1, 1); PG8_SCHED; PG8_LDA(At, 1, 0); PG8_STAGE(PG8_SA(0, 1), a2 + hstep, voffA);
;             PG8_WAIT_V(8); PG8_WAIT_L(0); PG8_BAR; PG8_MMA(0, 0, At, B0); PG8_MMA(0, 1, At, B1); PG8_BAR; PG8_SCHED;
;             PG8_LDA(At, 1, 1); PG8_STAGE(PG8_SB(1, 0), b3, voffB); PG8_STAGE(PG8_SB(1, 1), b3 + hstepB, voffB); PG8_STAGE(PG8_SA(1, 0), a3, voffA);
;             PG8_WAIT_V(8); PG8_WAIT_L(0); PG8_BAR; PG8_MMA(1, 0, At, B0); PG8_MMA(1, 1, At, B1); PG8_BAR; PG8_SCHED;
	s_add_i32 s22, 0, 0x18000
	s_add_i32 s23, 0, 0x1c000
	v_add_u32_e32 v78, s22, v170
	v_add_u32_e32 v168, s23, v170
	ds_read_b128 v[66:69], v78
	ds_read_b128 v[70:73], v78 offset:1024
	ds_read_b128 v[74:77], v78 offset:2048
	ds_read_b128 v[78:81], v78 offset:3072
	ds_read_b128 v[162:165], v168
	ds_read_b128 v[182:185], v168 offset:1024
	ds_read_b128 v[186:189], v168 offset:2048
	ds_read_b128 v[190:193], v168 offset:3072
	s_add_u32 s20, s52, 0x80000
	s_addc_u32 s21, s53, 0
	s_mov_b32 m0, s35
	ds_read_b128 v[194:197], v176 offset:32768
	ds_read_b128 v[198:201], v176 offset:33792
	ds_read_b128 v[202:205], v176 offset:34816
	ds_read_b128 v[206:209], v176 offset:35840
	ds_read_b128 v[210:213], v176 offset:36864
	ds_read_b128 v[214:217], v176 offset:37888
	ds_read_b128 v[218:221], v176 offset:38912
	ds_read_b128 v[222:225], v176 offset:39936
	global_load_lds_dwordx4 v152, s[20:21]
	s_mov_b32 m0, s36
	s_nop 0
	global_load_lds_dwordx4 v148, s[20:21]
	s_waitcnt vmcnt(8)
	s_waitcnt lgkmcnt(0)
	s_barrier
	s_waitcnt lgkmcnt(0)
	v_mfma_f32_16x16x32_bf16 v[142:145], v[66:69], v[194:197], v[142:145]
	v_mfma_f32_16x16x32_bf16 v[138:141], v[74:77], v[194:197], v[138:141]
	v_mfma_f32_16x16x32_bf16 v[126:129], v[66:69], v[202:205], v[126:129]
	v_mfma_f32_16x16x32_bf16 v[122:125], v[74:77], v[202:205], v[122:125]
	v_mfma_f32_16x16x32_bf16 v[110:113], v[66:69], v[210:213], v[110:113]
	v_mfma_f32_16x16x32_bf16 v[106:109], v[74:77], v[210:213], v[106:109]
	v_mfma_f32_16x16x32_bf16 v[94:97], v[66:69], v[218:221], v[94:97]
	v_mfma_f32_16x16x32_bf16 v[90:93], v[74:77], v[218:221], v[90:93]
	v_mfma_f32_16x16x32_bf16 v[142:145], v[70:73], v[198:201], v[142:145]
	v_mfma_f32_16x16x32_bf16 v[138:141], v[78:81], v[198:201], v[138:141]
	v_mfma_f32_16x16x32_bf16 v[126:129], v[70:73], v[206:209], v[126:129]
	v_mfma_f32_16x16x32_bf16 v[122:125], v[78:81], v[206:209], v[122:125]
	v_mfma_f32_16x16x32_bf16 v[110:113], v[70:73], v[214:217], v[110:113]
	v_mfma_f32_16x16x32_bf16 v[106:109], v[78:81], v[214:217], v[106:109]
	v_mfma_f32_16x16x32_bf16 v[94:97], v[70:73], v[222:225], v[94:97]
	v_mfma_f32_16x16x32_bf16 v[90:93], v[78:81], v[222:225], v[90:93]
	v_mfma_f32_16x16x32_bf16 v[134:137], v[162:165], v[194:197], v[134:137]
	v_mfma_f32_16x16x32_bf16 v[130:133], v[186:189], v[194:197], v[130:133]
	v_mfma_f32_16x16x32_bf16 v[118:121], v[162:165], v[202:205], v[118:121]
	v_mfma_f32_16x16x32_bf16 v[114:117], v[186:189], v[202:205], v[114:117]
	v_mfma_f32_16x16x32_bf16 v[102:105], v[162:165], v[210:213], v[102:105]
	v_mfma_f32_16x16x32_bf16 v[98:101], v[186:189], v[210:213], v[98:101]
	v_mfma_f32_16x16x32_bf16 v[86:89], v[162:165], v[218:221], v[86:89]
	v_mfma_f32_16x16x32_bf16 v[82:85], v[186:189], v[218:221], v[82:85]
	v_mfma_f32_16x16x32_bf16 v[134:137], v[182:185], v[198:201], v[134:137]
	v_mfma_f32_16x16x32_bf16 v[130:133], v[190:193], v[198:201], v[130:133]
	v_mfma_f32_16x16x32_bf16 v[118:121], v[182:185], v[206:209], v[118:121]
	v_mfma_f32_16x16x32_bf16 v[114:117], v[190:193], v[206:209], v[114:117]
	v_mfma_f32_16x16x32_bf16 v[102:105], v[182:185], v[214:217], v[102:105]
	v_mfma_f32_16x16x32_bf16 v[98:101], v[190:193], v[214:217], v[98:101]
	v_mfma_f32_16x16x32_bf16 v[86:89], v[182:185], v[222:225], v[86:89]
	v_mfma_f32_16x16x32_bf16 v[82:85], v[190:193], v[222:225], v[82:85]
	s_barrier
	s_add_u32 s98, s50, 0x80
	s_addc_u32 s99, s51, 0
	s_add_u32 s100, s52, 0x80
	s_addc_u32 s101, s53, 0
	s_add_i32 s20, s22, s27
	s_mov_b32 m0, s20
	ds_read_b128 v[194:197], v176 offset:49152
	ds_read_b128 v[198:201], v176 offset:50176
	ds_read_b128 v[202:205], v176 offset:51200
	ds_read_b128 v[206:209], v176 offset:52224
	ds_read_b128 v[210:213], v176 offset:53248
	ds_read_b128 v[214:217], v176 offset:54272
	ds_read_b128 v[218:221], v176 offset:55296
	ds_read_b128 v[222:225], v176 offset:56320
	global_load_lds_dwordx4 v150, s[98:99]
	s_add_i32 m0, s20, 0x2000
	s_add_u32 s20, s50, 0x80080
	s_addc_u32 s21, s51, 0
	s_add_i32 s22, s23, s27
	global_load_lds_dwordx4 v146, s[98:99]
	s_mov_b32 m0, s22
	s_nop 0
	global_load_lds_dwordx4 v150, s[20:21]
	s_add_i32 m0, s22, 0x2000
	s_nop 0
	global_load_lds_dwordx4 v146, s[20:21]
	s_mov_b32 m0, s55
	s_nop 0
	global_load_lds_dwordx4 v152, s[100:101]
	s_mov_b32 m0, s56
	s_nop 0
	global_load_lds_dwordx4 v148, s[100:101]
	s_waitcnt vmcnt(8)
	s_waitcnt lgkmcnt(0)
	s_barrier
	s_waitcnt lgkmcnt(0)
	v_mfma_f32_16x16x32_bf16 v[62:65], v[66:69], v[194:197], v[62:65]
	v_mfma_f32_16x16x32_bf16 v[58:61], v[74:77], v[194:197], v[58:61]
	v_mfma_f32_16x16x32_bf16 v[46:49], v[66:69], v[202:205], v[46:49]
	v_mfma_f32_16x16x32_bf16 v[42:45], v[74:77], v[202:205], v[42:45]
	v_mfma_f32_16x16x32_bf16 v[30:33], v[66:69], v[210:213], v[30:33]
	v_mfma_f32_16x16x32_bf16 v[26:29], v[74:77], v[210:213], v[26:29]
	v_mfma_f32_16x16x32_bf16 v[14:17], v[66:69], v[218:221], v[14:17]
	v_mfma_f32_16x16x32_bf16 v[10:13], v[74:77], v[218:221], v[10:13]
	v_mfma_f32_16x16x32_bf16 v[62:65], v[70:73], v[198:201], v[62:65]
	v_mfma_f32_16x16x32_bf16 v[58:61], v[78:81], v[198:201], v[58:61]
	v_mfma_f32_16x16x32_bf16 v[46:49], v[70:73], v[206:209], v[46:49]
	v_mfma_f32_16x16x32_bf16 v[42:45], v[78:81], v[206:209], v[42:45]
	v_mfma_f32_16x16x32_bf16 v[30:33], v[70:73], v[214:217], v[30:33]
	v_mfma_f32_16x16x32_bf16 v[26:29], v[78:81], v[214:217], v[26:29]
	v_mfma_f32_16x16x32_bf16 v[14:17], v[70:73], v[222:225], v[14:17]
	v_mfma_f32_16x16x32_bf16 v[10:13], v[78:81], v[222:225], v[10:13]
	v_mfma_f32_16x16x32_bf16 v[54:57], v[162:165], v[194:197], v[54:57]
	v_mfma_f32_16x16x32_bf16 v[50:53], v[186:189], v[194:197], v[50:53]
	v_mfma_f32_16x16x32_bf16 v[38:41], v[162:165], v[202:205], v[38:41]
	v_mfma_f32_16x16x32_bf16 v[34:37], v[186:189], v[202:205], v[34:37]
	v_mfma_f32_16x16x32_bf16 v[22:25], v[162:165], v[210:213], v[22:25]
	v_mfma_f32_16x16x32_bf16 v[18:21], v[186:189], v[210:213], v[18:21]
	v_mfma_f32_16x16x32_bf16 v[6:9], v[162:165], v[218:221], v[6:9]
	v_mfma_f32_16x16x32_bf16 v[2:5], v[186:189], v[218:221], v[2:5]
	v_mfma_f32_16x16x32_bf16 v[54:57], v[182:185], v[198:201], v[54:57]
	v_mfma_f32_16x16x32_bf16 v[50:53], v[190:193], v[198:201], v[50:53]
	v_mfma_f32_16x16x32_bf16 v[38:41], v[182:185], v[206:209], v[38:41]
	v_mfma_f32_16x16x32_bf16 v[34:37], v[190:193], v[206:209], v[34:37]
	v_mfma_f32_16x16x32_bf16 v[22:25], v[182:185], v[214:217], v[22:25]
	v_mfma_f32_16x16x32_bf16 v[18:21], v[190:193], v[214:217], v[18:21]
	v_mfma_f32_16x16x32_bf16 v[6:9], v[182:185], v[222:225], v[6:9]
	v_mfma_f32_16x16x32_bf16 v[2:5], v[190:193], v[222:225], v[2:5]
	s_barrier
	s_add_i32 s19, s19, 2
	s_add_u32 s16, s16, 0x100
	s_addc_u32 s17, s17, 0
	s_add_u32 s15, s15, 0x100
	s_addc_u32 s18, s18, 0
	s_cmp_gt_u32 s19, 29
; #define PG8_STAGE(bufoff, gbase, voff) do { _Pragma("unroll") for (int _i = 0; _i < 2; ++_i) \
;         __builtin_amdgcn_global_load_lds((const unsigned*)((const char*)(gbase) + (voff)[_i]), (LAS unsigned*)(lds + (bufoff) + ldsw + _i * 8192), 16, 0, 0); } while (0)
; #define PG8_LDA(dst, b, h) do { _Pragma("unroll") for (int m = 0; m < 4; ++m) _Pragma("unroll") for (int k = 0; k < 2; ++k) dst[m][k] = *(const LAS bf16x8*)(lds + PG8_SA(b, h) + aoff + m * 2048 + k * 1024); } while (0)
; #define PG8_LDB(dst, b, h) do { _Pragma("unroll") for (int n = 0; n < 2; ++n) _Pragma("unroll") for (int k = 0; k < 2; ++k) dst[n][k] = *(const LAS bf16x8*)(lds + PG8_SB(b, h) + boff + n * 2048 + k * 1024); } while (0)
; #define PG8_MMA(ai, bj, At, Bt) do { __builtin_amdgcn_s_setprio(1); _Pragma("unroll") for (int m = 0; m < 4; ++m) _Pragma("unroll") for (int n = 0; n < 2; ++n) _Pragma("unroll") for (int k = 0; k < 2; ++k) \
;         acc[ai][bj][m][n] = __builtin_amdgcn_mfma_f32_16x16x32_bf16(Bt[n][k], At[m][k], acc[ai][bj][m][n], 0, 0, 0); __builtin_amdgcn_s_setprio(0); } while (0)
; #define PG8_WAIT_V(n) asm volatile("s_waitcnt vmcnt(" #n ")" ::: "memory")
; #define PG8_WAIT_L(n) asm volatile("s_waitcnt lgkmcnt(" #n ")" ::: "memory")
; #define PG8_BAR __builtin_amdgcn_s_barrier()
; template <class Epi, class Sched, bool ALIGN_EPI = false, bool SP2 = false>
; __device__ __forceinline__ void gemm_phase(LAS unsigned char* lds, const Gemm g, const Sched& S, const Epi& E) {
;     ...
;             const bool last = (t == nt - 2);
;             const char* a1 = cA + (size_t)(t + 1) * kstep;
;             const char* a2 = last ? nA : cA + (size_t)(t + 2) * kstep; const char* b2 = last ? nB : cB + (size_t)(t + 2) * kstep;
;             const char* a3 = a2 + kstep; const char* b3 = b2 + kstep;
;             if (last && has_next) S.a_ready(nxt);
;             if constexpr (SP2) {
;             PG8_LDB(B0, 0, 0); PG8_LDB(B1, 0, 1); PG8_SCHED; PG8_LDA(At, 0, 0); PG8_STAGE(PG8_SA(1, 1), a1 + hstep, voffA);
;             PG8_WAIT_V(8); PG8_WAIT_L(0); PG8_BAR; PG8_MMA(0, 0, At, B0); PG8_MMA(0, 1, At, B1); PG8_BAR; PG8_SCHED;
;             PG8_LDA(At, 0, 1); PG8_STAGE(PG8_SB(0, 0), b2, voffB); PG8_STAGE(PG8_SB(0, 1), b2 + hstepB, voffB); PG8_STAGE(PG8_SA(0, 0), a2, voffA);
;             PG8_WAIT_V(8); PG8_WAIT_L(0); PG8_BAR; PG8_MMA(1, 0, At, B0); PG8_MMA(1, 1, At, B1); PG8_BAR; PG8_SCHED;
.LBB0_188:
	ds_read_b128 v[66:69], v174
	ds_read_b128 v[70:73], v174 offset:1024
	ds_read_b128 v[74:77], v174 offset:2048
	ds_read_b128 v[78:81], v174 offset:3072
	ds_read_b128 v[162:165], v175
	ds_read_b128 v[182:185], v175 offset:1024
	ds_read_b128 v[186:189], v175 offset:2048
	ds_read_b128 v[190:193], v175 offset:3072
	s_add_u32 s20, s16, 0xfff80080
	s_addc_u32 s21, s17, -1
	s_cmp_eq_u32 s19, 28
	s_cselect_b32 s53, s3, s21
	s_cselect_b32 s52, s12, s20
	s_cselect_b32 s51, s13, s18
	s_cselect_b32 s50, s14, s15
	s_add_i32 m0, s33, 0xc000
	ds_read_b128 v[194:197], v176
	ds_read_b128 v[198:201], v176 offset:1024
	ds_read_b128 v[202:205], v176 offset:2048
	ds_read_b128 v[206:209], v176 offset:3072
	ds_read_b128 v[210:213], v176 offset:4096
	ds_read_b128 v[214:217], v176 offset:5120
	ds_read_b128 v[218:221], v176 offset:6144
	ds_read_b128 v[222:225], v176 offset:7168
	global_load_lds_dwordx4 v154, s[16:17]
	s_add_i32 m0, s33, 0xe000
	s_nop 0
	global_load_lds_dwordx4 v156, s[16:17]
	s_waitcnt vmcnt(8)
	s_waitcnt lgkmcnt(0)
	s_barrier
	s_waitcnt lgkmcnt(0)
	v_mfma_f32_16x16x32_bf16 v[142:145], v[66:69], v[194:197], v[142:145]
	v_mfma_f32_16x16x32_bf16 v[138:141], v[74:77], v[194:197], v[138:141]
	v_mfma_f32_16x16x32_bf16 v[126:129], v[66:69], v[202:205], v[126:129]
	v_mfma_f32_16x16x32_bf16 v[122:125], v[74:77], v[202:205], v[122:125]
	v_mfma_f32_16x16x32_bf16 v[110:113], v[66:69], v[210:213], v[110:113]
	v_mfma_f32_16x16x32_bf16 v[106:109], v[74:77], v[210:213], v[106:109]
	v_mfma_f32_16x16x32_bf16 v[94:97], v[66:69], v[218:221], v[94:97]
	v_mfma_f32_16x16x32_bf16 v[90:93], v[74:77], v[218:221], v[90:93]
	v_mfma_f32_16x16x32_bf16 v[142:145], v[70:73], v[198:201], v[142:145]
	v_mfma_f32_16x16x32_bf16 v[138:141], v[78:81], v[198:201], v[138:141]
	v_mfma_f32_16x16x32_bf16 v[126:129], v[70:73], v[206:209], v[126:129]
	v_mfma_f32_16x16x32_bf16 v[122:125], v[78:81], v[206:209], v[122:125]
	v_mfma_f32_16x16x32_bf16 v[110:113], v[70:73], v[214:217], v[110:113]
	v_mfma_f32_16x16x32_bf16 v[106:109], v[78:81], v[214:217], v[106:109]
	v_mfma_f32_16x16x32_bf16 v[94:97], v[70:73], v[222:225], v[94:97]
	v_mfma_f32_16x16x32_bf16 v[90:93], v[78:81], v[222:225], v[90:93]
	v_mfma_f32_16x16x32_bf16 v[134:137], v[162:165], v[194:197], v[134:137]
	v_mfma_f32_16x16x32_bf16 v[130:133], v[186:189], v[194:197], v[130:133]
	v_mfma_f32_16x16x32_bf16 v[118:121], v[162:165], v[202:205], v[118:121]
	v_mfma_f32_16x16x32_bf16 v[114:117], v[186:189], v[202:205], v[114:117]
	v_mfma_f32_16x16x32_bf16 v[102:105], v[162:165], v[210:213], v[102:105]
	v_mfma_f32_16x16x32_bf16 v[98:101], v[186:189], v[210:213], v[98:101]
	v_mfma_f32_16x16x32_bf16 v[86:89], v[162:165], v[218:221], v[86:89]
	v_mfma_f32_16x16x32_bf16 v[82:85], v[186:189], v[218:221], v[82:85]
	v_mfma_f32_16x16x32_bf16 v[134:137], v[182:185], v[198:201], v[134:137]
	v_mfma_f32_16x16x32_bf16 v[130:133], v[190:193], v[198:201], v[130:133]
	v_mfma_f32_16x16x32_bf16 v[118:121], v[182:185], v[206:209], v[118:121]
	v_mfma_f32_16x16x32_bf16 v[114:117], v[190:193], v[206:209], v[114:117]
	v_mfma_f32_16x16x32_bf16 v[102:105], v[182:185], v[214:217], v[102:105]
	v_mfma_f32_16x16x32_bf16 v[98:101], v[190:193], v[214:217], v[98:101]
	v_mfma_f32_16x16x32_bf16 v[86:89], v[182:185], v[222:225], v[86:89]
	v_mfma_f32_16x16x32_bf16 v[82:85], v[190:193], v[222:225], v[82:85]
	s_barrier
	s_add_i32 s20, s57, s27
	s_mov_b32 m0, s20
	ds_read_b128 v[194:197], v176 offset:16384
	ds_read_b128 v[198:201], v176 offset:17408
	ds_read_b128 v[202:205], v176 offset:18432
	ds_read_b128 v[206:209], v176 offset:19456
	ds_read_b128 v[210:213], v176 offset:20480
	ds_read_b128 v[214:217], v176 offset:21504
	ds_read_b128 v[218:221], v176 offset:22528
	ds_read_b128 v[222:225], v176 offset:23552
	global_load_lds_dwordx4 v150, s[50:51]
	s_add_i32 m0, s20, 0x2000
	s_add_u32 s20, s50, 0x80000
	s_addc_u32 s21, s51, 0
	s_add_i32 s22, s58, s27
	global_load_lds_dwordx4 v146, s[50:51]
	s_mov_b32 m0, s22
	s_nop 0
	global_load_lds_dwordx4 v150, s[20:21]
	s_add_i32 m0, s22, 0x2000
	s_nop 0
	global_load_lds_dwordx4 v146, s[20:21]
	s_mov_b32 m0, s33
	s_nop 0
	global_load_lds_dwordx4 v152, s[52:53]
	s_mov_b32 m0, s34
	s_nop 0
	global_load_lds_dwordx4 v148, s[52:53]
	s_waitcnt vmcnt(8)
	s_waitcnt lgkmcnt(0)
	s_barrier
	s_waitcnt lgkmcnt(0)
	v_mfma_f32_16x16x32_bf16 v[62:65], v[66:69], v[194:197], v[62:65]
	v_mfma_f32_16x16x32_bf16 v[58:61], v[74:77], v[194:197], v[58:61]
	v_mfma_f32_16x16x32_bf16 v[46:49], v[66:69], v[202:205], v[46:49]
	v_mfma_f32_16x16x32_bf16 v[42:45], v[74:77], v[202:205], v[42:45]
	v_mfma_f32_16x16x32_bf16 v[30:33], v[66:69], v[210:213], v[30:33]
	v_mfma_f32_16x16x32_bf16 v[26:29], v[74:77], v[210:213], v[26:29]
	v_mfma_f32_16x16x32_bf16 v[14:17], v[66:69], v[218:221], v[14:17]
	v_mfma_f32_16x16x32_bf16 v[10:13], v[74:77], v[218:221], v[10:13]
	v_mfma_f32_16x16x32_bf16 v[62:65], v[70:73], v[198:201], v[62:65]
	v_mfma_f32_16x16x32_bf16 v[58:61], v[78:81], v[198:201], v[58:61]
	v_mfma_f32_16x16x32_bf16 v[46:49], v[70:73], v[206:209], v[46:49]
	v_mfma_f32_16x16x32_bf16 v[42:45], v[78:81], v[206:209], v[42:45]
	v_mfma_f32_16x16x32_bf16 v[30:33], v[70:73], v[214:217], v[30:33]
	v_mfma_f32_16x16x32_bf16 v[26:29], v[78:81], v[214:217], v[26:29]
	v_mfma_f32_16x16x32_bf16 v[14:17], v[70:73], v[222:225], v[14:17]
	v_mfma_f32_16x16x32_bf16 v[10:13], v[78:81], v[222:225], v[10:13]
	v_mfma_f32_16x16x32_bf16 v[54:57], v[162:165], v[194:197], v[54:57]
	v_mfma_f32_16x16x32_bf16 v[50:53], v[186:189], v[194:197], v[50:53]
	v_mfma_f32_16x16x32_bf16 v[38:41], v[162:165], v[202:205], v[38:41]
	v_mfma_f32_16x16x32_bf16 v[34:37], v[186:189], v[202:205], v[34:37]
	v_mfma_f32_16x16x32_bf16 v[22:25], v[162:165], v[210:213], v[22:25]
	v_mfma_f32_16x16x32_bf16 v[18:21], v[186:189], v[210:213], v[18:21]
	v_mfma_f32_16x16x32_bf16 v[6:9], v[162:165], v[218:221], v[6:9]
	v_mfma_f32_16x16x32_bf16 v[2:5], v[186:189], v[218:221], v[2:5]
	v_mfma_f32_16x16x32_bf16 v[54:57], v[182:185], v[198:201], v[54:57]
	v_mfma_f32_16x16x32_bf16 v[50:53], v[190:193], v[198:201], v[50:53]
	v_mfma_f32_16x16x32_bf16 v[38:41], v[182:185], v[206:209], v[38:41]
	v_mfma_f32_16x16x32_bf16 v[34:37], v[190:193], v[206:209], v[34:37]
	v_mfma_f32_16x16x32_bf16 v[22:25], v[182:185], v[214:217], v[22:25]
	v_mfma_f32_16x16x32_bf16 v[18:21], v[190:193], v[214:217], v[18:21]
	v_mfma_f32_16x16x32_bf16 v[6:9], v[182:185], v[222:225], v[6:9]
	v_mfma_f32_16x16x32_bf16 v[2:5], v[190:193], v[222:225], v[2:5]
	s_barrier
; #define PG8_STAGE(bufoff, gbase, voff) do { _Pragma("unroll") for (int _i = 0; _i < 2; ++_i) \
;         __builtin_amdgcn_global_load_lds((const unsigned*)((const char*)(gbase) + (voff)[_i]), (LAS unsigned*)(lds + (bufoff) + ldsw + _i * 8192), 16, 0, 0); } while (0)
; #define PG8_LDA(dst, b, h) do { _Pragma("unroll") for (int m = 0; m < 4; ++m) _Pragma("unroll") for (int k = 0; k < 2; ++k) dst[m][k] = *(const LAS bf16x8*)(lds + PG8_SA(b, h) + aoff + m * 2048 + k * 1024); } while (0)
; #define PG8_LDB(dst, b, h) do { _Pragma("unroll") for (int n = 0; n < 2; ++n) _Pragma("unroll") for (int k = 0; k < 2; ++k) dst[n][k] = *(const LAS bf16x8*)(lds + PG8_SB(b, h) + boff + n * 2048 + k * 1024); } while (0)
; #define PG8_MMA(ai, bj, At, Bt) do { __builtin_amdgcn_s_setprio(1); _Pragma("unroll") for (int m = 0; m < 4; ++m) _Pragma("unroll") for (int n = 0; n < 2; ++n) _Pragma("unroll") for (int k = 0; k < 2; ++k) \
;         acc[ai][bj][m][n] = __builtin_amdgcn_mfma_f32_16x16x32_bf16(Bt[n][k], At[m][k], acc[ai][bj][m][n], 0, 0, 0); __builtin_amdgcn_s_setprio(0); } while (0)
; #define PG8_WAIT_V(n) asm volatile("s_waitcnt vmcnt(" #n ")" ::: "memory")
; #define PG8_WAIT_L(n) asm volatile("s_waitcnt lgkmcnt(" #n ")" ::: "memory")
; #define PG8_BAR __builtin_amdgcn_s_barrier()
; #define PG8_SCHED __builtin_amdgcn_sched_barrier(0)
; template <class Epi, class Sched, bool ALIGN_EPI = false, bool SP2 = false>
; __device__ __forceinline__ void gemm_phase(LAS unsigned char* lds, const Gemm g, const Sched& S, const Epi& E) {
;     ...
;             PG8_LDB(B0, 1, 0); PG8_LDB(B1, 1, 1); PG8_SCHED; PG8_LDA(At, 1, 0); PG8_STAGE(PG8_SA(0, 1), a2 + hstep, voffA);
;             PG8_WAIT_V(8); PG8_WAIT_L(0); PG8_BAR; PG8_MMA(0, 0, At, B0); PG8_MMA(0, 1, At, B1); PG8_BAR; PG8_SCHED;
;             PG8_LDA(At, 1, 1); PG8_STAGE(PG8_SB(1, 0), b3, voffB); PG8_STAGE(PG8_SB(1, 1), b3 + hstepB, voffB); PG8_STAGE(PG8_SA(1, 0), a3, voffA);
;             PG8_WAIT_V(8); PG8_WAIT_L(0); PG8_BAR; PG8_MMA(1, 0, At, B0); PG8_MMA(1, 1, At, B1); PG8_BAR; PG8_SCHED;
	s_add_i32 s22, 0, 0x18000
	s_add_i32 s23, 0, 0x1c000
	v_add_u32_e32 v78, s22, v170
	v_add_u32_e32 v168, s23, v170
	ds_read_b128 v[66:69], v78
	ds_read_b128 v[70:73], v78 offset:1024
	ds_read_b128 v[74:77], v78 offset:2048
	ds_read_b128 v[78:81], v78 offset:3072
	ds_read_b128 v[162:165], v168
	ds_read_b128 v[182:185], v168 offset:1024
	ds_read_b128 v[186:189], v168 offset:2048
	ds_read_b128 v[190:193], v168 offset:3072
	s_add_u32 s20, s52, 0x80000
	s_addc_u32 s21, s53, 0
	s_mov_b32 m0, s35
	ds_read_b128 v[194:197], v176 offset:32768
	ds_read_b128 v[198:201], v176 offset:33792
	ds_read_b128 v[202:205], v176 offset:34816
	ds_read_b128 v[206:209], v176 offset:35840
	ds_read_b128 v[210:213], v176 offset:36864
	ds_read_b128 v[214:217], v176 offset:37888
	ds_read_b128 v[218:221], v176 offset:38912
	ds_read_b128 v[222:225], v176 offset:39936
	global_load_lds_dwordx4 v152, s[20:21]
	s_mov_b32 m0, s36
	s_nop 0
	global_load_lds_dwordx4 v148, s[20:21]
	s_waitcnt vmcnt(8)
	s_waitcnt lgkmcnt(0)
	s_barrier
	s_waitcnt lgkmcnt(0)
	v_mfma_f32_16x16x32_bf16 v[142:145], v[66:69], v[194:197], v[142:145]
	v_mfma_f32_16x16x32_bf16 v[138:141], v[74:77], v[194:197], v[138:141]
	v_mfma_f32_16x16x32_bf16 v[126:129], v[66:69], v[202:205], v[126:129]
	v_mfma_f32_16x16x32_bf16 v[122:125], v[74:77], v[202:205], v[122:125]
	v_mfma_f32_16x16x32_bf16 v[110:113], v[66:69], v[210:213], v[110:113]
	v_mfma_f32_16x16x32_bf16 v[106:109], v[74:77], v[210:213], v[106:109]
	v_mfma_f32_16x16x32_bf16 v[94:97], v[66:69], v[218:221], v[94:97]
	v_mfma_f32_16x16x32_bf16 v[90:93], v[74:77], v[218:221], v[90:93]
	v_mfma_f32_16x16x32_bf16 v[142:145], v[70:73], v[198:201], v[142:145]
	v_mfma_f32_16x16x32_bf16 v[138:141], v[78:81], v[198:201], v[138:141]
	v_mfma_f32_16x16x32_bf16 v[126:129], v[70:73], v[206:209], v[126:129]
	v_mfma_f32_16x16x32_bf16 v[122:125], v[78:81], v[206:209], v[122:125]
	v_mfma_f32_16x16x32_bf16 v[110:113], v[70:73], v[214:217], v[110:113]
	v_mfma_f32_16x16x32_bf16 v[106:109], v[78:81], v[214:217], v[106:109]
	v_mfma_f32_16x16x32_bf16 v[94:97], v[70:73], v[222:225], v[94:97]
	v_mfma_f32_16x16x32_bf16 v[90:93], v[78:81], v[222:225], v[90:93]
	v_mfma_f32_16x16x32_bf16 v[134:137], v[162:165], v[194:197], v[134:137]
	v_mfma_f32_16x16x32_bf16 v[130:133], v[186:189], v[194:197], v[130:133]
	v_mfma_f32_16x16x32_bf16 v[118:121], v[162:165], v[202:205], v[118:121]
	v_mfma_f32_16x16x32_bf16 v[114:117], v[186:189], v[202:205], v[114:117]
	v_mfma_f32_16x16x32_bf16 v[102:105], v[162:165], v[210:213], v[102:105]
	v_mfma_f32_16x16x32_bf16 v[98:101], v[186:189], v[210:213], v[98:101]
	v_mfma_f32_16x16x32_bf16 v[86:89], v[162:165], v[218:221], v[86:89]
	v_mfma_f32_16x16x32_bf16 v[82:85], v[186:189], v[218:221], v[82:85]
	v_mfma_f32_16x16x32_bf16 v[134:137], v[182:185], v[198:201], v[134:137]
	v_mfma_f32_16x16x32_bf16 v[130:133], v[190:193], v[198:201], v[130:133]
	v_mfma_f32_16x16x32_bf16 v[118:121], v[182:185], v[206:209], v[118:121]
	v_mfma_f32_16x16x32_bf16 v[114:117], v[190:193], v[206:209], v[114:117]
	v_mfma_f32_16x16x32_bf16 v[102:105], v[182:185], v[214:217], v[102:105]
	v_mfma_f32_16x16x32_bf16 v[98:101], v[190:193], v[214:217], v[98:101]
	v_mfma_f32_16x16x32_bf16 v[86:89], v[182:185], v[222:225], v[86:89]
	v_mfma_f32_16x16x32_bf16 v[82:85], v[190:193], v[222:225], v[82:85]
	s_barrier
	s_add_u32 s98, s50, 0x80
	s_addc_u32 s99, s51, 0
	s_add_u32 s100, s52, 0x80
	s_addc_u32 s101, s53, 0
	s_add_i32 s20, s22, s27
	s_mov_b32 m0, s20
	ds_read_b128 v[194:197], v176 offset:49152
	ds_read_b128 v[198:201], v176 offset:50176
	ds_read_b128 v[202:205], v176 offset:51200
	ds_read_b128 v[206:209], v176 offset:52224
	ds_read_b128 v[210:213], v176 offset:53248
	ds_read_b128 v[214:217], v176 offset:54272
	ds_read_b128 v[218:221], v176 offset:55296
	ds_read_b128 v[222:225], v176 offset:56320
	global_load_lds_dwordx4 v150, s[98:99]
	s_add_i32 m0, s20, 0x2000
	s_add_u32 s20, s50, 0x80080
	s_addc_u32 s21, s51, 0
	s_add_i32 s22, s23, s27
	global_load_lds_dwordx4 v146, s[98:99]
	s_mov_b32 m0, s22
	s_nop 0
	global_load_lds_dwordx4 v150, s[20:21]
	s_add_i32 m0, s22, 0x2000
	s_nop 0
	global_load_lds_dwordx4 v146, s[20:21]
	s_mov_b32 m0, s55
	s_nop 0
	global_load_lds_dwordx4 v152, s[100:101]
	s_mov_b32 m0, s56
	s_nop 0
	global_load_lds_dwordx4 v148, s[100:101]
	s_waitcnt vmcnt(8)
	s_waitcnt lgkmcnt(0)
	s_barrier
	s_waitcnt lgkmcnt(0)
	v_mfma_f32_16x16x32_bf16 v[62:65], v[66:69], v[194:197], v[62:65]
	v_mfma_f32_16x16x32_bf16 v[58:61], v[74:77], v[194:197], v[58:61]
	v_mfma_f32_16x16x32_bf16 v[46:49], v[66:69], v[202:205], v[46:49]
	v_mfma_f32_16x16x32_bf16 v[42:45], v[74:77], v[202:205], v[42:45]
	v_mfma_f32_16x16x32_bf16 v[30:33], v[66:69], v[210:213], v[30:33]
	v_mfma_f32_16x16x32_bf16 v[26:29], v[74:77], v[210:213], v[26:29]
	v_mfma_f32_16x16x32_bf16 v[14:17], v[66:69], v[218:221], v[14:17]
	v_mfma_f32_16x16x32_bf16 v[10:13], v[74:77], v[218:221], v[10:13]
	v_mfma_f32_16x16x32_bf16 v[62:65], v[70:73], v[198:201], v[62:65]
	v_mfma_f32_16x16x32_bf16 v[58:61], v[78:81], v[198:201], v[58:61]
	v_mfma_f32_16x16x32_bf16 v[46:49], v[70:73], v[206:209], v[46:49]
	v_mfma_f32_16x16x32_bf16 v[42:45], v[78:81], v[206:209], v[42:45]
	v_mfma_f32_16x16x32_bf16 v[30:33], v[70:73], v[214:217], v[30:33]
	v_mfma_f32_16x16x32_bf16 v[26:29], v[78:81], v[214:217], v[26:29]
	v_mfma_f32_16x16x32_bf16 v[14:17], v[70:73], v[222:225], v[14:17]
	v_mfma_f32_16x16x32_bf16 v[10:13], v[78:81], v[222:225], v[10:13]
	v_mfma_f32_16x16x32_bf16 v[54:57], v[162:165], v[194:197], v[54:57]
	v_mfma_f32_16x16x32_bf16 v[50:53], v[186:189], v[194:197], v[50:53]
	v_mfma_f32_16x16x32_bf16 v[38:41], v[162:165], v[202:205], v[38:41]
	v_mfma_f32_16x16x32_bf16 v[34:37], v[186:189], v[202:205], v[34:37]
	v_mfma_f32_16x16x32_bf16 v[22:25], v[162:165], v[210:213], v[22:25]
	v_mfma_f32_16x16x32_bf16 v[18:21], v[186:189], v[210:213], v[18:21]
	v_mfma_f32_16x16x32_bf16 v[6:9], v[162:165], v[218:221], v[6:9]
	v_mfma_f32_16x16x32_bf16 v[2:5], v[186:189], v[218:221], v[2:5]
	v_mfma_f32_16x16x32_bf16 v[54:57], v[182:185], v[198:201], v[54:57]
	v_mfma_f32_16x16x32_bf16 v[50:53], v[190:193], v[198:201], v[50:53]
	v_mfma_f32_16x16x32_bf16 v[38:41], v[182:185], v[206:209], v[38:41]
	v_mfma_f32_16x16x32_bf16 v[34:37], v[190:193], v[206:209], v[34:37]
	v_mfma_f32_16x16x32_bf16 v[22:25], v[182:185], v[214:217], v[22:25]
	v_mfma_f32_16x16x32_bf16 v[18:21], v[190:193], v[214:217], v[18:21]
	v_mfma_f32_16x16x32_bf16 v[6:9], v[182:185], v[222:225], v[6:9]
	v_mfma_f32_16x16x32_bf16 v[2:5], v[190:193], v[222:225], v[2:5]
	s_barrier
	s_add_i32 s19, s19, 2
	s_add_u32 s16, s16, 0x100
	s_addc_u32 s17, s17, 0
	s_add_u32 s15, s15, 0x100
	s_addc_u32 s18, s18, 0
	s_cmp_gt_u32 s19, 29
	s_cbranch_scc0 .LBB0_188
	s_setprio 0
	s_and_b64 vcc, exec, s[40:41]
	s_cbranch_vccz .LBB0_191
	s_barrier

; #define PG8_STAGE(bufoff, gbase, voff) do { _Pragma("unroll") for (int _i = 0; _i < 2; ++_i) \
;         __builtin_amdgcn_global_load_lds((const unsigned*)((const char*)(gbase) + (voff)[_i]), (LAS unsigned*)(lds + (bufoff) + ldsw + _i * 8192), 16, 0, 0); } while (0)
; #define PG8_LDA(dst, b, h) do { _Pragma("unroll") for (int m = 0; m < 4; ++m) _Pragma("unroll") for (int k = 0; k < 2; ++k) dst[m][k] = *(const LAS bf16x8*)(lds + PG8_SA(b, h) + aoff + m * 2048 + k * 1024); } while (0)
; #define PG8_LDB(dst, b, h) do { _Pragma("unroll") for (int n = 0; n < 2; ++n) _Pragma("unroll") for (int k = 0; k < 2; ++k) dst[n][k] = *(const LAS bf16x8*)(lds + PG8_SB(b, h) + boff + n * 2048 + k * 1024); } while (0)
; #define PG8_MMA(ai, bj, At, Bt) do { __builtin_amdgcn_s_setprio(1); _Pragma("unroll") for (int m = 0; m < 4; ++m) _Pragma("unroll") for (int n = 0; n < 2; ++n) _Pragma("unroll") for (int k = 0; k < 2; ++k) \
;         acc[ai][bj][m][n] = __builtin_amdgcn_mfma_f32_16x16x32_bf16(Bt[n][k], At[m][k], acc[ai][bj][m][n], 0, 0, 0); __builtin_amdgcn_s_setprio(0); } while (0)
; #define PG8_WAIT_V(n) asm volatile("s_waitcnt vmcnt(" #n ")" ::: "memory")
; #define PG8_WAIT_L(n) asm volatile("s_waitcnt lgkmcnt(" #n ")" ::: "memory")
; #define PG8_BAR __builtin_amdgcn_s_barrier()
; template <class Epi, class Sched, bool ALIGN_EPI = false, bool SP2 = false>
; __device__ __forceinline__ void gemm_phase(LAS unsigned char* lds, const Gemm g, const Sched& S, const Epi& E) {
;     ...
;             const bool last = (t == nt - 2);
;             const char* a1 = cA + (size_t)(t + 1) * kstep;
;             const char* a2 = last ? nA : cA + (size_t)(t + 2) * kstep; const char* b2 = last ? nB : cB + (size_t)(t + 2) * kstep;
;             const char* a3 = a2 + kstep; const char* b3 = b2 + kstep;
;             if (last && has_next) S.a_ready(nxt);
;             if constexpr (SP2) {
;             PG8_LDB(B0, 0, 0); PG8_LDB(B1, 0, 1); PG8_SCHED; PG8_LDA(At, 0, 0); PG8_STAGE(PG8_SA(1, 1), a1 + hstep, voffA);
;             PG8_WAIT_V(8); PG8_WAIT_L(0); PG8_BAR; PG8_MMA(0, 0, At, B0); PG8_MMA(0, 1, At, B1); PG8_BAR; PG8_SCHED;
;             PG8_LDA(At, 0, 1); PG8_STAGE(PG8_SB(0, 0), b2, voffB); PG8_STAGE(PG8_SB(0, 1), b2 + hstepB, voffB); PG8_STAGE(PG8_SA(0, 0), a2, voffA);
;             PG8_WAIT_V(8); PG8_WAIT_L(0); PG8_BAR; PG8_MMA(1, 0, At, B0); PG8_MMA(1, 1, At, B1); PG8_BAR; PG8_SCHED;
.Lprio_317:
	ds_read_b128 v[130:133], v196
	ds_read_b128 v[134:137], v196 offset:1024
	ds_read_b128 v[138:141], v196 offset:2048
	ds_read_b128 v[142:145], v196 offset:3072
	ds_read_b128 v[166:169], v197
	ds_read_b128 v[170:173], v197 offset:1024
	ds_read_b128 v[174:177], v197 offset:2048
	ds_read_b128 v[178:181], v197 offset:3072
	s_add_u32 s54, s16, 0x100
	s_addc_u32 s55, s17, 0
	s_cmpk_eq_i32 s13, 0x54
	s_cselect_b32 s59, s3, s55
	s_cselect_b32 s58, s2, s54
	s_cselect_b32 s57, s53, s12
	s_cselect_b32 s56, s52, s5
	v_lshl_add_u64 v[190:191], s[16:17], 0, v[158:159]
	s_add_i32 m0, s29, 0xc000
	ds_read_b128 v[182:185], v198
	ds_read_b128 v[186:189], v198 offset:1024
	ds_read_b128 v[202:205], v198 offset:2048
	ds_read_b128 v[206:209], v198 offset:3072
	ds_read_b128 v[210:213], v198 offset:4096
	ds_read_b128 v[214:217], v198 offset:5120
	ds_read_b128 v[218:221], v198 offset:6144
	ds_read_b128 v[222:225], v198 offset:7168
	global_load_lds_dwordx4 v[190:191], off
	v_lshl_add_u64 v[190:191], s[16:17], 0, v[160:161]
	s_add_i32 m0, s29, 0xe000
	s_nop 0
	global_load_lds_dwordx4 v[190:191], off
	s_waitcnt lgkmcnt(0)
	s_barrier
	s_waitcnt lgkmcnt(0)
	v_mfma_f32_16x16x32_bf16 v[126:129], v[130:133], v[182:185], 0
	v_mfma_f32_16x16x32_bf16 v[122:125], v[138:141], v[182:185], 0
	v_mfma_f32_16x16x32_bf16 v[110:113], v[130:133], v[202:205], 0
	v_mfma_f32_16x16x32_bf16 v[106:109], v[138:141], v[202:205], 0
	v_mfma_f32_16x16x32_bf16 v[94:97], v[130:133], v[210:213], 0
	v_mfma_f32_16x16x32_bf16 v[90:93], v[138:141], v[210:213], 0
	v_mfma_f32_16x16x32_bf16 v[78:81], v[130:133], v[218:221], 0
	v_mfma_f32_16x16x32_bf16 v[74:77], v[138:141], v[218:221], 0
	v_mfma_f32_16x16x32_bf16 v[126:129], v[134:137], v[186:189], v[126:129]
	v_mfma_f32_16x16x32_bf16 v[122:125], v[142:145], v[186:189], v[122:125]
	v_mfma_f32_16x16x32_bf16 v[110:113], v[134:137], v[206:209], v[110:113]
	v_mfma_f32_16x16x32_bf16 v[106:109], v[142:145], v[206:209], v[106:109]
	v_mfma_f32_16x16x32_bf16 v[94:97], v[134:137], v[214:217], v[94:97]
	v_mfma_f32_16x16x32_bf16 v[90:93], v[142:145], v[214:217], v[90:93]
	v_mfma_f32_16x16x32_bf16 v[78:81], v[134:137], v[222:225], v[78:81]
	v_mfma_f32_16x16x32_bf16 v[74:77], v[142:145], v[222:225], v[74:77]
	v_mfma_f32_16x16x32_bf16 v[118:121], v[166:169], v[182:185], 0
	v_mfma_f32_16x16x32_bf16 v[114:117], v[174:177], v[182:185], 0
	v_mfma_f32_16x16x32_bf16 v[102:105], v[166:169], v[202:205], 0
	v_mfma_f32_16x16x32_bf16 v[98:101], v[174:177], v[202:205], 0
	v_mfma_f32_16x16x32_bf16 v[86:89], v[166:169], v[210:213], 0
	v_mfma_f32_16x16x32_bf16 v[82:85], v[174:177], v[210:213], 0
	v_mfma_f32_16x16x32_bf16 v[70:73], v[166:169], v[218:221], 0
	v_mfma_f32_16x16x32_bf16 v[66:69], v[174:177], v[218:221], 0
	v_mfma_f32_16x16x32_bf16 v[118:121], v[170:173], v[186:189], v[118:121]
	v_mfma_f32_16x16x32_bf16 v[114:117], v[178:181], v[186:189], v[114:117]
	v_mfma_f32_16x16x32_bf16 v[102:105], v[170:173], v[206:209], v[102:105]
	v_mfma_f32_16x16x32_bf16 v[98:101], v[178:181], v[206:209], v[98:101]
	v_mfma_f32_16x16x32_bf16 v[86:89], v[170:173], v[214:217], v[86:89]
	v_mfma_f32_16x16x32_bf16 v[82:85], v[178:181], v[214:217], v[82:85]
	v_mfma_f32_16x16x32_bf16 v[70:73], v[170:173], v[222:225], v[70:73]
	v_mfma_f32_16x16x32_bf16 v[66:69], v[178:181], v[222:225], v[66:69]
	s_barrier
	s_add_i32 s14, s64, s28
	s_mov_b32 m0, s14
	ds_read_b128 v[182:185], v198 offset:16384
	ds_read_b128 v[186:189], v198 offset:17408
	ds_read_b128 v[202:205], v198 offset:18432
	ds_read_b128 v[206:209], v198 offset:19456
	ds_read_b128 v[210:213], v198 offset:20480
	ds_read_b128 v[214:217], v198 offset:21504
	ds_read_b128 v[218:221], v198 offset:22528
	ds_read_b128 v[222:225], v198 offset:23552
	global_load_lds_dwordx4 v148, s[56:57]
	s_add_i32 m0, s14, 0x2000
	s_add_u32 s14, s56, 0x58000
	s_addc_u32 s15, s57, 0
	s_add_i32 s16, s65, s28
	global_load_lds_dwordx4 v152, s[56:57]
	s_mov_b32 m0, s16
	s_nop 0
	global_load_lds_dwordx4 v148, s[14:15]
	s_add_i32 m0, s16, 0x2000
	s_nop 0
	global_load_lds_dwordx4 v152, s[14:15]
	s_mov_b32 m0, s29
	s_nop 0
	global_load_lds_dwordx4 v146, s[58:59]
	s_mov_b32 m0, s30
	s_nop 0
	global_load_lds_dwordx4 v150, s[58:59]
	s_waitcnt lgkmcnt(0)
	s_barrier
	s_waitcnt lgkmcnt(0)
	v_mfma_f32_16x16x32_bf16 v[62:65], v[130:133], v[182:185], 0
	v_mfma_f32_16x16x32_bf16 v[58:61], v[138:141], v[182:185], 0
	v_mfma_f32_16x16x32_bf16 v[46:49], v[130:133], v[202:205], 0
	v_mfma_f32_16x16x32_bf16 v[42:45], v[138:141], v[202:205], 0
	v_mfma_f32_16x16x32_bf16 v[30:33], v[130:133], v[210:213], 0
	v_mfma_f32_16x16x32_bf16 v[26:29], v[138:141], v[210:213], 0
	v_mfma_f32_16x16x32_bf16 v[14:17], v[130:133], v[218:221], 0
	v_mfma_f32_16x16x32_bf16 v[10:13], v[138:141], v[218:221], 0
	v_mfma_f32_16x16x32_bf16 v[62:65], v[134:137], v[186:189], v[62:65]
	v_mfma_f32_16x16x32_bf16 v[58:61], v[142:145], v[186:189], v[58:61]
	v_mfma_f32_16x16x32_bf16 v[46:49], v[134:137], v[206:209], v[46:49]
	v_mfma_f32_16x16x32_bf16 v[42:45], v[142:145], v[206:209], v[42:45]
	v_mfma_f32_16x16x32_bf16 v[30:33], v[134:137], v[214:217], v[30:33]
	v_mfma_f32_16x16x32_bf16 v[26:29], v[142:145], v[214:217], v[26:29]
	v_mfma_f32_16x16x32_bf16 v[14:17], v[134:137], v[222:225], v[14:17]
	v_mfma_f32_16x16x32_bf16 v[10:13], v[142:145], v[222:225], v[10:13]
	v_mfma_f32_16x16x32_bf16 v[54:57], v[166:169], v[182:185], 0
	v_mfma_f32_16x16x32_bf16 v[50:53], v[174:177], v[182:185], 0
	v_mfma_f32_16x16x32_bf16 v[38:41], v[166:169], v[202:205], 0
	v_mfma_f32_16x16x32_bf16 v[34:37], v[174:177], v[202:205], 0
	v_mfma_f32_16x16x32_bf16 v[22:25], v[166:169], v[210:213], 0
	v_mfma_f32_16x16x32_bf16 v[18:21], v[174:177], v[210:213], 0
	v_mfma_f32_16x16x32_bf16 v[6:9], v[166:169], v[218:221], 0
	v_mfma_f32_16x16x32_bf16 v[2:5], v[174:177], v[218:221], 0
	v_mfma_f32_16x16x32_bf16 v[54:57], v[170:173], v[186:189], v[54:57]
	v_mfma_f32_16x16x32_bf16 v[50:53], v[178:181], v[186:189], v[50:53]
	v_mfma_f32_16x16x32_bf16 v[38:41], v[170:173], v[206:209], v[38:41]
	v_mfma_f32_16x16x32_bf16 v[34:37], v[178:181], v[206:209], v[34:37]
	v_mfma_f32_16x16x32_bf16 v[22:25], v[170:173], v[214:217], v[22:25]
	v_mfma_f32_16x16x32_bf16 v[18:21], v[178:181], v[214:217], v[18:21]
	v_mfma_f32_16x16x32_bf16 v[6:9], v[170:173], v[222:225], v[6:9]
	v_mfma_f32_16x16x32_bf16 v[2:5], v[178:181], v[222:225], v[2:5]
	s_barrier
; #define PG8_STAGE(bufoff, gbase, voff) do { _Pragma("unroll") for (int _i = 0; _i < 2; ++_i) \
;         __builtin_amdgcn_global_load_lds((const unsigned*)((const char*)(gbase) + (voff)[_i]), (LAS unsigned*)(lds + (bufoff) + ldsw + _i * 8192), 16, 0, 0); } while (0)
; #define PG8_LDA(dst, b, h) do { _Pragma("unroll") for (int m = 0; m < 4; ++m) _Pragma("unroll") for (int k = 0; k < 2; ++k) dst[m][k] = *(const LAS bf16x8*)(lds + PG8_SA(b, h) + aoff + m * 2048 + k * 1024); } while (0)
; #define PG8_LDB(dst, b, h) do { _Pragma("unroll") for (int n = 0; n < 2; ++n) _Pragma("unroll") for (int k = 0; k < 2; ++k) dst[n][k] = *(const LAS bf16x8*)(lds + PG8_SB(b, h) + boff + n * 2048 + k * 1024); } while (0)
; #define PG8_MMA(ai, bj, At, Bt) do { __builtin_amdgcn_s_setprio(1); _Pragma("unroll") for (int m = 0; m < 4; ++m) _Pragma("unroll") for (int n = 0; n < 2; ++n) _Pragma("unroll") for (int k = 0; k < 2; ++k) \
;         acc[ai][bj][m][n] = __builtin_amdgcn_mfma_f32_16x16x32_bf16(Bt[n][k], At[m][k], acc[ai][bj][m][n], 0, 0, 0); __builtin_amdgcn_s_setprio(0); } while (0)
; #define PG8_WAIT_V(n) asm volatile("s_waitcnt vmcnt(" #n ")" ::: "memory")
; #define PG8_WAIT_L(n) asm volatile("s_waitcnt lgkmcnt(" #n ")" ::: "memory")
; #define PG8_BAR __builtin_amdgcn_s_barrier()
; #define PG8_SCHED __builtin_amdgcn_sched_barrier(0)
; template <class Epi, class Sched, bool ALIGN_EPI = false, bool SP2 = false>
; __device__ __forceinline__ void gemm_phase(LAS unsigned char* lds, const Gemm g, const Sched& S, const Epi& E) {
;     ...
;             PG8_LDB(B0, 1, 0); PG8_LDB(B1, 1, 1); PG8_SCHED; PG8_LDA(At, 1, 0); PG8_STAGE(PG8_SA(0, 1), a2 + hstep, voffA);
;             PG8_WAIT_V(8); PG8_WAIT_L(0); PG8_BAR; PG8_MMA(0, 0, At, B0); PG8_MMA(0, 1, At, B1); PG8_BAR; PG8_SCHED;
;             PG8_LDA(At, 1, 1); PG8_STAGE(PG8_SB(1, 0), b3, voffB); PG8_STAGE(PG8_SB(1, 1), b3 + hstepB, voffB); PG8_STAGE(PG8_SA(1, 0), a3, voffA);
;             PG8_WAIT_V(8); PG8_WAIT_L(0); PG8_BAR; PG8_MMA(1, 0, At, B0); PG8_MMA(1, 1, At, B1); PG8_BAR; PG8_SCHED;
	s_add_i32 s16, 0, 0x18000
	s_add_i32 s17, 0, 0x1c000
	v_add_u32_e32 v142, s16, v1
	v_add_u32_e32 v154, s17, v1
	ds_read_b128 v[130:133], v142
	ds_read_b128 v[134:137], v142 offset:1024
	ds_read_b128 v[138:141], v142 offset:2048
	ds_read_b128 v[142:145], v142 offset:3072
	ds_read_b128 v[166:169], v154
	ds_read_b128 v[170:173], v154 offset:1024
	ds_read_b128 v[174:177], v154 offset:2048
	ds_read_b128 v[178:181], v154 offset:3072
	s_add_u32 s14, s58, 0x160000
	s_addc_u32 s15, s59, 0
	s_mov_b32 m0, s31
	ds_read_b128 v[182:185], v198 offset:32768
	ds_read_b128 v[186:189], v198 offset:33792
	ds_read_b128 v[202:205], v198 offset:34816
	ds_read_b128 v[206:209], v198 offset:35840
	ds_read_b128 v[210:213], v198 offset:36864
	ds_read_b128 v[214:217], v198 offset:37888
	ds_read_b128 v[218:221], v198 offset:38912
	ds_read_b128 v[222:225], v198 offset:39936
	global_load_lds_dwordx4 v146, s[14:15]
	s_mov_b32 m0, s33
	s_nop 0
	global_load_lds_dwordx4 v150, s[14:15]
	s_waitcnt vmcnt(8)
	s_waitcnt lgkmcnt(0)
	s_barrier
	s_waitcnt lgkmcnt(0)
	v_mfma_f32_16x16x32_bf16 v[126:129], v[130:133], v[182:185], v[126:129]
	v_mfma_f32_16x16x32_bf16 v[122:125], v[138:141], v[182:185], v[122:125]
	v_mfma_f32_16x16x32_bf16 v[110:113], v[130:133], v[202:205], v[110:113]
	v_mfma_f32_16x16x32_bf16 v[106:109], v[138:141], v[202:205], v[106:109]
	v_mfma_f32_16x16x32_bf16 v[94:97], v[130:133], v[210:213], v[94:97]
	v_mfma_f32_16x16x32_bf16 v[90:93], v[138:141], v[210:213], v[90:93]
	v_mfma_f32_16x16x32_bf16 v[78:81], v[130:133], v[218:221], v[78:81]
	v_mfma_f32_16x16x32_bf16 v[74:77], v[138:141], v[218:221], v[74:77]
	v_mfma_f32_16x16x32_bf16 v[126:129], v[134:137], v[186:189], v[126:129]
	v_mfma_f32_16x16x32_bf16 v[122:125], v[142:145], v[186:189], v[122:125]
	v_mfma_f32_16x16x32_bf16 v[110:113], v[134:137], v[206:209], v[110:113]
	v_mfma_f32_16x16x32_bf16 v[106:109], v[142:145], v[206:209], v[106:109]
	v_mfma_f32_16x16x32_bf16 v[94:97], v[134:137], v[214:217], v[94:97]
	v_mfma_f32_16x16x32_bf16 v[90:93], v[142:145], v[214:217], v[90:93]
	v_mfma_f32_16x16x32_bf16 v[78:81], v[134:137], v[222:225], v[78:81]
	v_mfma_f32_16x16x32_bf16 v[74:77], v[142:145], v[222:225], v[74:77]
	v_mfma_f32_16x16x32_bf16 v[118:121], v[166:169], v[182:185], v[118:121]
	v_mfma_f32_16x16x32_bf16 v[114:117], v[174:177], v[182:185], v[114:117]
	v_mfma_f32_16x16x32_bf16 v[102:105], v[166:169], v[202:205], v[102:105]
	v_mfma_f32_16x16x32_bf16 v[98:101], v[174:177], v[202:205], v[98:101]
	v_mfma_f32_16x16x32_bf16 v[86:89], v[166:169], v[210:213], v[86:89]
	v_mfma_f32_16x16x32_bf16 v[82:85], v[174:177], v[210:213], v[82:85]
	v_mfma_f32_16x16x32_bf16 v[70:73], v[166:169], v[218:221], v[70:73]
	v_mfma_f32_16x16x32_bf16 v[66:69], v[174:177], v[218:221], v[66:69]
	v_mfma_f32_16x16x32_bf16 v[118:121], v[170:173], v[186:189], v[118:121]
	v_mfma_f32_16x16x32_bf16 v[114:117], v[178:181], v[186:189], v[114:117]
	v_mfma_f32_16x16x32_bf16 v[102:105], v[170:173], v[206:209], v[102:105]
	v_mfma_f32_16x16x32_bf16 v[98:101], v[178:181], v[206:209], v[98:101]
	v_mfma_f32_16x16x32_bf16 v[86:89], v[170:173], v[214:217], v[86:89]
	v_mfma_f32_16x16x32_bf16 v[82:85], v[178:181], v[214:217], v[82:85]
	v_mfma_f32_16x16x32_bf16 v[70:73], v[170:173], v[222:225], v[70:73]
	v_mfma_f32_16x16x32_bf16 v[66:69], v[178:181], v[222:225], v[66:69]
	s_barrier
	s_add_u32 s98, s56, 0x80
	s_addc_u32 s99, s57, 0
	s_add_u32 s100, s58, 0x80
	s_addc_u32 s101, s59, 0
	s_add_i32 s14, s16, s28
	s_mov_b32 m0, s14
	ds_read_b128 v[182:185], v198 offset:49152
	ds_read_b128 v[186:189], v198 offset:50176
	ds_read_b128 v[202:205], v198 offset:51200
	ds_read_b128 v[206:209], v198 offset:52224
	ds_read_b128 v[210:213], v198 offset:53248
	ds_read_b128 v[214:217], v198 offset:54272
	ds_read_b128 v[218:221], v198 offset:55296
	ds_read_b128 v[222:225], v198 offset:56320
	global_load_lds_dwordx4 v148, s[98:99]
	s_add_i32 m0, s14, 0x2000
	s_add_u32 s14, s56, 0x58080
	s_addc_u32 s15, s57, 0
	s_add_i32 s16, s17, s28
	global_load_lds_dwordx4 v152, s[98:99]
	s_mov_b32 m0, s16
	s_nop 0
	global_load_lds_dwordx4 v148, s[14:15]
	s_add_i32 m0, s16, 0x2000
	s_nop 0
	global_load_lds_dwordx4 v152, s[14:15]
	s_mov_b32 m0, s61
	s_nop 0
	global_load_lds_dwordx4 v146, s[100:101]
	s_mov_b32 m0, s62
	s_nop 0
	global_load_lds_dwordx4 v150, s[100:101]
	s_waitcnt vmcnt(8)
	s_waitcnt lgkmcnt(0)
	s_barrier
	s_waitcnt lgkmcnt(0)
	v_mfma_f32_16x16x32_bf16 v[62:65], v[130:133], v[182:185], v[62:65]
	v_mfma_f32_16x16x32_bf16 v[58:61], v[138:141], v[182:185], v[58:61]
	v_mfma_f32_16x16x32_bf16 v[46:49], v[130:133], v[202:205], v[46:49]
	v_mfma_f32_16x16x32_bf16 v[42:45], v[138:141], v[202:205], v[42:45]
	v_mfma_f32_16x16x32_bf16 v[30:33], v[130:133], v[210:213], v[30:33]
	v_mfma_f32_16x16x32_bf16 v[26:29], v[138:141], v[210:213], v[26:29]
	v_mfma_f32_16x16x32_bf16 v[14:17], v[130:133], v[218:221], v[14:17]
	v_mfma_f32_16x16x32_bf16 v[10:13], v[138:141], v[218:221], v[10:13]
	v_mfma_f32_16x16x32_bf16 v[62:65], v[134:137], v[186:189], v[62:65]
	v_mfma_f32_16x16x32_bf16 v[58:61], v[142:145], v[186:189], v[58:61]
	v_mfma_f32_16x16x32_bf16 v[46:49], v[134:137], v[206:209], v[46:49]
	v_mfma_f32_16x16x32_bf16 v[42:45], v[142:145], v[206:209], v[42:45]
	v_mfma_f32_16x16x32_bf16 v[30:33], v[134:137], v[214:217], v[30:33]
	v_mfma_f32_16x16x32_bf16 v[26:29], v[142:145], v[214:217], v[26:29]
	v_mfma_f32_16x16x32_bf16 v[14:17], v[134:137], v[222:225], v[14:17]
	v_mfma_f32_16x16x32_bf16 v[10:13], v[142:145], v[222:225], v[10:13]
	v_mfma_f32_16x16x32_bf16 v[54:57], v[166:169], v[182:185], v[54:57]
	v_mfma_f32_16x16x32_bf16 v[50:53], v[174:177], v[182:185], v[50:53]
	v_mfma_f32_16x16x32_bf16 v[38:41], v[166:169], v[202:205], v[38:41]
	v_mfma_f32_16x16x32_bf16 v[34:37], v[174:177], v[202:205], v[34:37]
	v_mfma_f32_16x16x32_bf16 v[22:25], v[166:169], v[210:213], v[22:25]
	v_mfma_f32_16x16x32_bf16 v[18:21], v[174:177], v[210:213], v[18:21]
	v_mfma_f32_16x16x32_bf16 v[6:9], v[166:169], v[218:221], v[6:9]
	v_mfma_f32_16x16x32_bf16 v[2:5], v[174:177], v[218:221], v[2:5]
	v_mfma_f32_16x16x32_bf16 v[54:57], v[170:173], v[186:189], v[54:57]
	v_mfma_f32_16x16x32_bf16 v[50:53], v[178:181], v[186:189], v[50:53]
	v_mfma_f32_16x16x32_bf16 v[38:41], v[170:173], v[206:209], v[38:41]
	v_mfma_f32_16x16x32_bf16 v[34:37], v[178:181], v[206:209], v[34:37]
	v_mfma_f32_16x16x32_bf16 v[22:25], v[170:173], v[214:217], v[22:25]
	v_mfma_f32_16x16x32_bf16 v[18:21], v[178:181], v[214:217], v[18:21]
	v_mfma_f32_16x16x32_bf16 v[6:9], v[170:173], v[222:225], v[6:9]
	v_mfma_f32_16x16x32_bf16 v[2:5], v[178:181], v[222:225], v[2:5]
	s_barrier
	s_add_i32 s13, s13, 2
	s_add_u32 s5, s5, 0x100
	s_addc_u32 s12, s12, 0
	s_cmpk_gt_u32 s13, 0x55
	s_mov_b64 s[16:17], s[54:55]
; #define PG8_STAGE(bufoff, gbase, voff) do { _Pragma("unroll") for (int _i = 0; _i < 2; ++_i) \
;         __builtin_amdgcn_global_load_lds((const unsigned*)((const char*)(gbase) + (voff)[_i]), (LAS unsigned*)(lds + (bufoff) + ldsw + _i * 8192), 16, 0, 0); } while (0)
; #define PG8_LDA(dst, b, h) do { _Pragma("unroll") for (int m = 0; m < 4; ++m) _Pragma("unroll") for (int k = 0; k < 2; ++k) dst[m][k] = *(const LAS bf16x8*)(lds + PG8_SA(b, h) + aoff + m * 2048 + k * 1024); } while (0)
; #define PG8_LDB(dst, b, h) do { _Pragma("unroll") for (int n = 0; n < 2; ++n) _Pragma("unroll") for (int k = 0; k < 2; ++k) dst[n][k] = *(const LAS bf16x8*)(lds + PG8_SB(b, h) + boff + n * 2048 + k * 1024); } while (0)
; #define PG8_MMA(ai, bj, At, Bt) do { __builtin_amdgcn_s_setprio(1); _Pragma("unroll") for (int m = 0; m < 4; ++m) _Pragma("unroll") for (int n = 0; n < 2; ++n) _Pragma("unroll") for (int k = 0; k < 2; ++k) \
;         acc[ai][bj][m][n] = __builtin_amdgcn_mfma_f32_16x16x32_bf16(Bt[n][k], At[m][k], acc[ai][bj][m][n], 0, 0, 0); __builtin_amdgcn_s_setprio(0); } while (0)
; #define PG8_WAIT_V(n) asm volatile("s_waitcnt vmcnt(" #n ")" ::: "memory")
; #define PG8_WAIT_L(n) asm volatile("s_waitcnt lgkmcnt(" #n ")" ::: "memory")
; #define PG8_BAR __builtin_amdgcn_s_barrier()
; template <class Epi, class Sched, bool ALIGN_EPI = false, bool SP2 = false>
; __device__ __forceinline__ void gemm_phase(LAS unsigned char* lds, const Gemm g, const Sched& S, const Epi& E) {
;     ...
;             const bool last = (t == nt - 2);
;             const char* a1 = cA + (size_t)(t + 1) * kstep;
;             const char* a2 = last ? nA : cA + (size_t)(t + 2) * kstep; const char* b2 = last ? nB : cB + (size_t)(t + 2) * kstep;
;             const char* a3 = a2 + kstep; const char* b3 = b2 + kstep;
;             if (last && has_next) S.a_ready(nxt);
;             if constexpr (SP2) {
;             PG8_LDB(B0, 0, 0); PG8_LDB(B1, 0, 1); PG8_SCHED; PG8_LDA(At, 0, 0); PG8_STAGE(PG8_SA(1, 1), a1 + hstep, voffA);
;             PG8_WAIT_V(8); PG8_WAIT_L(0); PG8_BAR; PG8_MMA(0, 0, At, B0); PG8_MMA(0, 1, At, B1); PG8_BAR; PG8_SCHED;
;             PG8_LDA(At, 0, 1); PG8_STAGE(PG8_SB(0, 0), b2, voffB); PG8_STAGE(PG8_SB(0, 1), b2 + hstepB, voffB); PG8_STAGE(PG8_SA(0, 0), a2, voffA);
;             PG8_WAIT_V(8); PG8_WAIT_L(0); PG8_BAR; PG8_MMA(1, 0, At, B0); PG8_MMA(1, 1, At, B1); PG8_BAR; PG8_SCHED;
.LBB0_317:
	ds_read_b128 v[130:133], v196
	ds_read_b128 v[134:137], v196 offset:1024
	ds_read_b128 v[138:141], v196 offset:2048
	ds_read_b128 v[142:145], v196 offset:3072
	ds_read_b128 v[166:169], v197
	ds_read_b128 v[170:173], v197 offset:1024
	ds_read_b128 v[174:177], v197 offset:2048
	ds_read_b128 v[178:181], v197 offset:3072
	s_add_u32 s54, s16, 0x100
	s_addc_u32 s55, s17, 0
	s_cmpk_eq_i32 s13, 0x54
	s_cselect_b32 s59, s3, s55
	s_cselect_b32 s58, s2, s54
	s_cselect_b32 s57, s53, s12
	s_cselect_b32 s56, s52, s5
	v_lshl_add_u64 v[190:191], s[16:17], 0, v[158:159]
	s_add_i32 m0, s29, 0xc000
	ds_read_b128 v[182:185], v198
	ds_read_b128 v[186:189], v198 offset:1024
	ds_read_b128 v[202:205], v198 offset:2048
	ds_read_b128 v[206:209], v198 offset:3072
	ds_read_b128 v[210:213], v198 offset:4096
	ds_read_b128 v[214:217], v198 offset:5120
	ds_read_b128 v[218:221], v198 offset:6144
	ds_read_b128 v[222:225], v198 offset:7168
	global_load_lds_dwordx4 v[190:191], off
	v_lshl_add_u64 v[190:191], s[16:17], 0, v[160:161]
	s_add_i32 m0, s29, 0xe000
	s_nop 0
	global_load_lds_dwordx4 v[190:191], off
	s_waitcnt vmcnt(8)
	s_waitcnt lgkmcnt(0)
	s_barrier
	s_waitcnt lgkmcnt(0)
	v_mfma_f32_16x16x32_bf16 v[126:129], v[130:133], v[182:185], v[126:129]
	v_mfma_f32_16x16x32_bf16 v[122:125], v[138:141], v[182:185], v[122:125]
	v_mfma_f32_16x16x32_bf16 v[110:113], v[130:133], v[202:205], v[110:113]
	v_mfma_f32_16x16x32_bf16 v[106:109], v[138:141], v[202:205], v[106:109]
	v_mfma_f32_16x16x32_bf16 v[94:97], v[130:133], v[210:213], v[94:97]
	v_mfma_f32_16x16x32_bf16 v[90:93], v[138:141], v[210:213], v[90:93]
	v_mfma_f32_16x16x32_bf16 v[78:81], v[130:133], v[218:221], v[78:81]
	v_mfma_f32_16x16x32_bf16 v[74:77], v[138:141], v[218:221], v[74:77]
	v_mfma_f32_16x16x32_bf16 v[126:129], v[134:137], v[186:189], v[126:129]
	v_mfma_f32_16x16x32_bf16 v[122:125], v[142:145], v[186:189], v[122:125]
	v_mfma_f32_16x16x32_bf16 v[110:113], v[134:137], v[206:209], v[110:113]
	v_mfma_f32_16x16x32_bf16 v[106:109], v[142:145], v[206:209], v[106:109]
	v_mfma_f32_16x16x32_bf16 v[94:97], v[134:137], v[214:217], v[94:97]
	v_mfma_f32_16x16x32_bf16 v[90:93], v[142:145], v[214:217], v[90:93]
	v_mfma_f32_16x16x32_bf16 v[78:81], v[134:137], v[222:225], v[78:81]
	v_mfma_f32_16x16x32_bf16 v[74:77], v[142:145], v[222:225], v[74:77]
	v_mfma_f32_16x16x32_bf16 v[118:121], v[166:169], v[182:185], v[118:121]
	v_mfma_f32_16x16x32_bf16 v[114:117], v[174:177], v[182:185], v[114:117]
	v_mfma_f32_16x16x32_bf16 v[102:105], v[166:169], v[202:205], v[102:105]
	v_mfma_f32_16x16x32_bf16 v[98:101], v[174:177], v[202:205], v[98:101]
	v_mfma_f32_16x16x32_bf16 v[86:89], v[166:169], v[210:213], v[86:89]
	v_mfma_f32_16x16x32_bf16 v[82:85], v[174:177], v[210:213], v[82:85]
	v_mfma_f32_16x16x32_bf16 v[70:73], v[166:169], v[218:221], v[70:73]
	v_mfma_f32_16x16x32_bf16 v[66:69], v[174:177], v[218:221], v[66:69]
	v_mfma_f32_16x16x32_bf16 v[118:121], v[170:173], v[186:189], v[118:121]
	v_mfma_f32_16x16x32_bf16 v[114:117], v[178:181], v[186:189], v[114:117]
	v_mfma_f32_16x16x32_bf16 v[102:105], v[170:173], v[206:209], v[102:105]
	v_mfma_f32_16x16x32_bf16 v[98:101], v[178:181], v[206:209], v[98:101]
	v_mfma_f32_16x16x32_bf16 v[86:89], v[170:173], v[214:217], v[86:89]
	v_mfma_f32_16x16x32_bf16 v[82:85], v[178:181], v[214:217], v[82:85]
	v_mfma_f32_16x16x32_bf16 v[70:73], v[170:173], v[222:225], v[70:73]
	v_mfma_f32_16x16x32_bf16 v[66:69], v[178:181], v[222:225], v[66:69]
	s_barrier
	s_add_i32 s14, s64, s28
	s_mov_b32 m0, s14
	ds_read_b128 v[182:185], v198 offset:16384
	ds_read_b128 v[186:189], v198 offset:17408
	ds_read_b128 v[202:205], v198 offset:18432
	ds_read_b128 v[206:209], v198 offset:19456
	ds_read_b128 v[210:213], v198 offset:20480
	ds_read_b128 v[214:217], v198 offset:21504
	ds_read_b128 v[218:221], v198 offset:22528
	ds_read_b128 v[222:225], v198 offset:23552
	global_load_lds_dwordx4 v148, s[56:57]
	s_add_i32 m0, s14, 0x2000
	s_add_u32 s14, s56, 0x58000
	s_addc_u32 s15, s57, 0
	s_add_i32 s16, s65, s28
	global_load_lds_dwordx4 v152, s[56:57]
	s_mov_b32 m0, s16
	s_nop 0
	global_load_lds_dwordx4 v148, s[14:15]
	s_add_i32 m0, s16, 0x2000
	s_nop 0
	global_load_lds_dwordx4 v152, s[14:15]
	s_mov_b32 m0, s29
	s_nop 0
	global_load_lds_dwordx4 v146, s[58:59]
	s_mov_b32 m0, s30
	s_nop 0
	global_load_lds_dwordx4 v150, s[58:59]
	s_waitcnt vmcnt(8)
	s_waitcnt lgkmcnt(0)
	s_barrier
	s_waitcnt lgkmcnt(0)
	v_mfma_f32_16x16x32_bf16 v[62:65], v[130:133], v[182:185], v[62:65]
	v_mfma_f32_16x16x32_bf16 v[58:61], v[138:141], v[182:185], v[58:61]
	v_mfma_f32_16x16x32_bf16 v[46:49], v[130:133], v[202:205], v[46:49]
	v_mfma_f32_16x16x32_bf16 v[42:45], v[138:141], v[202:205], v[42:45]
	v_mfma_f32_16x16x32_bf16 v[30:33], v[130:133], v[210:213], v[30:33]
	v_mfma_f32_16x16x32_bf16 v[26:29], v[138:141], v[210:213], v[26:29]
	v_mfma_f32_16x16x32_bf16 v[14:17], v[130:133], v[218:221], v[14:17]
	v_mfma_f32_16x16x32_bf16 v[10:13], v[138:141], v[218:221], v[10:13]
	v_mfma_f32_16x16x32_bf16 v[62:65], v[134:137], v[186:189], v[62:65]
	v_mfma_f32_16x16x32_bf16 v[58:61], v[142:145], v[186:189], v[58:61]
	v_mfma_f32_16x16x32_bf16 v[46:49], v[134:137], v[206:209], v[46:49]
	v_mfma_f32_16x16x32_bf16 v[42:45], v[142:145], v[206:209], v[42:45]
	v_mfma_f32_16x16x32_bf16 v[30:33], v[134:137], v[214:217], v[30:33]
	v_mfma_f32_16x16x32_bf16 v[26:29], v[142:145], v[214:217], v[26:29]
	v_mfma_f32_16x16x32_bf16 v[14:17], v[134:137], v[222:225], v[14:17]
	v_mfma_f32_16x16x32_bf16 v[10:13], v[142:145], v[222:225], v[10:13]
	v_mfma_f32_16x16x32_bf16 v[54:57], v[166:169], v[182:185], v[54:57]
	v_mfma_f32_16x16x32_bf16 v[50:53], v[174:177], v[182:185], v[50:53]
	v_mfma_f32_16x16x32_bf16 v[38:41], v[166:169], v[202:205], v[38:41]
	v_mfma_f32_16x16x32_bf16 v[34:37], v[174:177], v[202:205], v[34:37]
	v_mfma_f32_16x16x32_bf16 v[22:25], v[166:169], v[210:213], v[22:25]
	v_mfma_f32_16x16x32_bf16 v[18:21], v[174:177], v[210:213], v[18:21]
	v_mfma_f32_16x16x32_bf16 v[6:9], v[166:169], v[218:221], v[6:9]
	v_mfma_f32_16x16x32_bf16 v[2:5], v[174:177], v[218:221], v[2:5]
	v_mfma_f32_16x16x32_bf16 v[54:57], v[170:173], v[186:189], v[54:57]
	v_mfma_f32_16x16x32_bf16 v[50:53], v[178:181], v[186:189], v[50:53]
	v_mfma_f32_16x16x32_bf16 v[38:41], v[170:173], v[206:209], v[38:41]
	v_mfma_f32_16x16x32_bf16 v[34:37], v[178:181], v[206:209], v[34:37]
	v_mfma_f32_16x16x32_bf16 v[22:25], v[170:173], v[214:217], v[22:25]
	v_mfma_f32_16x16x32_bf16 v[18:21], v[178:181], v[214:217], v[18:21]
	v_mfma_f32_16x16x32_bf16 v[6:9], v[170:173], v[222:225], v[6:9]
	v_mfma_f32_16x16x32_bf16 v[2:5], v[178:181], v[222:225], v[2:5]
	s_barrier
; #define PG8_STAGE(bufoff, gbase, voff) do { _Pragma("unroll") for (int _i = 0; _i < 2; ++_i) \
;         __builtin_amdgcn_global_load_lds((const unsigned*)((const char*)(gbase) + (voff)[_i]), (LAS unsigned*)(lds + (bufoff) + ldsw + _i * 8192), 16, 0, 0); } while (0)
; #define PG8_LDA(dst, b, h) do { _Pragma("unroll") for (int m = 0; m < 4; ++m) _Pragma("unroll") for (int k = 0; k < 2; ++k) dst[m][k] = *(const LAS bf16x8*)(lds + PG8_SA(b, h) + aoff + m * 2048 + k * 1024); } while (0)
; #define PG8_LDB(dst, b, h) do { _Pragma("unroll") for (int n = 0; n < 2; ++n) _Pragma("unroll") for (int k = 0; k < 2; ++k) dst[n][k] = *(const LAS bf16x8*)(lds + PG8_SB(b, h) + boff + n * 2048 + k * 1024); } while (0)
; #define PG8_MMA(ai, bj, At, Bt) do { __builtin_amdgcn_s_setprio(1); _Pragma("unroll") for (int m = 0; m < 4; ++m) _Pragma("unroll") for (int n = 0; n < 2; ++n) _Pragma("unroll") for (int k = 0; k < 2; ++k) \
;         acc[ai][bj][m][n] = __builtin_amdgcn_mfma_f32_16x16x32_bf16(Bt[n][k], At[m][k], acc[ai][bj][m][n], 0, 0, 0); __builtin_amdgcn_s_setprio(0); } while (0)
; #define PG8_WAIT_V(n) asm volatile("s_waitcnt vmcnt(" #n ")" ::: "memory")
; #define PG8_WAIT_L(n) asm volatile("s_waitcnt lgkmcnt(" #n ")" ::: "memory")
; #define PG8_BAR __builtin_amdgcn_s_barrier()
; #define PG8_SCHED __builtin_amdgcn_sched_barrier(0)
; template <class Epi, class Sched, bool ALIGN_EPI = false, bool SP2 = false>
; __device__ __forceinline__ void gemm_phase(LAS unsigned char* lds, const Gemm g, const Sched& S, const Epi& E) {
;     ...
;             PG8_LDB(B0, 1, 0); PG8_LDB(B1, 1, 1); PG8_SCHED; PG8_LDA(At, 1, 0); PG8_STAGE(PG8_SA(0, 1), a2 + hstep, voffA);
;             PG8_WAIT_V(8); PG8_WAIT_L(0); PG8_BAR; PG8_MMA(0, 0, At, B0); PG8_MMA(0, 1, At, B1); PG8_BAR; PG8_SCHED;
;             PG8_LDA(At, 1, 1); PG8_STAGE(PG8_SB(1, 0), b3, voffB); PG8_STAGE(PG8_SB(1, 1), b3 + hstepB, voffB); PG8_STAGE(PG8_SA(1, 0), a3, voffA);
;             PG8_WAIT_V(8); PG8_WAIT_L(0); PG8_BAR; PG8_MMA(1, 0, At, B0); PG8_MMA(1, 1, At, B1); PG8_BAR; PG8_SCHED;
	s_add_i32 s16, 0, 0x18000
	s_add_i32 s17, 0, 0x1c000
	v_add_u32_e32 v142, s16, v1
	v_add_u32_e32 v154, s17, v1
	ds_read_b128 v[130:133], v142
	ds_read_b128 v[134:137], v142 offset:1024
	ds_read_b128 v[138:141], v142 offset:2048
	ds_read_b128 v[142:145], v142 offset:3072
	ds_read_b128 v[166:169], v154
	ds_read_b128 v[170:173], v154 offset:1024
	ds_read_b128 v[174:177], v154 offset:2048
	ds_read_b128 v[178:181], v154 offset:3072
	s_add_u32 s14, s58, 0x160000
	s_addc_u32 s15, s59, 0
	s_mov_b32 m0, s31
	ds_read_b128 v[182:185], v198 offset:32768
	ds_read_b128 v[186:189], v198 offset:33792
	ds_read_b128 v[202:205], v198 offset:34816
	ds_read_b128 v[206:209], v198 offset:35840
	ds_read_b128 v[210:213], v198 offset:36864
	ds_read_b128 v[214:217], v198 offset:37888
	ds_read_b128 v[218:221], v198 offset:38912
	ds_read_b128 v[222:225], v198 offset:39936
	global_load_lds_dwordx4 v146, s[14:15]
	s_mov_b32 m0, s33
	s_nop 0
	global_load_lds_dwordx4 v150, s[14:15]
	s_waitcnt vmcnt(8)
	s_waitcnt lgkmcnt(0)
	s_barrier
	s_waitcnt lgkmcnt(0)
	v_mfma_f32_16x16x32_bf16 v[126:129], v[130:133], v[182:185], v[126:129]
	v_mfma_f32_16x16x32_bf16 v[122:125], v[138:141], v[182:185], v[122:125]
	v_mfma_f32_16x16x32_bf16 v[110:113], v[130:133], v[202:205], v[110:113]
	v_mfma_f32_16x16x32_bf16 v[106:109], v[138:141], v[202:205], v[106:109]
	v_mfma_f32_16x16x32_bf16 v[94:97], v[130:133], v[210:213], v[94:97]
	v_mfma_f32_16x16x32_bf16 v[90:93], v[138:141], v[210:213], v[90:93]
	v_mfma_f32_16x16x32_bf16 v[78:81], v[130:133], v[218:221], v[78:81]
	v_mfma_f32_16x16x32_bf16 v[74:77], v[138:141], v[218:221], v[74:77]
	v_mfma_f32_16x16x32_bf16 v[126:129], v[134:137], v[186:189], v[126:129]
	v_mfma_f32_16x16x32_bf16 v[122:125], v[142:145], v[186:189], v[122:125]
	v_mfma_f32_16x16x32_bf16 v[110:113], v[134:137], v[206:209], v[110:113]
	v_mfma_f32_16x16x32_bf16 v[106:109], v[142:145], v[206:209], v[106:109]
	v_mfma_f32_16x16x32_bf16 v[94:97], v[134:137], v[214:217], v[94:97]
	v_mfma_f32_16x16x32_bf16 v[90:93], v[142:145], v[214:217], v[90:93]
	v_mfma_f32_16x16x32_bf16 v[78:81], v[134:137], v[222:225], v[78:81]
	v_mfma_f32_16x16x32_bf16 v[74:77], v[142:145], v[222:225], v[74:77]
	v_mfma_f32_16x16x32_bf16 v[118:121], v[166:169], v[182:185], v[118:121]
	v_mfma_f32_16x16x32_bf16 v[114:117], v[174:177], v[182:185], v[114:117]
	v_mfma_f32_16x16x32_bf16 v[102:105], v[166:169], v[202:205], v[102:105]
	v_mfma_f32_16x16x32_bf16 v[98:101], v[174:177], v[202:205], v[98:101]
	v_mfma_f32_16x16x32_bf16 v[86:89], v[166:169], v[210:213], v[86:89]
	v_mfma_f32_16x16x32_bf16 v[82:85], v[174:177], v[210:213], v[82:85]
	v_mfma_f32_16x16x32_bf16 v[70:73], v[166:169], v[218:221], v[70:73]
	v_mfma_f32_16x16x32_bf16 v[66:69], v[174:177], v[218:221], v[66:69]
	v_mfma_f32_16x16x32_bf16 v[118:121], v[170:173], v[186:189], v[118:121]
	v_mfma_f32_16x16x32_bf16 v[114:117], v[178:181], v[186:189], v[114:117]
	v_mfma_f32_16x16x32_bf16 v[102:105], v[170:173], v[206:209], v[102:105]
	v_mfma_f32_16x16x32_bf16 v[98:101], v[178:181], v[206:209], v[98:101]
	v_mfma_f32_16x16x32_bf16 v[86:89], v[170:173], v[214:217], v[86:89]
	v_mfma_f32_16x16x32_bf16 v[82:85], v[178:181], v[214:217], v[82:85]
	v_mfma_f32_16x16x32_bf16 v[70:73], v[170:173], v[222:225], v[70:73]
	v_mfma_f32_16x16x32_bf16 v[66:69], v[178:181], v[222:225], v[66:69]
	s_barrier
	s_add_u32 s98, s56, 0x80
	s_addc_u32 s99, s57, 0
	s_add_u32 s100, s58, 0x80
	s_addc_u32 s101, s59, 0
	s_add_i32 s14, s16, s28
	s_mov_b32 m0, s14
	ds_read_b128 v[182:185], v198 offset:49152
	ds_read_b128 v[186:189], v198 offset:50176
	ds_read_b128 v[202:205], v198 offset:51200
	ds_read_b128 v[206:209], v198 offset:52224
	ds_read_b128 v[210:213], v198 offset:53248
	ds_read_b128 v[214:217], v198 offset:54272
	ds_read_b128 v[218:221], v198 offset:55296
	ds_read_b128 v[222:225], v198 offset:56320
	global_load_lds_dwordx4 v148, s[98:99]
	s_add_i32 m0, s14, 0x2000
	s_add_u32 s14, s56, 0x58080
	s_addc_u32 s15, s57, 0
	s_add_i32 s16, s17, s28
	global_load_lds_dwordx4 v152, s[98:99]
	s_mov_b32 m0, s16
	s_nop 0
	global_load_lds_dwordx4 v148, s[14:15]
	s_add_i32 m0, s16, 0x2000
	s_nop 0
	global_load_lds_dwordx4 v152, s[14:15]
	s_mov_b32 m0, s61
	s_nop 0
	global_load_lds_dwordx4 v146, s[100:101]
	s_mov_b32 m0, s62
	s_nop 0
	global_load_lds_dwordx4 v150, s[100:101]
	s_waitcnt vmcnt(8)
	s_waitcnt lgkmcnt(0)
	s_barrier
	s_waitcnt lgkmcnt(0)
	v_mfma_f32_16x16x32_bf16 v[62:65], v[130:133], v[182:185], v[62:65]
	v_mfma_f32_16x16x32_bf16 v[58:61], v[138:141], v[182:185], v[58:61]
	v_mfma_f32_16x16x32_bf16 v[46:49], v[130:133], v[202:205], v[46:49]
	v_mfma_f32_16x16x32_bf16 v[42:45], v[138:141], v[202:205], v[42:45]
	v_mfma_f32_16x16x32_bf16 v[30:33], v[130:133], v[210:213], v[30:33]
	v_mfma_f32_16x16x32_bf16 v[26:29], v[138:141], v[210:213], v[26:29]
	v_mfma_f32_16x16x32_bf16 v[14:17], v[130:133], v[218:221], v[14:17]
	v_mfma_f32_16x16x32_bf16 v[10:13], v[138:141], v[218:221], v[10:13]
	v_mfma_f32_16x16x32_bf16 v[62:65], v[134:137], v[186:189], v[62:65]
	v_mfma_f32_16x16x32_bf16 v[58:61], v[142:145], v[186:189], v[58:61]
	v_mfma_f32_16x16x32_bf16 v[46:49], v[134:137], v[206:209], v[46:49]
	v_mfma_f32_16x16x32_bf16 v[42:45], v[142:145], v[206:209], v[42:45]
	v_mfma_f32_16x16x32_bf16 v[30:33], v[134:137], v[214:217], v[30:33]
	v_mfma_f32_16x16x32_bf16 v[26:29], v[142:145], v[214:217], v[26:29]
	v_mfma_f32_16x16x32_bf16 v[14:17], v[134:137], v[222:225], v[14:17]
	v_mfma_f32_16x16x32_bf16 v[10:13], v[142:145], v[222:225], v[10:13]
	v_mfma_f32_16x16x32_bf16 v[54:57], v[166:169], v[182:185], v[54:57]
	v_mfma_f32_16x16x32_bf16 v[50:53], v[174:177], v[182:185], v[50:53]
	v_mfma_f32_16x16x32_bf16 v[38:41], v[166:169], v[202:205], v[38:41]
	v_mfma_f32_16x16x32_bf16 v[34:37], v[174:177], v[202:205], v[34:37]
	v_mfma_f32_16x16x32_bf16 v[22:25], v[166:169], v[210:213], v[22:25]
	v_mfma_f32_16x16x32_bf16 v[18:21], v[174:177], v[210:213], v[18:21]
	v_mfma_f32_16x16x32_bf16 v[6:9], v[166:169], v[218:221], v[6:9]
	v_mfma_f32_16x16x32_bf16 v[2:5], v[174:177], v[218:221], v[2:5]
	v_mfma_f32_16x16x32_bf16 v[54:57], v[170:173], v[186:189], v[54:57]
	v_mfma_f32_16x16x32_bf16 v[50:53], v[178:181], v[186:189], v[50:53]
	v_mfma_f32_16x16x32_bf16 v[38:41], v[170:173], v[206:209], v[38:41]
	v_mfma_f32_16x16x32_bf16 v[34:37], v[178:181], v[206:209], v[34:37]
	v_mfma_f32_16x16x32_bf16 v[22:25], v[170:173], v[214:217], v[22:25]
	v_mfma_f32_16x16x32_bf16 v[18:21], v[178:181], v[214:217], v[18:21]
	v_mfma_f32_16x16x32_bf16 v[6:9], v[170:173], v[222:225], v[6:9]
	v_mfma_f32_16x16x32_bf16 v[2:5], v[178:181], v[222:225], v[2:5]
	s_barrier
	s_add_i32 s13, s13, 2
	s_add_u32 s5, s5, 0x100
	s_addc_u32 s12, s12, 0
	s_cmpk_gt_u32 s13, 0x55
	s_mov_b64 s[16:17], s[54:55]
	s_cbranch_scc0 .LBB0_317
	s_setprio 0
	s_and_b64 vcc, exec, s[50:51]
	s_cbranch_vccz .LBB0_320
	s_barrier

; #define PG8_STAGE(bufoff, gbase, voff) do { _Pragma("unroll") for (int _i = 0; _i < 2; ++_i) \
;         __builtin_amdgcn_global_load_lds((const unsigned*)((const char*)(gbase) + (voff)[_i]), (LAS unsigned*)(lds + (bufoff) + ldsw + _i * 8192), 16, 0, 0); } while (0)
; #define PG8_LDA(dst, b, h) do { _Pragma("unroll") for (int m = 0; m < 4; ++m) _Pragma("unroll") for (int k = 0; k < 2; ++k) dst[m][k] = *(const LAS bf16x8*)(lds + PG8_SA(b, h) + aoff + m * 2048 + k * 1024); } while (0)
; #define PG8_LDB(dst, b, h) do { _Pragma("unroll") for (int n = 0; n < 2; ++n) _Pragma("unroll") for (int k = 0; k < 2; ++k) dst[n][k] = *(const LAS bf16x8*)(lds + PG8_SB(b, h) + boff + n * 2048 + k * 1024); } while (0)
; #define PG8_MMA(ai, bj, At, Bt) do { __builtin_amdgcn_s_setprio(1); _Pragma("unroll") for (int m = 0; m < 4; ++m) _Pragma("unroll") for (int n = 0; n < 2; ++n) _Pragma("unroll") for (int k = 0; k < 2; ++k) \
;         acc[ai][bj][m][n] = __builtin_amdgcn_mfma_f32_16x16x32_bf16(Bt[n][k], At[m][k], acc[ai][bj][m][n], 0, 0, 0); __builtin_amdgcn_s_setprio(0); } while (0)
; #define PG8_WAIT_V(n) asm volatile("s_waitcnt vmcnt(" #n ")" ::: "memory")
; #define PG8_WAIT_L(n) asm volatile("s_waitcnt lgkmcnt(" #n ")" ::: "memory")
; #define PG8_BAR __builtin_amdgcn_s_barrier()
; template <class Epi, class Sched, bool ALIGN_EPI = false, bool SP2 = false>
; __device__ __forceinline__ void gemm_phase(LAS unsigned char* lds, const Gemm g, const Sched& S, const Epi& E) {
;     ...
;             const bool last = (t == nt - 2);
;             const char* a1 = cA + (size_t)(t + 1) * kstep;
;             const char* a2 = last ? nA : cA + (size_t)(t + 2) * kstep; const char* b2 = last ? nB : cB + (size_t)(t + 2) * kstep;
;             const char* a3 = a2 + kstep; const char* b3 = b2 + kstep;
;             if (last && has_next) S.a_ready(nxt);
;             if constexpr (SP2) {
;             PG8_LDB(B0, 0, 0); PG8_LDB(B1, 0, 1); PG8_SCHED; PG8_LDA(At, 0, 0); PG8_STAGE(PG8_SA(1, 1), a1 + hstep, voffA);
;             PG8_WAIT_V(8); PG8_WAIT_L(0); PG8_BAR; PG8_MMA(0, 0, At, B0); PG8_MMA(0, 1, At, B1); PG8_BAR; PG8_SCHED;
;             PG8_LDA(At, 0, 1); PG8_STAGE(PG8_SB(0, 0), b2, voffB); PG8_STAGE(PG8_SB(0, 1), b2 + hstepB, voffB); PG8_STAGE(PG8_SA(0, 0), a2, voffA);
;             PG8_WAIT_V(8); PG8_WAIT_L(0); PG8_BAR; PG8_MMA(1, 0, At, B0); PG8_MMA(1, 1, At, B1); PG8_BAR; PG8_SCHED;
.Lprio_535:
	ds_read_b128 v[34:37], v203
	ds_read_b128 v[38:41], v203 offset:1024
	ds_read_b128 v[42:45], v203 offset:2048
	ds_read_b128 v[46:49], v203 offset:3072
	s_waitcnt vmcnt(0)
	ds_read_b128 v[98:101], v204
	ds_read_b128 v[102:105], v204 offset:1024
	ds_read_b128 v[106:109], v204 offset:2048
	ds_read_b128 v[110:113], v204 offset:3072
	s_add_u32 s21, s16, 0xfff80080
	s_addc_u32 s22, s17, -1
	s_cmp_eq_u32 s20, 28
	s_cselect_b32 s59, s0, s22
	s_cselect_b32 s58, s3, s21
	s_cselect_b32 s49, s14, s19
	s_cselect_b32 s48, s15, s18
	s_add_i32 m0, s30, 0xc000
	ds_read_b128 v[212:215], v205
	ds_read_b128 v[216:219], v205 offset:1024
	ds_read_b128 v[220:223], v205 offset:2048
	ds_read_b128 v[224:227], v205 offset:3072
	ds_read_b128 v[228:231], v205 offset:4096
	ds_read_b128 v[232:235], v205 offset:5120
	ds_read_b128 v[236:239], v205 offset:6144
	ds_read_b128 v[240:243], v205 offset:7168
	global_load_lds_dwordx4 v172, s[16:17]
	s_add_i32 m0, s30, 0xe000
	s_nop 0
	global_load_lds_dwordx4 v174, s[16:17]
	s_waitcnt lgkmcnt(0)
	s_barrier
	s_waitcnt lgkmcnt(0)
	v_mfma_f32_16x16x32_bf16 v[158:161], v[34:37], v[212:215], 0
	v_mfma_f32_16x16x32_bf16 v[154:157], v[42:45], v[212:215], 0
	v_mfma_f32_16x16x32_bf16 v[142:145], v[34:37], v[220:223], 0
	v_mfma_f32_16x16x32_bf16 v[138:141], v[42:45], v[220:223], 0
	v_mfma_f32_16x16x32_bf16 v[126:129], v[34:37], v[228:231], 0
	v_mfma_f32_16x16x32_bf16 v[122:125], v[42:45], v[228:231], 0
	v_mfma_f32_16x16x32_bf16 v[94:97], v[34:37], v[236:239], 0
	v_mfma_f32_16x16x32_bf16 v[90:93], v[42:45], v[236:239], 0
	v_mfma_f32_16x16x32_bf16 v[158:161], v[38:41], v[216:219], v[158:161]
	v_mfma_f32_16x16x32_bf16 v[154:157], v[46:49], v[216:219], v[154:157]
	v_mfma_f32_16x16x32_bf16 v[142:145], v[38:41], v[224:227], v[142:145]
	v_mfma_f32_16x16x32_bf16 v[138:141], v[46:49], v[224:227], v[138:141]
	v_mfma_f32_16x16x32_bf16 v[126:129], v[38:41], v[232:235], v[126:129]
	v_mfma_f32_16x16x32_bf16 v[122:125], v[46:49], v[232:235], v[122:125]
	v_mfma_f32_16x16x32_bf16 v[94:97], v[38:41], v[240:243], v[94:97]
	v_mfma_f32_16x16x32_bf16 v[90:93], v[46:49], v[240:243], v[90:93]
	v_mfma_f32_16x16x32_bf16 v[150:153], v[98:101], v[212:215], 0
	v_mfma_f32_16x16x32_bf16 v[146:149], v[106:109], v[212:215], 0
	v_mfma_f32_16x16x32_bf16 v[134:137], v[98:101], v[220:223], 0
	v_mfma_f32_16x16x32_bf16 v[130:133], v[106:109], v[220:223], 0
	v_mfma_f32_16x16x32_bf16 v[118:121], v[98:101], v[228:231], 0
	v_mfma_f32_16x16x32_bf16 v[114:117], v[106:109], v[228:231], 0
	v_mfma_f32_16x16x32_bf16 v[86:89], v[98:101], v[236:239], 0
	v_mfma_f32_16x16x32_bf16 v[82:85], v[106:109], v[236:239], 0
	v_mfma_f32_16x16x32_bf16 v[150:153], v[102:105], v[216:219], v[150:153]
	v_mfma_f32_16x16x32_bf16 v[146:149], v[110:113], v[216:219], v[146:149]
	v_mfma_f32_16x16x32_bf16 v[134:137], v[102:105], v[224:227], v[134:137]
	v_mfma_f32_16x16x32_bf16 v[130:133], v[110:113], v[224:227], v[130:133]
	v_mfma_f32_16x16x32_bf16 v[118:121], v[102:105], v[232:235], v[118:121]
	v_mfma_f32_16x16x32_bf16 v[114:117], v[110:113], v[232:235], v[114:117]
	v_mfma_f32_16x16x32_bf16 v[86:89], v[102:105], v[240:243], v[86:89]
	v_mfma_f32_16x16x32_bf16 v[82:85], v[110:113], v[240:243], v[82:85]
	s_barrier
	s_add_i32 s21, s68, s29
	s_mov_b32 m0, s21
	ds_read_b128 v[212:215], v205 offset:16384
	ds_read_b128 v[216:219], v205 offset:17408
	ds_read_b128 v[220:223], v205 offset:18432
	ds_read_b128 v[224:227], v205 offset:19456
	ds_read_b128 v[228:231], v205 offset:20480
	ds_read_b128 v[232:235], v205 offset:21504
	ds_read_b128 v[236:239], v205 offset:22528
	ds_read_b128 v[240:243], v205 offset:23552
	global_load_lds_dwordx4 v164, s[48:49]
	s_add_i32 m0, s21, 0x2000
	s_add_u32 s22, s48, 0x20000
	s_addc_u32 s23, s49, 0
	s_add_i32 s21, s69, s29
	global_load_lds_dwordx4 v168, s[48:49]
	s_mov_b32 m0, s21
	s_nop 0
	global_load_lds_dwordx4 v164, s[22:23]
	s_add_i32 m0, s21, 0x2000
	s_nop 0
	global_load_lds_dwordx4 v168, s[22:23]
	s_mov_b32 m0, s30
	s_nop 0
	global_load_lds_dwordx4 v162, s[58:59]
	s_mov_b32 m0, s31
	s_nop 0
	global_load_lds_dwordx4 v166, s[58:59]
	s_waitcnt lgkmcnt(0)
	s_barrier
	s_waitcnt lgkmcnt(0)
	v_mfma_f32_16x16x32_bf16 v[78:81], v[34:37], v[212:215], 0
	v_mfma_f32_16x16x32_bf16 v[74:77], v[42:45], v[212:215], 0
	v_mfma_f32_16x16x32_bf16 v[62:65], v[34:37], v[220:223], 0
	v_mfma_f32_16x16x32_bf16 v[58:61], v[42:45], v[220:223], 0
	v_mfma_f32_16x16x32_bf16 v[30:33], v[34:37], v[228:231], 0
	v_mfma_f32_16x16x32_bf16 v[26:29], v[42:45], v[228:231], 0
	v_mfma_f32_16x16x32_bf16 v[14:17], v[34:37], v[236:239], 0
	v_mfma_f32_16x16x32_bf16 v[10:13], v[42:45], v[236:239], 0
	v_mfma_f32_16x16x32_bf16 v[78:81], v[38:41], v[216:219], v[78:81]
	v_mfma_f32_16x16x32_bf16 v[74:77], v[46:49], v[216:219], v[74:77]
	v_mfma_f32_16x16x32_bf16 v[62:65], v[38:41], v[224:227], v[62:65]
	v_mfma_f32_16x16x32_bf16 v[58:61], v[46:49], v[224:227], v[58:61]
	v_mfma_f32_16x16x32_bf16 v[30:33], v[38:41], v[232:235], v[30:33]
	v_mfma_f32_16x16x32_bf16 v[26:29], v[46:49], v[232:235], v[26:29]
	v_mfma_f32_16x16x32_bf16 v[14:17], v[38:41], v[240:243], v[14:17]
	v_mfma_f32_16x16x32_bf16 v[10:13], v[46:49], v[240:243], v[10:13]
	v_mfma_f32_16x16x32_bf16 v[22:25], v[98:101], v[228:231], 0
	v_mfma_f32_16x16x32_bf16 v[18:21], v[106:109], v[228:231], 0
	v_mfma_f32_16x16x32_bf16 v[6:9], v[98:101], v[236:239], 0
	v_mfma_f32_16x16x32_bf16 v[2:5], v[106:109], v[236:239], 0
	v_mfma_f32_16x16x32_bf16 v[34:37], v[98:101], v[212:215], 0
	v_mfma_f32_16x16x32_bf16 v[38:41], v[106:109], v[212:215], 0
	v_mfma_f32_16x16x32_bf16 v[42:45], v[98:101], v[220:223], 0
	v_mfma_f32_16x16x32_bf16 v[46:49], v[106:109], v[220:223], 0
	v_mfma_f32_16x16x32_bf16 v[22:25], v[102:105], v[232:235], v[22:25]
	v_mfma_f32_16x16x32_bf16 v[18:21], v[110:113], v[232:235], v[18:21]
	v_mfma_f32_16x16x32_bf16 v[6:9], v[102:105], v[240:243], v[6:9]
	v_mfma_f32_16x16x32_bf16 v[2:5], v[110:113], v[240:243], v[2:5]
	v_mfma_f32_16x16x32_bf16 v[34:37], v[102:105], v[216:219], v[34:37]
	v_mfma_f32_16x16x32_bf16 v[38:41], v[110:113], v[216:219], v[38:41]
	v_mfma_f32_16x16x32_bf16 v[42:45], v[102:105], v[224:227], v[42:45]
	v_mfma_f32_16x16x32_bf16 v[46:49], v[110:113], v[224:227], v[46:49]
	s_barrier
; #define PG8_STAGE(bufoff, gbase, voff) do { _Pragma("unroll") for (int _i = 0; _i < 2; ++_i) \
;         __builtin_amdgcn_global_load_lds((const unsigned*)((const char*)(gbase) + (voff)[_i]), (LAS unsigned*)(lds + (bufoff) + ldsw + _i * 8192), 16, 0, 0); } while (0)
; #define PG8_LDA(dst, b, h) do { _Pragma("unroll") for (int m = 0; m < 4; ++m) _Pragma("unroll") for (int k = 0; k < 2; ++k) dst[m][k] = *(const LAS bf16x8*)(lds + PG8_SA(b, h) + aoff + m * 2048 + k * 1024); } while (0)
; #define PG8_LDB(dst, b, h) do { _Pragma("unroll") for (int n = 0; n < 2; ++n) _Pragma("unroll") for (int k = 0; k < 2; ++k) dst[n][k] = *(const LAS bf16x8*)(lds + PG8_SB(b, h) + boff + n * 2048 + k * 1024); } while (0)
; #define PG8_MMA(ai, bj, At, Bt) do { __builtin_amdgcn_s_setprio(1); _Pragma("unroll") for (int m = 0; m < 4; ++m) _Pragma("unroll") for (int n = 0; n < 2; ++n) _Pragma("unroll") for (int k = 0; k < 2; ++k) \
;         acc[ai][bj][m][n] = __builtin_amdgcn_mfma_f32_16x16x32_bf16(Bt[n][k], At[m][k], acc[ai][bj][m][n], 0, 0, 0); __builtin_amdgcn_s_setprio(0); } while (0)
; #define PG8_WAIT_V(n) asm volatile("s_waitcnt vmcnt(" #n ")" ::: "memory")
; #define PG8_WAIT_L(n) asm volatile("s_waitcnt lgkmcnt(" #n ")" ::: "memory")
; #define PG8_BAR __builtin_amdgcn_s_barrier()
; #define PG8_SCHED __builtin_amdgcn_sched_barrier(0)
; template <class Epi, class Sched, bool ALIGN_EPI = false, bool SP2 = false>
; __device__ __forceinline__ void gemm_phase(LAS unsigned char* lds, const Gemm g, const Sched& S, const Epi& E) {
;     ...
;             PG8_LDB(B0, 1, 0); PG8_LDB(B1, 1, 1); PG8_SCHED; PG8_LDA(At, 1, 0); PG8_STAGE(PG8_SA(0, 1), a2 + hstep, voffA);
;             PG8_WAIT_V(8); PG8_WAIT_L(0); PG8_BAR; PG8_MMA(0, 0, At, B0); PG8_MMA(0, 1, At, B1); PG8_BAR; PG8_SCHED;
;             PG8_LDA(At, 1, 1); PG8_STAGE(PG8_SB(1, 0), b3, voffB); PG8_STAGE(PG8_SB(1, 1), b3 + hstepB, voffB); PG8_STAGE(PG8_SA(1, 0), a3, voffA);
;             PG8_WAIT_V(8); PG8_WAIT_L(0); PG8_BAR; PG8_MMA(1, 0, At, B0); PG8_MMA(1, 1, At, B1); PG8_BAR; PG8_SCHED;
	s_add_i32 s21, 0, 0x18000
	s_add_i32 s24, 0, 0x1c000
	v_add_u32_e32 v70, s21, v186
	v_add_u32_e32 v110, s24, v186
	ds_read_b128 v[50:53], v70
	ds_read_b128 v[54:57], v70 offset:1024
	ds_read_b128 v[66:69], v70 offset:2048
	ds_read_b128 v[70:73], v70 offset:3072
	ds_read_b128 v[98:101], v110
	ds_read_b128 v[102:105], v110 offset:1024
	ds_read_b128 v[106:109], v110 offset:2048
	ds_read_b128 v[110:113], v110 offset:3072
	s_add_u32 s22, s58, 0x80000
	s_addc_u32 s23, s59, 0
	s_mov_b32 m0, s33
	ds_read_b128 v[212:215], v205 offset:32768
	ds_read_b128 v[216:219], v205 offset:33792
	ds_read_b128 v[220:223], v205 offset:34816
	ds_read_b128 v[224:227], v205 offset:35840
	ds_read_b128 v[228:231], v205 offset:36864
	ds_read_b128 v[232:235], v205 offset:37888
	ds_read_b128 v[236:239], v205 offset:38912
	ds_read_b128 v[240:243], v205 offset:39936
	global_load_lds_dwordx4 v162, s[22:23]
	s_mov_b32 m0, s60
	s_nop 0
	global_load_lds_dwordx4 v166, s[22:23]
	s_waitcnt vmcnt(8)
	s_waitcnt lgkmcnt(0)
	s_barrier
	s_waitcnt lgkmcnt(0)
	v_mfma_f32_16x16x32_bf16 v[158:161], v[50:53], v[212:215], v[158:161]
	v_mfma_f32_16x16x32_bf16 v[154:157], v[66:69], v[212:215], v[154:157]
	v_mfma_f32_16x16x32_bf16 v[142:145], v[50:53], v[220:223], v[142:145]
	v_mfma_f32_16x16x32_bf16 v[138:141], v[66:69], v[220:223], v[138:141]
	v_mfma_f32_16x16x32_bf16 v[126:129], v[50:53], v[228:231], v[126:129]
	v_mfma_f32_16x16x32_bf16 v[122:125], v[66:69], v[228:231], v[122:125]
	v_mfma_f32_16x16x32_bf16 v[94:97], v[50:53], v[236:239], v[94:97]
	v_mfma_f32_16x16x32_bf16 v[90:93], v[66:69], v[236:239], v[90:93]
	v_mfma_f32_16x16x32_bf16 v[158:161], v[54:57], v[216:219], v[158:161]
	v_mfma_f32_16x16x32_bf16 v[154:157], v[70:73], v[216:219], v[154:157]
	v_mfma_f32_16x16x32_bf16 v[142:145], v[54:57], v[224:227], v[142:145]
	v_mfma_f32_16x16x32_bf16 v[138:141], v[70:73], v[224:227], v[138:141]
	v_mfma_f32_16x16x32_bf16 v[126:129], v[54:57], v[232:235], v[126:129]
	v_mfma_f32_16x16x32_bf16 v[122:125], v[70:73], v[232:235], v[122:125]
	v_mfma_f32_16x16x32_bf16 v[94:97], v[54:57], v[240:243], v[94:97]
	v_mfma_f32_16x16x32_bf16 v[90:93], v[70:73], v[240:243], v[90:93]
	v_mfma_f32_16x16x32_bf16 v[150:153], v[98:101], v[212:215], v[150:153]
	v_mfma_f32_16x16x32_bf16 v[146:149], v[106:109], v[212:215], v[146:149]
	v_mfma_f32_16x16x32_bf16 v[134:137], v[98:101], v[220:223], v[134:137]
	v_mfma_f32_16x16x32_bf16 v[130:133], v[106:109], v[220:223], v[130:133]
	v_mfma_f32_16x16x32_bf16 v[118:121], v[98:101], v[228:231], v[118:121]
	v_mfma_f32_16x16x32_bf16 v[114:117], v[106:109], v[228:231], v[114:117]
	v_mfma_f32_16x16x32_bf16 v[86:89], v[98:101], v[236:239], v[86:89]
	v_mfma_f32_16x16x32_bf16 v[82:85], v[106:109], v[236:239], v[82:85]
	v_mfma_f32_16x16x32_bf16 v[150:153], v[102:105], v[216:219], v[150:153]
	v_mfma_f32_16x16x32_bf16 v[146:149], v[110:113], v[216:219], v[146:149]
	v_mfma_f32_16x16x32_bf16 v[134:137], v[102:105], v[224:227], v[134:137]
	v_mfma_f32_16x16x32_bf16 v[130:133], v[110:113], v[224:227], v[130:133]
	v_mfma_f32_16x16x32_bf16 v[118:121], v[102:105], v[232:235], v[118:121]
	v_mfma_f32_16x16x32_bf16 v[114:117], v[110:113], v[232:235], v[114:117]
	v_mfma_f32_16x16x32_bf16 v[86:89], v[102:105], v[240:243], v[86:89]
	v_mfma_f32_16x16x32_bf16 v[82:85], v[110:113], v[240:243], v[82:85]
	s_barrier
	s_add_u32 s98, s48, 0x80
	s_addc_u32 s99, s49, 0
	s_add_u32 s100, s58, 0x80
	s_addc_u32 s101, s59, 0
	s_add_i32 s21, s21, s29
	s_mov_b32 m0, s21
	ds_read_b128 v[212:215], v205 offset:49152
	ds_read_b128 v[216:219], v205 offset:50176
	ds_read_b128 v[220:223], v205 offset:51200
	ds_read_b128 v[224:227], v205 offset:52224
	ds_read_b128 v[228:231], v205 offset:53248
	ds_read_b128 v[232:235], v205 offset:54272
	ds_read_b128 v[236:239], v205 offset:55296
	ds_read_b128 v[240:243], v205 offset:56320
	global_load_lds_dwordx4 v164, s[98:99]
	s_add_i32 m0, s21, 0x2000
	s_add_u32 s22, s48, 0x20080
	s_addc_u32 s23, s49, 0
	s_add_i32 s21, s24, s29
	global_load_lds_dwordx4 v168, s[98:99]
	s_mov_b32 m0, s21
	s_nop 0
	global_load_lds_dwordx4 v164, s[22:23]
	s_add_i32 m0, s21, 0x2000
	s_nop 0
	global_load_lds_dwordx4 v168, s[22:23]
	s_mov_b32 m0, s65
	s_nop 0
	global_load_lds_dwordx4 v162, s[100:101]
	s_mov_b32 m0, s66
	s_nop 0
	global_load_lds_dwordx4 v166, s[100:101]
	s_waitcnt vmcnt(8)
	s_waitcnt lgkmcnt(0)
	s_barrier
	s_waitcnt lgkmcnt(0)
	v_mfma_f32_16x16x32_bf16 v[78:81], v[50:53], v[212:215], v[78:81]
	v_mfma_f32_16x16x32_bf16 v[74:77], v[66:69], v[212:215], v[74:77]
	v_mfma_f32_16x16x32_bf16 v[62:65], v[50:53], v[220:223], v[62:65]
	v_mfma_f32_16x16x32_bf16 v[58:61], v[66:69], v[220:223], v[58:61]
	v_mfma_f32_16x16x32_bf16 v[30:33], v[50:53], v[228:231], v[30:33]
	v_mfma_f32_16x16x32_bf16 v[26:29], v[66:69], v[228:231], v[26:29]
	v_mfma_f32_16x16x32_bf16 v[14:17], v[50:53], v[236:239], v[14:17]
	v_mfma_f32_16x16x32_bf16 v[10:13], v[66:69], v[236:239], v[10:13]
	v_mfma_f32_16x16x32_bf16 v[78:81], v[54:57], v[216:219], v[78:81]
	v_mfma_f32_16x16x32_bf16 v[74:77], v[70:73], v[216:219], v[74:77]
	v_mfma_f32_16x16x32_bf16 v[62:65], v[54:57], v[224:227], v[62:65]
	v_mfma_f32_16x16x32_bf16 v[58:61], v[70:73], v[224:227], v[58:61]
	v_mfma_f32_16x16x32_bf16 v[30:33], v[54:57], v[232:235], v[30:33]
	v_mfma_f32_16x16x32_bf16 v[26:29], v[70:73], v[232:235], v[26:29]
	v_mfma_f32_16x16x32_bf16 v[14:17], v[54:57], v[240:243], v[14:17]
	v_mfma_f32_16x16x32_bf16 v[10:13], v[70:73], v[240:243], v[10:13]
	v_mfma_f32_16x16x32_bf16 v[34:37], v[98:101], v[212:215], v[34:37]
	v_mfma_f32_16x16x32_bf16 v[70:73], v[102:105], v[216:219], v[34:37]
	v_mfma_f32_16x16x32_bf16 v[34:37], v[106:109], v[212:215], v[38:41]
	v_mfma_f32_16x16x32_bf16 v[66:69], v[110:113], v[216:219], v[34:37]
	v_mfma_f32_16x16x32_bf16 v[34:37], v[98:101], v[220:223], v[42:45]
	v_mfma_f32_16x16x32_bf16 v[54:57], v[102:105], v[224:227], v[34:37]
	v_mfma_f32_16x16x32_bf16 v[34:37], v[106:109], v[220:223], v[46:49]
	v_mfma_f32_16x16x32_bf16 v[22:25], v[98:101], v[228:231], v[22:25]
	v_mfma_f32_16x16x32_bf16 v[18:21], v[106:109], v[228:231], v[18:21]
	v_mfma_f32_16x16x32_bf16 v[6:9], v[98:101], v[236:239], v[6:9]
	v_mfma_f32_16x16x32_bf16 v[2:5], v[106:109], v[236:239], v[2:5]
	v_mfma_f32_16x16x32_bf16 v[50:53], v[110:113], v[224:227], v[34:37]
	v_mfma_f32_16x16x32_bf16 v[22:25], v[102:105], v[232:235], v[22:25]
	v_mfma_f32_16x16x32_bf16 v[18:21], v[110:113], v[232:235], v[18:21]
	v_mfma_f32_16x16x32_bf16 v[6:9], v[102:105], v[240:243], v[6:9]
	v_mfma_f32_16x16x32_bf16 v[2:5], v[110:113], v[240:243], v[2:5]
	s_barrier
	s_add_i32 s20, s20, 2
	s_add_u32 s16, s16, 0x100
	s_addc_u32 s17, s17, 0
	s_add_u32 s18, s18, 0x100
	s_addc_u32 s19, s19, 0
	s_cmp_gt_u32 s20, 29
; #define PG8_STAGE(bufoff, gbase, voff) do { _Pragma("unroll") for (int _i = 0; _i < 2; ++_i) \
;         __builtin_amdgcn_global_load_lds((const unsigned*)((const char*)(gbase) + (voff)[_i]), (LAS unsigned*)(lds + (bufoff) + ldsw + _i * 8192), 16, 0, 0); } while (0)
; #define PG8_LDA(dst, b, h) do { _Pragma("unroll") for (int m = 0; m < 4; ++m) _Pragma("unroll") for (int k = 0; k < 2; ++k) dst[m][k] = *(const LAS bf16x8*)(lds + PG8_SA(b, h) + aoff + m * 2048 + k * 1024); } while (0)
; #define PG8_LDB(dst, b, h) do { _Pragma("unroll") for (int n = 0; n < 2; ++n) _Pragma("unroll") for (int k = 0; k < 2; ++k) dst[n][k] = *(const LAS bf16x8*)(lds + PG8_SB(b, h) + boff + n * 2048 + k * 1024); } while (0)
; #define PG8_MMA(ai, bj, At, Bt) do { __builtin_amdgcn_s_setprio(1); _Pragma("unroll") for (int m = 0; m < 4; ++m) _Pragma("unroll") for (int n = 0; n < 2; ++n) _Pragma("unroll") for (int k = 0; k < 2; ++k) \
;         acc[ai][bj][m][n] = __builtin_amdgcn_mfma_f32_16x16x32_bf16(Bt[n][k], At[m][k], acc[ai][bj][m][n], 0, 0, 0); __builtin_amdgcn_s_setprio(0); } while (0)
; #define PG8_WAIT_V(n) asm volatile("s_waitcnt vmcnt(" #n ")" ::: "memory")
; #define PG8_WAIT_L(n) asm volatile("s_waitcnt lgkmcnt(" #n ")" ::: "memory")
; #define PG8_BAR __builtin_amdgcn_s_barrier()
; template <class Epi, class Sched, bool ALIGN_EPI = false, bool SP2 = false>
; __device__ __forceinline__ void gemm_phase(LAS unsigned char* lds, const Gemm g, const Sched& S, const Epi& E) {
;     ...
;             const bool last = (t == nt - 2);
;             const char* a1 = cA + (size_t)(t + 1) * kstep;
;             const char* a2 = last ? nA : cA + (size_t)(t + 2) * kstep; const char* b2 = last ? nB : cB + (size_t)(t + 2) * kstep;
;             const char* a3 = a2 + kstep; const char* b3 = b2 + kstep;
;             if (last && has_next) S.a_ready(nxt);
;             if constexpr (SP2) {
;             PG8_LDB(B0, 0, 0); PG8_LDB(B1, 0, 1); PG8_SCHED; PG8_LDA(At, 0, 0); PG8_STAGE(PG8_SA(1, 1), a1 + hstep, voffA);
;             PG8_WAIT_V(8); PG8_WAIT_L(0); PG8_BAR; PG8_MMA(0, 0, At, B0); PG8_MMA(0, 1, At, B1); PG8_BAR; PG8_SCHED;
;             PG8_LDA(At, 0, 1); PG8_STAGE(PG8_SB(0, 0), b2, voffB); PG8_STAGE(PG8_SB(0, 1), b2 + hstepB, voffB); PG8_STAGE(PG8_SA(0, 0), a2, voffA);
;             PG8_WAIT_V(8); PG8_WAIT_L(0); PG8_BAR; PG8_MMA(1, 0, At, B0); PG8_MMA(1, 1, At, B1); PG8_BAR; PG8_SCHED;
.LBB0_535:
	ds_read_b128 v[34:37], v203
	ds_read_b128 v[38:41], v203 offset:1024
	ds_read_b128 v[42:45], v203 offset:2048
	ds_read_b128 v[46:49], v203 offset:3072
	s_waitcnt vmcnt(0)
	ds_read_b128 v[98:101], v204
	ds_read_b128 v[102:105], v204 offset:1024
	ds_read_b128 v[106:109], v204 offset:2048
	ds_read_b128 v[110:113], v204 offset:3072
	s_add_u32 s21, s16, 0xfff80080
	s_addc_u32 s22, s17, -1
	s_cmp_eq_u32 s20, 28
	s_cselect_b32 s59, s0, s22
	s_cselect_b32 s58, s3, s21
	s_cselect_b32 s49, s14, s19
	s_cselect_b32 s48, s15, s18
	s_add_i32 m0, s30, 0xc000
	ds_read_b128 v[212:215], v205
	ds_read_b128 v[216:219], v205 offset:1024
	ds_read_b128 v[220:223], v205 offset:2048
	ds_read_b128 v[224:227], v205 offset:3072
	ds_read_b128 v[228:231], v205 offset:4096
	ds_read_b128 v[232:235], v205 offset:5120
	ds_read_b128 v[236:239], v205 offset:6144
	ds_read_b128 v[240:243], v205 offset:7168
	global_load_lds_dwordx4 v172, s[16:17]
	s_add_i32 m0, s30, 0xe000
	s_nop 0
	global_load_lds_dwordx4 v174, s[16:17]
	s_waitcnt vmcnt(8)
	s_waitcnt lgkmcnt(0)
	s_barrier
	s_waitcnt lgkmcnt(0)
	v_mfma_f32_16x16x32_bf16 v[158:161], v[34:37], v[212:215], v[158:161]
	v_mfma_f32_16x16x32_bf16 v[154:157], v[42:45], v[212:215], v[154:157]
	v_mfma_f32_16x16x32_bf16 v[142:145], v[34:37], v[220:223], v[142:145]
	v_mfma_f32_16x16x32_bf16 v[138:141], v[42:45], v[220:223], v[138:141]
	v_mfma_f32_16x16x32_bf16 v[126:129], v[34:37], v[228:231], v[126:129]
	v_mfma_f32_16x16x32_bf16 v[122:125], v[42:45], v[228:231], v[122:125]
	v_mfma_f32_16x16x32_bf16 v[94:97], v[34:37], v[236:239], v[94:97]
	v_mfma_f32_16x16x32_bf16 v[90:93], v[42:45], v[236:239], v[90:93]
	v_mfma_f32_16x16x32_bf16 v[158:161], v[38:41], v[216:219], v[158:161]
	v_mfma_f32_16x16x32_bf16 v[154:157], v[46:49], v[216:219], v[154:157]
	v_mfma_f32_16x16x32_bf16 v[142:145], v[38:41], v[224:227], v[142:145]
	v_mfma_f32_16x16x32_bf16 v[138:141], v[46:49], v[224:227], v[138:141]
	v_mfma_f32_16x16x32_bf16 v[126:129], v[38:41], v[232:235], v[126:129]
	v_mfma_f32_16x16x32_bf16 v[122:125], v[46:49], v[232:235], v[122:125]
	v_mfma_f32_16x16x32_bf16 v[94:97], v[38:41], v[240:243], v[94:97]
	v_mfma_f32_16x16x32_bf16 v[90:93], v[46:49], v[240:243], v[90:93]
	v_mfma_f32_16x16x32_bf16 v[150:153], v[98:101], v[212:215], v[150:153]
	v_mfma_f32_16x16x32_bf16 v[146:149], v[106:109], v[212:215], v[146:149]
	v_mfma_f32_16x16x32_bf16 v[134:137], v[98:101], v[220:223], v[134:137]
	v_mfma_f32_16x16x32_bf16 v[130:133], v[106:109], v[220:223], v[130:133]
	v_mfma_f32_16x16x32_bf16 v[118:121], v[98:101], v[228:231], v[118:121]
	v_mfma_f32_16x16x32_bf16 v[114:117], v[106:109], v[228:231], v[114:117]
	v_mfma_f32_16x16x32_bf16 v[86:89], v[98:101], v[236:239], v[86:89]
	v_mfma_f32_16x16x32_bf16 v[82:85], v[106:109], v[236:239], v[82:85]
	v_mfma_f32_16x16x32_bf16 v[150:153], v[102:105], v[216:219], v[150:153]
	v_mfma_f32_16x16x32_bf16 v[146:149], v[110:113], v[216:219], v[146:149]
	v_mfma_f32_16x16x32_bf16 v[134:137], v[102:105], v[224:227], v[134:137]
	v_mfma_f32_16x16x32_bf16 v[130:133], v[110:113], v[224:227], v[130:133]
	v_mfma_f32_16x16x32_bf16 v[118:121], v[102:105], v[232:235], v[118:121]
	v_mfma_f32_16x16x32_bf16 v[114:117], v[110:113], v[232:235], v[114:117]
	v_mfma_f32_16x16x32_bf16 v[86:89], v[102:105], v[240:243], v[86:89]
	v_mfma_f32_16x16x32_bf16 v[82:85], v[110:113], v[240:243], v[82:85]
	s_barrier
	s_add_i32 s21, s68, s29
	s_mov_b32 m0, s21
	ds_read_b128 v[212:215], v205 offset:16384
	ds_read_b128 v[216:219], v205 offset:17408
	ds_read_b128 v[220:223], v205 offset:18432
	ds_read_b128 v[224:227], v205 offset:19456
	ds_read_b128 v[228:231], v205 offset:20480
	ds_read_b128 v[232:235], v205 offset:21504
	ds_read_b128 v[236:239], v205 offset:22528
	ds_read_b128 v[240:243], v205 offset:23552
	global_load_lds_dwordx4 v164, s[48:49]
	s_add_i32 m0, s21, 0x2000
	s_add_u32 s22, s48, 0x20000
	s_addc_u32 s23, s49, 0
	s_add_i32 s21, s69, s29
	global_load_lds_dwordx4 v168, s[48:49]
	s_mov_b32 m0, s21
	s_nop 0
	global_load_lds_dwordx4 v164, s[22:23]
	s_add_i32 m0, s21, 0x2000
	s_nop 0
	global_load_lds_dwordx4 v168, s[22:23]
	s_mov_b32 m0, s30
	s_nop 0
	global_load_lds_dwordx4 v162, s[58:59]
	s_mov_b32 m0, s31
	s_nop 0
	global_load_lds_dwordx4 v166, s[58:59]
	s_waitcnt vmcnt(8)
	s_waitcnt lgkmcnt(0)
	s_barrier
	s_waitcnt lgkmcnt(0)
	v_mfma_f32_16x16x32_bf16 v[78:81], v[34:37], v[212:215], v[78:81]
	v_mfma_f32_16x16x32_bf16 v[74:77], v[42:45], v[212:215], v[74:77]
	v_mfma_f32_16x16x32_bf16 v[62:65], v[34:37], v[220:223], v[62:65]
	v_mfma_f32_16x16x32_bf16 v[58:61], v[42:45], v[220:223], v[58:61]
	v_mfma_f32_16x16x32_bf16 v[30:33], v[34:37], v[228:231], v[30:33]
	v_mfma_f32_16x16x32_bf16 v[26:29], v[42:45], v[228:231], v[26:29]
	v_mfma_f32_16x16x32_bf16 v[14:17], v[34:37], v[236:239], v[14:17]
	v_mfma_f32_16x16x32_bf16 v[10:13], v[42:45], v[236:239], v[10:13]
	v_mfma_f32_16x16x32_bf16 v[78:81], v[38:41], v[216:219], v[78:81]
	v_mfma_f32_16x16x32_bf16 v[74:77], v[46:49], v[216:219], v[74:77]
	v_mfma_f32_16x16x32_bf16 v[62:65], v[38:41], v[224:227], v[62:65]
	v_mfma_f32_16x16x32_bf16 v[58:61], v[46:49], v[224:227], v[58:61]
	v_mfma_f32_16x16x32_bf16 v[30:33], v[38:41], v[232:235], v[30:33]
	v_mfma_f32_16x16x32_bf16 v[26:29], v[46:49], v[232:235], v[26:29]
	v_mfma_f32_16x16x32_bf16 v[14:17], v[38:41], v[240:243], v[14:17]
	v_mfma_f32_16x16x32_bf16 v[10:13], v[46:49], v[240:243], v[10:13]
	v_mfma_f32_16x16x32_bf16 v[22:25], v[98:101], v[228:231], v[22:25]
	v_mfma_f32_16x16x32_bf16 v[18:21], v[106:109], v[228:231], v[18:21]
	v_mfma_f32_16x16x32_bf16 v[6:9], v[98:101], v[236:239], v[6:9]
	v_mfma_f32_16x16x32_bf16 v[2:5], v[106:109], v[236:239], v[2:5]
	v_mfma_f32_16x16x32_bf16 v[34:37], v[98:101], v[212:215], v[70:73]
	v_mfma_f32_16x16x32_bf16 v[38:41], v[106:109], v[212:215], v[66:69]
	v_mfma_f32_16x16x32_bf16 v[42:45], v[98:101], v[220:223], v[54:57]
	v_mfma_f32_16x16x32_bf16 v[46:49], v[106:109], v[220:223], v[50:53]
	v_mfma_f32_16x16x32_bf16 v[22:25], v[102:105], v[232:235], v[22:25]
	v_mfma_f32_16x16x32_bf16 v[18:21], v[110:113], v[232:235], v[18:21]
	v_mfma_f32_16x16x32_bf16 v[6:9], v[102:105], v[240:243], v[6:9]
	v_mfma_f32_16x16x32_bf16 v[2:5], v[110:113], v[240:243], v[2:5]
	v_mfma_f32_16x16x32_bf16 v[34:37], v[102:105], v[216:219], v[34:37]
	v_mfma_f32_16x16x32_bf16 v[38:41], v[110:113], v[216:219], v[38:41]
	v_mfma_f32_16x16x32_bf16 v[42:45], v[102:105], v[224:227], v[42:45]
	v_mfma_f32_16x16x32_bf16 v[46:49], v[110:113], v[224:227], v[46:49]
	s_barrier
; #define PG8_STAGE(bufoff, gbase, voff) do { _Pragma("unroll") for (int _i = 0; _i < 2; ++_i) \
;         __builtin_amdgcn_global_load_lds((const unsigned*)((const char*)(gbase) + (voff)[_i]), (LAS unsigned*)(lds + (bufoff) + ldsw + _i * 8192), 16, 0, 0); } while (0)
; #define PG8_LDA(dst, b, h) do { _Pragma("unroll") for (int m = 0; m < 4; ++m) _Pragma("unroll") for (int k = 0; k < 2; ++k) dst[m][k] = *(const LAS bf16x8*)(lds + PG8_SA(b, h) + aoff + m * 2048 + k * 1024); } while (0)
; #define PG8_LDB(dst, b, h) do { _Pragma("unroll") for (int n = 0; n < 2; ++n) _Pragma("unroll") for (int k = 0; k < 2; ++k) dst[n][k] = *(const LAS bf16x8*)(lds + PG8_SB(b, h) + boff + n * 2048 + k * 1024); } while (0)
; #define PG8_MMA(ai, bj, At, Bt) do { __builtin_amdgcn_s_setprio(1); _Pragma("unroll") for (int m = 0; m < 4; ++m) _Pragma("unroll") for (int n = 0; n < 2; ++n) _Pragma("unroll") for (int k = 0; k < 2; ++k) \
;         acc[ai][bj][m][n] = __builtin_amdgcn_mfma_f32_16x16x32_bf16(Bt[n][k], At[m][k], acc[ai][bj][m][n], 0, 0, 0); __builtin_amdgcn_s_setprio(0); } while (0)
; #define PG8_WAIT_V(n) asm volatile("s_waitcnt vmcnt(" #n ")" ::: "memory")
; #define PG8_WAIT_L(n) asm volatile("s_waitcnt lgkmcnt(" #n ")" ::: "memory")
; #define PG8_BAR __builtin_amdgcn_s_barrier()
; #define PG8_SCHED __builtin_amdgcn_sched_barrier(0)
; template <class Epi, class Sched, bool ALIGN_EPI = false, bool SP2 = false>
; __device__ __forceinline__ void gemm_phase(LAS unsigned char* lds, const Gemm g, const Sched& S, const Epi& E) {
;     ...
;             PG8_LDB(B0, 1, 0); PG8_LDB(B1, 1, 1); PG8_SCHED; PG8_LDA(At, 1, 0); PG8_STAGE(PG8_SA(0, 1), a2 + hstep, voffA);
;             PG8_WAIT_V(8); PG8_WAIT_L(0); PG8_BAR; PG8_MMA(0, 0, At, B0); PG8_MMA(0, 1, At, B1); PG8_BAR; PG8_SCHED;
;             PG8_LDA(At, 1, 1); PG8_STAGE(PG8_SB(1, 0), b3, voffB); PG8_STAGE(PG8_SB(1, 1), b3 + hstepB, voffB); PG8_STAGE(PG8_SA(1, 0), a3, voffA);
;             PG8_WAIT_V(8); PG8_WAIT_L(0); PG8_BAR; PG8_MMA(1, 0, At, B0); PG8_MMA(1, 1, At, B1); PG8_BAR; PG8_SCHED;
	s_add_i32 s21, 0, 0x18000
	s_add_i32 s24, 0, 0x1c000
	v_add_u32_e32 v70, s21, v186
	v_add_u32_e32 v110, s24, v186
	ds_read_b128 v[50:53], v70
	ds_read_b128 v[54:57], v70 offset:1024
	ds_read_b128 v[66:69], v70 offset:2048
	ds_read_b128 v[70:73], v70 offset:3072
	ds_read_b128 v[98:101], v110
	ds_read_b128 v[102:105], v110 offset:1024
	ds_read_b128 v[106:109], v110 offset:2048
	ds_read_b128 v[110:113], v110 offset:3072
	s_add_u32 s22, s58, 0x80000
	s_addc_u32 s23, s59, 0
	s_mov_b32 m0, s33
	ds_read_b128 v[212:215], v205 offset:32768
	ds_read_b128 v[216:219], v205 offset:33792
	ds_read_b128 v[220:223], v205 offset:34816
	ds_read_b128 v[224:227], v205 offset:35840
	ds_read_b128 v[228:231], v205 offset:36864
	ds_read_b128 v[232:235], v205 offset:37888
	ds_read_b128 v[236:239], v205 offset:38912
	ds_read_b128 v[240:243], v205 offset:39936
	global_load_lds_dwordx4 v162, s[22:23]
	s_mov_b32 m0, s60
	s_nop 0
	global_load_lds_dwordx4 v166, s[22:23]
	s_waitcnt vmcnt(8)
	s_waitcnt lgkmcnt(0)
	s_barrier
	s_waitcnt lgkmcnt(0)
	v_mfma_f32_16x16x32_bf16 v[158:161], v[50:53], v[212:215], v[158:161]
	v_mfma_f32_16x16x32_bf16 v[154:157], v[66:69], v[212:215], v[154:157]
	v_mfma_f32_16x16x32_bf16 v[142:145], v[50:53], v[220:223], v[142:145]
	v_mfma_f32_16x16x32_bf16 v[138:141], v[66:69], v[220:223], v[138:141]
	v_mfma_f32_16x16x32_bf16 v[126:129], v[50:53], v[228:231], v[126:129]
	v_mfma_f32_16x16x32_bf16 v[122:125], v[66:69], v[228:231], v[122:125]
	v_mfma_f32_16x16x32_bf16 v[94:97], v[50:53], v[236:239], v[94:97]
	v_mfma_f32_16x16x32_bf16 v[90:93], v[66:69], v[236:239], v[90:93]
	v_mfma_f32_16x16x32_bf16 v[158:161], v[54:57], v[216:219], v[158:161]
	v_mfma_f32_16x16x32_bf16 v[154:157], v[70:73], v[216:219], v[154:157]
	v_mfma_f32_16x16x32_bf16 v[142:145], v[54:57], v[224:227], v[142:145]
	v_mfma_f32_16x16x32_bf16 v[138:141], v[70:73], v[224:227], v[138:141]
	v_mfma_f32_16x16x32_bf16 v[126:129], v[54:57], v[232:235], v[126:129]
	v_mfma_f32_16x16x32_bf16 v[122:125], v[70:73], v[232:235], v[122:125]
	v_mfma_f32_16x16x32_bf16 v[94:97], v[54:57], v[240:243], v[94:97]
	v_mfma_f32_16x16x32_bf16 v[90:93], v[70:73], v[240:243], v[90:93]
	v_mfma_f32_16x16x32_bf16 v[150:153], v[98:101], v[212:215], v[150:153]
	v_mfma_f32_16x16x32_bf16 v[146:149], v[106:109], v[212:215], v[146:149]
	v_mfma_f32_16x16x32_bf16 v[134:137], v[98:101], v[220:223], v[134:137]
	v_mfma_f32_16x16x32_bf16 v[130:133], v[106:109], v[220:223], v[130:133]
	v_mfma_f32_16x16x32_bf16 v[118:121], v[98:101], v[228:231], v[118:121]
	v_mfma_f32_16x16x32_bf16 v[114:117], v[106:109], v[228:231], v[114:117]
	v_mfma_f32_16x16x32_bf16 v[86:89], v[98:101], v[236:239], v[86:89]
	v_mfma_f32_16x16x32_bf16 v[82:85], v[106:109], v[236:239], v[82:85]
	v_mfma_f32_16x16x32_bf16 v[150:153], v[102:105], v[216:219], v[150:153]
	v_mfma_f32_16x16x32_bf16 v[146:149], v[110:113], v[216:219], v[146:149]
	v_mfma_f32_16x16x32_bf16 v[134:137], v[102:105], v[224:227], v[134:137]
	v_mfma_f32_16x16x32_bf16 v[130:133], v[110:113], v[224:227], v[130:133]
	v_mfma_f32_16x16x32_bf16 v[118:121], v[102:105], v[232:235], v[118:121]
	v_mfma_f32_16x16x32_bf16 v[114:117], v[110:113], v[232:235], v[114:117]
	v_mfma_f32_16x16x32_bf16 v[86:89], v[102:105], v[240:243], v[86:89]
	v_mfma_f32_16x16x32_bf16 v[82:85], v[110:113], v[240:243], v[82:85]
	s_barrier
	s_add_u32 s98, s48, 0x80
	s_addc_u32 s99, s49, 0
	s_add_u32 s100, s58, 0x80
	s_addc_u32 s101, s59, 0
	s_add_i32 s21, s21, s29
	s_mov_b32 m0, s21
	ds_read_b128 v[212:215], v205 offset:49152
	ds_read_b128 v[216:219], v205 offset:50176
	ds_read_b128 v[220:223], v205 offset:51200
	ds_read_b128 v[224:227], v205 offset:52224
	ds_read_b128 v[228:231], v205 offset:53248
	ds_read_b128 v[232:235], v205 offset:54272
	ds_read_b128 v[236:239], v205 offset:55296
	ds_read_b128 v[240:243], v205 offset:56320
	global_load_lds_dwordx4 v164, s[98:99]
	s_add_i32 m0, s21, 0x2000
	s_add_u32 s22, s48, 0x20080
	s_addc_u32 s23, s49, 0
	s_add_i32 s21, s24, s29
	global_load_lds_dwordx4 v168, s[98:99]
	s_mov_b32 m0, s21
	s_nop 0
	global_load_lds_dwordx4 v164, s[22:23]
	s_add_i32 m0, s21, 0x2000
	s_nop 0
	global_load_lds_dwordx4 v168, s[22:23]
	s_mov_b32 m0, s65
	s_nop 0
	global_load_lds_dwordx4 v162, s[100:101]
	s_mov_b32 m0, s66
	s_nop 0
	global_load_lds_dwordx4 v166, s[100:101]
	s_waitcnt vmcnt(8)
	s_waitcnt lgkmcnt(0)
	s_barrier
	s_waitcnt lgkmcnt(0)
	v_mfma_f32_16x16x32_bf16 v[78:81], v[50:53], v[212:215], v[78:81]
	v_mfma_f32_16x16x32_bf16 v[74:77], v[66:69], v[212:215], v[74:77]
	v_mfma_f32_16x16x32_bf16 v[62:65], v[50:53], v[220:223], v[62:65]
	v_mfma_f32_16x16x32_bf16 v[58:61], v[66:69], v[220:223], v[58:61]
	v_mfma_f32_16x16x32_bf16 v[30:33], v[50:53], v[228:231], v[30:33]
	v_mfma_f32_16x16x32_bf16 v[26:29], v[66:69], v[228:231], v[26:29]
	v_mfma_f32_16x16x32_bf16 v[14:17], v[50:53], v[236:239], v[14:17]
	v_mfma_f32_16x16x32_bf16 v[10:13], v[66:69], v[236:239], v[10:13]
	v_mfma_f32_16x16x32_bf16 v[78:81], v[54:57], v[216:219], v[78:81]
	v_mfma_f32_16x16x32_bf16 v[74:77], v[70:73], v[216:219], v[74:77]
	v_mfma_f32_16x16x32_bf16 v[62:65], v[54:57], v[224:227], v[62:65]
	v_mfma_f32_16x16x32_bf16 v[58:61], v[70:73], v[224:227], v[58:61]
	v_mfma_f32_16x16x32_bf16 v[30:33], v[54:57], v[232:235], v[30:33]
	v_mfma_f32_16x16x32_bf16 v[26:29], v[70:73], v[232:235], v[26:29]
	v_mfma_f32_16x16x32_bf16 v[14:17], v[54:57], v[240:243], v[14:17]
	v_mfma_f32_16x16x32_bf16 v[10:13], v[70:73], v[240:243], v[10:13]
	v_mfma_f32_16x16x32_bf16 v[34:37], v[98:101], v[212:215], v[34:37]
	v_mfma_f32_16x16x32_bf16 v[70:73], v[102:105], v[216:219], v[34:37]
	v_mfma_f32_16x16x32_bf16 v[34:37], v[106:109], v[212:215], v[38:41]
	v_mfma_f32_16x16x32_bf16 v[66:69], v[110:113], v[216:219], v[34:37]
	v_mfma_f32_16x16x32_bf16 v[34:37], v[98:101], v[220:223], v[42:45]
	v_mfma_f32_16x16x32_bf16 v[54:57], v[102:105], v[224:227], v[34:37]
	v_mfma_f32_16x16x32_bf16 v[34:37], v[106:109], v[220:223], v[46:49]
	v_mfma_f32_16x16x32_bf16 v[22:25], v[98:101], v[228:231], v[22:25]
	v_mfma_f32_16x16x32_bf16 v[18:21], v[106:109], v[228:231], v[18:21]
	v_mfma_f32_16x16x32_bf16 v[6:9], v[98:101], v[236:239], v[6:9]
	v_mfma_f32_16x16x32_bf16 v[2:5], v[106:109], v[236:239], v[2:5]
	v_mfma_f32_16x16x32_bf16 v[50:53], v[110:113], v[224:227], v[34:37]
	v_mfma_f32_16x16x32_bf16 v[22:25], v[102:105], v[232:235], v[22:25]
	v_mfma_f32_16x16x32_bf16 v[18:21], v[110:113], v[232:235], v[18:21]
	v_mfma_f32_16x16x32_bf16 v[6:9], v[102:105], v[240:243], v[6:9]
	v_mfma_f32_16x16x32_bf16 v[2:5], v[110:113], v[240:243], v[2:5]
	s_barrier
	s_add_i32 s20, s20, 2
	s_add_u32 s16, s16, 0x100
	s_addc_u32 s17, s17, 0
	s_add_u32 s18, s18, 0x100
	s_addc_u32 s19, s19, 0
	s_cmp_gt_u32 s20, 29
	s_cbranch_scc0 .LBB0_535
	s_setprio 0
	s_and_b64 vcc, exec, s[76:77]
	s_cbranch_vccz .LBB0_538
	s_barrier

; #define PG8_STAGE(bufoff, gbase, voff) do { _Pragma("unroll") for (int _i = 0; _i < 2; ++_i) \
;         __builtin_amdgcn_global_load_lds((const unsigned*)((const char*)(gbase) + (voff)[_i]), (LAS unsigned*)(lds + (bufoff) + ldsw + _i * 8192), 16, 0, 0); } while (0)
; #define PG8_LDA(dst, b, h) do { _Pragma("unroll") for (int m = 0; m < 4; ++m) _Pragma("unroll") for (int k = 0; k < 2; ++k) dst[m][k] = *(const LAS bf16x8*)(lds + PG8_SA(b, h) + aoff + m * 2048 + k * 1024); } while (0)
; #define PG8_LDB(dst, b, h) do { _Pragma("unroll") for (int n = 0; n < 2; ++n) _Pragma("unroll") for (int k = 0; k < 2; ++k) dst[n][k] = *(const LAS bf16x8*)(lds + PG8_SB(b, h) + boff + n * 2048 + k * 1024); } while (0)
; #define PG8_MMA(ai, bj, At, Bt) do { __builtin_amdgcn_s_setprio(1); _Pragma("unroll") for (int m = 0; m < 4; ++m) _Pragma("unroll") for (int n = 0; n < 2; ++n) _Pragma("unroll") for (int k = 0; k < 2; ++k) \
;         acc[ai][bj][m][n] = __builtin_amdgcn_mfma_f32_16x16x32_bf16(Bt[n][k], At[m][k], acc[ai][bj][m][n], 0, 0, 0); __builtin_amdgcn_s_setprio(0); } while (0)
; #define PG8_WAIT_V(n) asm volatile("s_waitcnt vmcnt(" #n ")" ::: "memory")
; #define PG8_WAIT_L(n) asm volatile("s_waitcnt lgkmcnt(" #n ")" ::: "memory")
; #define PG8_BAR __builtin_amdgcn_s_barrier()
; #define PG8_SCHED __builtin_amdgcn_sched_barrier(0)
; template <class Epi, class Sched, bool ALIGN_EPI = false, bool SP2 = false>
; __device__ __forceinline__ void gemm_phase(LAS unsigned char* lds, const Gemm g, const Sched& S, const Epi& E) {
;     ...
;             PG8_LDB(B0, 0, 0); PG8_LDB(B1, 0, 1); PG8_SCHED; PG8_LDA(At, 0, 0); PG8_STAGE(PG8_SA(1, 1), a1 + hstep, voffA);
;             PG8_WAIT_V(8); PG8_WAIT_L(0); PG8_BAR; PG8_MMA(0, 0, At, B0); PG8_MMA(0, 1, At, B1); PG8_BAR; PG8_SCHED;
;             PG8_LDA(At, 0, 1); PG8_STAGE(PG8_SB(0, 0), b2, voffB); PG8_STAGE(PG8_SB(0, 1), b2 + hstepB, voffB); PG8_STAGE(PG8_SA(0, 0), a2, voffA);
;             PG8_WAIT_V(8); PG8_WAIT_L(0); PG8_BAR; PG8_MMA(1, 0, At, B0); PG8_MMA(1, 1, At, B1); PG8_BAR; PG8_SCHED;
.Lprio_1595:
	ds_read_b128 v[130:133], v196
	ds_read_b128 v[134:137], v196 offset:1024
	ds_read_b128 v[138:141], v196 offset:2048
	ds_read_b128 v[142:145], v196 offset:3072
	ds_read_b128 v[166:169], v197
	ds_read_b128 v[170:173], v197 offset:1024
	ds_read_b128 v[174:177], v197 offset:2048
	ds_read_b128 v[178:181], v197 offset:3072
	s_add_u32 s20, s16, 0x100
	s_addc_u32 s21, s17, 0
	s_cmpk_eq_i32 s25, 0x54
	s_cselect_b32 s47, s3, s21
	s_cselect_b32 s46, s2, s20
	s_cselect_b32 s23, s19, s24
	s_cselect_b32 s22, s18, s9
	v_lshl_add_u64 v[190:191], s[16:17], 0, v[158:159]
	s_add_i32 m0, s31, 0xc000
	ds_read_b128 v[182:185], v198
	ds_read_b128 v[186:189], v198 offset:1024
	ds_read_b128 v[202:205], v198 offset:2048
	ds_read_b128 v[206:209], v198 offset:3072
	ds_read_b128 v[210:213], v198 offset:4096
	ds_read_b128 v[214:217], v198 offset:5120
	ds_read_b128 v[218:221], v198 offset:6144
	ds_read_b128 v[222:225], v198 offset:7168
	global_load_lds_dwordx4 v[190:191], off
	v_lshl_add_u64 v[190:191], s[16:17], 0, v[160:161]
	s_add_i32 m0, s31, 0xe000
	s_nop 0
	global_load_lds_dwordx4 v[190:191], off
	s_waitcnt lgkmcnt(0)
	s_barrier
	s_waitcnt lgkmcnt(0)
	v_mfma_f32_16x16x32_bf16 v[126:129], v[130:133], v[182:185], 0
	v_mfma_f32_16x16x32_bf16 v[122:125], v[138:141], v[182:185], 0
	v_mfma_f32_16x16x32_bf16 v[110:113], v[130:133], v[202:205], 0
	v_mfma_f32_16x16x32_bf16 v[106:109], v[138:141], v[202:205], 0
	v_mfma_f32_16x16x32_bf16 v[94:97], v[130:133], v[210:213], 0
	v_mfma_f32_16x16x32_bf16 v[90:93], v[138:141], v[210:213], 0
	v_mfma_f32_16x16x32_bf16 v[78:81], v[130:133], v[218:221], 0
	v_mfma_f32_16x16x32_bf16 v[74:77], v[138:141], v[218:221], 0
	v_mfma_f32_16x16x32_bf16 v[126:129], v[134:137], v[186:189], v[126:129]
	v_mfma_f32_16x16x32_bf16 v[122:125], v[142:145], v[186:189], v[122:125]
	v_mfma_f32_16x16x32_bf16 v[110:113], v[134:137], v[206:209], v[110:113]
	v_mfma_f32_16x16x32_bf16 v[106:109], v[142:145], v[206:209], v[106:109]
	v_mfma_f32_16x16x32_bf16 v[94:97], v[134:137], v[214:217], v[94:97]
	v_mfma_f32_16x16x32_bf16 v[90:93], v[142:145], v[214:217], v[90:93]
	v_mfma_f32_16x16x32_bf16 v[78:81], v[134:137], v[222:225], v[78:81]
	v_mfma_f32_16x16x32_bf16 v[74:77], v[142:145], v[222:225], v[74:77]
	v_mfma_f32_16x16x32_bf16 v[118:121], v[166:169], v[182:185], 0
	v_mfma_f32_16x16x32_bf16 v[114:117], v[174:177], v[182:185], 0
	v_mfma_f32_16x16x32_bf16 v[102:105], v[166:169], v[202:205], 0
	v_mfma_f32_16x16x32_bf16 v[98:101], v[174:177], v[202:205], 0
	v_mfma_f32_16x16x32_bf16 v[86:89], v[166:169], v[210:213], 0
	v_mfma_f32_16x16x32_bf16 v[82:85], v[174:177], v[210:213], 0
	v_mfma_f32_16x16x32_bf16 v[70:73], v[166:169], v[218:221], 0
	v_mfma_f32_16x16x32_bf16 v[66:69], v[174:177], v[218:221], 0
	v_mfma_f32_16x16x32_bf16 v[118:121], v[170:173], v[186:189], v[118:121]
	v_mfma_f32_16x16x32_bf16 v[114:117], v[178:181], v[186:189], v[114:117]
	v_mfma_f32_16x16x32_bf16 v[102:105], v[170:173], v[206:209], v[102:105]
	v_mfma_f32_16x16x32_bf16 v[98:101], v[178:181], v[206:209], v[98:101]
	v_mfma_f32_16x16x32_bf16 v[86:89], v[170:173], v[214:217], v[86:89]
	v_mfma_f32_16x16x32_bf16 v[82:85], v[178:181], v[214:217], v[82:85]
	v_mfma_f32_16x16x32_bf16 v[70:73], v[170:173], v[222:225], v[70:73]
	v_mfma_f32_16x16x32_bf16 v[66:69], v[178:181], v[222:225], v[66:69]
	s_barrier
	s_add_i32 s16, s52, s30
	s_mov_b32 m0, s16
	ds_read_b128 v[182:185], v198 offset:16384
	ds_read_b128 v[186:189], v198 offset:17408
	ds_read_b128 v[202:205], v198 offset:18432
	ds_read_b128 v[206:209], v198 offset:19456
	ds_read_b128 v[210:213], v198 offset:20480
	ds_read_b128 v[214:217], v198 offset:21504
	ds_read_b128 v[218:221], v198 offset:22528
	ds_read_b128 v[222:225], v198 offset:23552
	global_load_lds_dwordx4 v148, s[22:23]
	s_add_i32 m0, s16, 0x2000
	s_add_u32 s16, s22, 0x58000
	v_lshl_add_u64 v[226:227], s[22:23], 0, v[152:153]
	s_addc_u32 s17, s23, 0
	s_add_i32 s56, s53, s30
	global_load_lds_dwordx4 v152, s[22:23]
	s_mov_b32 m0, s56
	s_nop 0
	global_load_lds_dwordx4 v148, s[16:17]
	s_add_i32 m0, s56, 0x2000
	s_nop 0
	global_load_lds_dwordx4 v152, s[16:17]
	s_mov_b32 m0, s31
	s_nop 0
	global_load_lds_dwordx4 v146, s[46:47]
	s_mov_b32 m0, s33
	s_nop 0
	global_load_lds_dwordx4 v150, s[46:47]
	s_waitcnt lgkmcnt(0)
	s_barrier
	s_waitcnt lgkmcnt(0)
	v_mfma_f32_16x16x32_bf16 v[62:65], v[130:133], v[182:185], 0
	v_mfma_f32_16x16x32_bf16 v[58:61], v[138:141], v[182:185], 0
	v_mfma_f32_16x16x32_bf16 v[46:49], v[130:133], v[202:205], 0
	v_mfma_f32_16x16x32_bf16 v[42:45], v[138:141], v[202:205], 0
	v_mfma_f32_16x16x32_bf16 v[30:33], v[130:133], v[210:213], 0
	v_mfma_f32_16x16x32_bf16 v[26:29], v[138:141], v[210:213], 0
	v_mfma_f32_16x16x32_bf16 v[14:17], v[130:133], v[218:221], 0
	v_mfma_f32_16x16x32_bf16 v[10:13], v[138:141], v[218:221], 0
	v_mfma_f32_16x16x32_bf16 v[62:65], v[134:137], v[186:189], v[62:65]
	v_mfma_f32_16x16x32_bf16 v[58:61], v[142:145], v[186:189], v[58:61]
	v_mfma_f32_16x16x32_bf16 v[46:49], v[134:137], v[206:209], v[46:49]
	v_mfma_f32_16x16x32_bf16 v[42:45], v[142:145], v[206:209], v[42:45]
	v_mfma_f32_16x16x32_bf16 v[30:33], v[134:137], v[214:217], v[30:33]
	v_mfma_f32_16x16x32_bf16 v[26:29], v[142:145], v[214:217], v[26:29]
	v_mfma_f32_16x16x32_bf16 v[14:17], v[134:137], v[222:225], v[14:17]
	v_mfma_f32_16x16x32_bf16 v[10:13], v[142:145], v[222:225], v[10:13]
	v_mfma_f32_16x16x32_bf16 v[54:57], v[166:169], v[182:185], 0
	v_mfma_f32_16x16x32_bf16 v[50:53], v[174:177], v[182:185], 0
	v_mfma_f32_16x16x32_bf16 v[38:41], v[166:169], v[202:205], 0
	v_mfma_f32_16x16x32_bf16 v[34:37], v[174:177], v[202:205], 0
	v_mfma_f32_16x16x32_bf16 v[22:25], v[166:169], v[210:213], 0
	v_mfma_f32_16x16x32_bf16 v[18:21], v[174:177], v[210:213], 0
	v_mfma_f32_16x16x32_bf16 v[6:9], v[166:169], v[218:221], 0
	v_mfma_f32_16x16x32_bf16 v[2:5], v[174:177], v[218:221], 0
	v_mfma_f32_16x16x32_bf16 v[54:57], v[170:173], v[186:189], v[54:57]
	v_mfma_f32_16x16x32_bf16 v[50:53], v[178:181], v[186:189], v[50:53]
	v_mfma_f32_16x16x32_bf16 v[38:41], v[170:173], v[206:209], v[38:41]
	v_mfma_f32_16x16x32_bf16 v[34:37], v[178:181], v[206:209], v[34:37]
	v_mfma_f32_16x16x32_bf16 v[22:25], v[170:173], v[214:217], v[22:25]
	v_mfma_f32_16x16x32_bf16 v[18:21], v[178:181], v[214:217], v[18:21]
	v_mfma_f32_16x16x32_bf16 v[6:9], v[170:173], v[222:225], v[6:9]
	v_mfma_f32_16x16x32_bf16 v[2:5], v[178:181], v[222:225], v[2:5]
	s_barrier
; #define PG8_STAGE(bufoff, gbase, voff) do { _Pragma("unroll") for (int _i = 0; _i < 2; ++_i) \
;         __builtin_amdgcn_global_load_lds((const unsigned*)((const char*)(gbase) + (voff)[_i]), (LAS unsigned*)(lds + (bufoff) + ldsw + _i * 8192), 16, 0, 0); } while (0)
; #define PG8_LDA(dst, b, h) do { _Pragma("unroll") for (int m = 0; m < 4; ++m) _Pragma("unroll") for (int k = 0; k < 2; ++k) dst[m][k] = *(const LAS bf16x8*)(lds + PG8_SA(b, h) + aoff + m * 2048 + k * 1024); } while (0)
; #define PG8_LDB(dst, b, h) do { _Pragma("unroll") for (int n = 0; n < 2; ++n) _Pragma("unroll") for (int k = 0; k < 2; ++k) dst[n][k] = *(const LAS bf16x8*)(lds + PG8_SB(b, h) + boff + n * 2048 + k * 1024); } while (0)
; #define PG8_MMA(ai, bj, At, Bt) do { __builtin_amdgcn_s_setprio(1); _Pragma("unroll") for (int m = 0; m < 4; ++m) _Pragma("unroll") for (int n = 0; n < 2; ++n) _Pragma("unroll") for (int k = 0; k < 2; ++k) \
;         acc[ai][bj][m][n] = __builtin_amdgcn_mfma_f32_16x16x32_bf16(Bt[n][k], At[m][k], acc[ai][bj][m][n], 0, 0, 0); __builtin_amdgcn_s_setprio(0); } while (0)
; #define PG8_WAIT_V(n) asm volatile("s_waitcnt vmcnt(" #n ")" ::: "memory")
; #define PG8_WAIT_L(n) asm volatile("s_waitcnt lgkmcnt(" #n ")" ::: "memory")
; #define PG8_BAR __builtin_amdgcn_s_barrier()
; #define PG8_SCHED __builtin_amdgcn_sched_barrier(0)
; template <class Epi, class Sched, bool ALIGN_EPI = false, bool SP2 = false>
; __device__ __forceinline__ void gemm_phase(LAS unsigned char* lds, const Gemm g, const Sched& S, const Epi& E) {
;     ...
;             PG8_LDB(B0, 1, 0); PG8_LDB(B1, 1, 1); PG8_SCHED; PG8_LDA(At, 1, 0); PG8_STAGE(PG8_SA(0, 1), a2 + hstep, voffA);
;             PG8_WAIT_V(8); PG8_WAIT_L(0); PG8_BAR; PG8_MMA(0, 0, At, B0); PG8_MMA(0, 1, At, B1); PG8_BAR; PG8_SCHED;
;             PG8_LDA(At, 1, 1); PG8_STAGE(PG8_SB(1, 0), b3, voffB); PG8_STAGE(PG8_SB(1, 1), b3 + hstepB, voffB); PG8_STAGE(PG8_SA(1, 0), a3, voffA);
;             PG8_WAIT_V(8); PG8_WAIT_L(0); PG8_BAR; PG8_MMA(1, 0, At, B0); PG8_MMA(1, 1, At, B1); PG8_BAR; PG8_SCHED;
	s_add_i32 s56, 0, 0x18000
	s_add_i32 s57, 0, 0x1c000
	v_add_u32_e32 v142, s56, v1
	v_add_u32_e32 v154, s57, v1
	ds_read_b128 v[130:133], v142
	ds_read_b128 v[134:137], v142 offset:1024
	ds_read_b128 v[138:141], v142 offset:2048
	ds_read_b128 v[142:145], v142 offset:3072
	ds_read_b128 v[166:169], v154
	ds_read_b128 v[170:173], v154 offset:1024
	ds_read_b128 v[174:177], v154 offset:2048
	ds_read_b128 v[178:181], v154 offset:3072
	s_add_u32 s16, s46, 0x160000
	s_addc_u32 s17, s47, 0
	s_mov_b32 m0, s34
	ds_read_b128 v[182:185], v198 offset:32768
	ds_read_b128 v[186:189], v198 offset:33792
	ds_read_b128 v[202:205], v198 offset:34816
	ds_read_b128 v[206:209], v198 offset:35840
	ds_read_b128 v[210:213], v198 offset:36864
	ds_read_b128 v[214:217], v198 offset:37888
	ds_read_b128 v[218:221], v198 offset:38912
	ds_read_b128 v[222:225], v198 offset:39936
	global_load_lds_dwordx4 v146, s[16:17]
	s_mov_b32 m0, s35
	s_nop 0
	global_load_lds_dwordx4 v150, s[16:17]
	s_waitcnt vmcnt(8)
	s_waitcnt lgkmcnt(0)
	s_barrier
	s_waitcnt lgkmcnt(0)
	v_mfma_f32_16x16x32_bf16 v[126:129], v[130:133], v[182:185], v[126:129]
	v_mfma_f32_16x16x32_bf16 v[122:125], v[138:141], v[182:185], v[122:125]
	v_mfma_f32_16x16x32_bf16 v[110:113], v[130:133], v[202:205], v[110:113]
	v_mfma_f32_16x16x32_bf16 v[106:109], v[138:141], v[202:205], v[106:109]
	v_mfma_f32_16x16x32_bf16 v[94:97], v[130:133], v[210:213], v[94:97]
	v_mfma_f32_16x16x32_bf16 v[90:93], v[138:141], v[210:213], v[90:93]
	v_mfma_f32_16x16x32_bf16 v[78:81], v[130:133], v[218:221], v[78:81]
	v_mfma_f32_16x16x32_bf16 v[74:77], v[138:141], v[218:221], v[74:77]
	v_mfma_f32_16x16x32_bf16 v[126:129], v[134:137], v[186:189], v[126:129]
	v_mfma_f32_16x16x32_bf16 v[122:125], v[142:145], v[186:189], v[122:125]
	v_mfma_f32_16x16x32_bf16 v[110:113], v[134:137], v[206:209], v[110:113]
	v_mfma_f32_16x16x32_bf16 v[106:109], v[142:145], v[206:209], v[106:109]
	v_mfma_f32_16x16x32_bf16 v[94:97], v[134:137], v[214:217], v[94:97]
	v_mfma_f32_16x16x32_bf16 v[90:93], v[142:145], v[214:217], v[90:93]
	v_mfma_f32_16x16x32_bf16 v[78:81], v[134:137], v[222:225], v[78:81]
	v_mfma_f32_16x16x32_bf16 v[74:77], v[142:145], v[222:225], v[74:77]
	v_mfma_f32_16x16x32_bf16 v[118:121], v[166:169], v[182:185], v[118:121]
	v_mfma_f32_16x16x32_bf16 v[114:117], v[174:177], v[182:185], v[114:117]
	v_mfma_f32_16x16x32_bf16 v[102:105], v[166:169], v[202:205], v[102:105]
	v_mfma_f32_16x16x32_bf16 v[98:101], v[174:177], v[202:205], v[98:101]
	v_mfma_f32_16x16x32_bf16 v[86:89], v[166:169], v[210:213], v[86:89]
	v_mfma_f32_16x16x32_bf16 v[82:85], v[174:177], v[210:213], v[82:85]
	v_mfma_f32_16x16x32_bf16 v[70:73], v[166:169], v[218:221], v[70:73]
	v_mfma_f32_16x16x32_bf16 v[66:69], v[174:177], v[218:221], v[66:69]
	v_mfma_f32_16x16x32_bf16 v[118:121], v[170:173], v[186:189], v[118:121]
	v_mfma_f32_16x16x32_bf16 v[114:117], v[178:181], v[186:189], v[114:117]
	v_mfma_f32_16x16x32_bf16 v[102:105], v[170:173], v[206:209], v[102:105]
	v_mfma_f32_16x16x32_bf16 v[98:101], v[178:181], v[206:209], v[98:101]
	v_mfma_f32_16x16x32_bf16 v[86:89], v[170:173], v[214:217], v[86:89]
	v_mfma_f32_16x16x32_bf16 v[82:85], v[178:181], v[214:217], v[82:85]
	v_mfma_f32_16x16x32_bf16 v[70:73], v[170:173], v[222:225], v[70:73]
	v_mfma_f32_16x16x32_bf16 v[66:69], v[178:181], v[222:225], v[66:69]
	s_barrier
	s_add_u32 s98, s22, 0x80
	s_addc_u32 s99, s23, 0
	s_add_u32 s100, s46, 0x80
	s_addc_u32 s101, s47, 0
	s_add_i32 s16, s56, s30
	s_mov_b32 m0, s16
	ds_read_b128 v[182:185], v198 offset:49152
	ds_read_b128 v[186:189], v198 offset:50176
	ds_read_b128 v[202:205], v198 offset:51200
	ds_read_b128 v[206:209], v198 offset:52224
	ds_read_b128 v[210:213], v198 offset:53248
	ds_read_b128 v[214:217], v198 offset:54272
	ds_read_b128 v[218:221], v198 offset:55296
	ds_read_b128 v[222:225], v198 offset:56320
	global_load_lds_dwordx4 v148, s[98:99]
	s_add_i32 m0, s16, 0x2000
	s_add_u32 s16, s22, 0x58080
	v_lshl_add_u64 v[190:191], v[226:227], 0, s[12:13]
	s_addc_u32 s17, s23, 0
	s_add_i32 s22, s57, s30
	global_load_lds_dwordx4 v[190:191], off
	s_mov_b32 m0, s22
	s_nop 0
	global_load_lds_dwordx4 v148, s[16:17]
	s_add_i32 m0, s22, 0x2000
	s_nop 0
	global_load_lds_dwordx4 v152, s[16:17]
	s_mov_b32 m0, s49
	s_nop 0
	global_load_lds_dwordx4 v146, s[100:101]
	s_mov_b32 m0, s50
	s_nop 0
	global_load_lds_dwordx4 v150, s[100:101]
	s_waitcnt vmcnt(8)
	s_waitcnt lgkmcnt(0)
	s_barrier
	s_waitcnt lgkmcnt(0)
	v_mfma_f32_16x16x32_bf16 v[62:65], v[130:133], v[182:185], v[62:65]
	v_mfma_f32_16x16x32_bf16 v[58:61], v[138:141], v[182:185], v[58:61]
	v_mfma_f32_16x16x32_bf16 v[46:49], v[130:133], v[202:205], v[46:49]
	v_mfma_f32_16x16x32_bf16 v[42:45], v[138:141], v[202:205], v[42:45]
	v_mfma_f32_16x16x32_bf16 v[30:33], v[130:133], v[210:213], v[30:33]
	v_mfma_f32_16x16x32_bf16 v[26:29], v[138:141], v[210:213], v[26:29]
	v_mfma_f32_16x16x32_bf16 v[14:17], v[130:133], v[218:221], v[14:17]
	v_mfma_f32_16x16x32_bf16 v[10:13], v[138:141], v[218:221], v[10:13]
	v_mfma_f32_16x16x32_bf16 v[62:65], v[134:137], v[186:189], v[62:65]
	v_mfma_f32_16x16x32_bf16 v[58:61], v[142:145], v[186:189], v[58:61]
	v_mfma_f32_16x16x32_bf16 v[46:49], v[134:137], v[206:209], v[46:49]
	v_mfma_f32_16x16x32_bf16 v[42:45], v[142:145], v[206:209], v[42:45]
	v_mfma_f32_16x16x32_bf16 v[30:33], v[134:137], v[214:217], v[30:33]
	v_mfma_f32_16x16x32_bf16 v[26:29], v[142:145], v[214:217], v[26:29]
	v_mfma_f32_16x16x32_bf16 v[14:17], v[134:137], v[222:225], v[14:17]
	v_mfma_f32_16x16x32_bf16 v[10:13], v[142:145], v[222:225], v[10:13]
	v_mfma_f32_16x16x32_bf16 v[54:57], v[166:169], v[182:185], v[54:57]
	v_mfma_f32_16x16x32_bf16 v[50:53], v[174:177], v[182:185], v[50:53]
	v_mfma_f32_16x16x32_bf16 v[38:41], v[166:169], v[202:205], v[38:41]
	v_mfma_f32_16x16x32_bf16 v[34:37], v[174:177], v[202:205], v[34:37]
	v_mfma_f32_16x16x32_bf16 v[22:25], v[166:169], v[210:213], v[22:25]
	v_mfma_f32_16x16x32_bf16 v[18:21], v[174:177], v[210:213], v[18:21]
	v_mfma_f32_16x16x32_bf16 v[6:9], v[166:169], v[218:221], v[6:9]
	v_mfma_f32_16x16x32_bf16 v[2:5], v[174:177], v[218:221], v[2:5]
	v_mfma_f32_16x16x32_bf16 v[54:57], v[170:173], v[186:189], v[54:57]
	v_mfma_f32_16x16x32_bf16 v[50:53], v[178:181], v[186:189], v[50:53]
	v_mfma_f32_16x16x32_bf16 v[38:41], v[170:173], v[206:209], v[38:41]
	v_mfma_f32_16x16x32_bf16 v[34:37], v[178:181], v[206:209], v[34:37]
	v_mfma_f32_16x16x32_bf16 v[22:25], v[170:173], v[214:217], v[22:25]
	v_mfma_f32_16x16x32_bf16 v[18:21], v[178:181], v[214:217], v[18:21]
	v_mfma_f32_16x16x32_bf16 v[6:9], v[170:173], v[222:225], v[6:9]
	v_mfma_f32_16x16x32_bf16 v[2:5], v[178:181], v[222:225], v[2:5]
	s_barrier
	s_add_i32 s25, s25, 2
	s_add_u32 s9, s9, 0x100
	s_addc_u32 s24, s24, 0
	s_cmpk_gt_u32 s25, 0x55
	s_mov_b64 s[16:17], s[20:21]
; #define PG8_STAGE(bufoff, gbase, voff) do { _Pragma("unroll") for (int _i = 0; _i < 2; ++_i) \
;         __builtin_amdgcn_global_load_lds((const unsigned*)((const char*)(gbase) + (voff)[_i]), (LAS unsigned*)(lds + (bufoff) + ldsw + _i * 8192), 16, 0, 0); } while (0)
; #define PG8_LDA(dst, b, h) do { _Pragma("unroll") for (int m = 0; m < 4; ++m) _Pragma("unroll") for (int k = 0; k < 2; ++k) dst[m][k] = *(const LAS bf16x8*)(lds + PG8_SA(b, h) + aoff + m * 2048 + k * 1024); } while (0)
; #define PG8_LDB(dst, b, h) do { _Pragma("unroll") for (int n = 0; n < 2; ++n) _Pragma("unroll") for (int k = 0; k < 2; ++k) dst[n][k] = *(const LAS bf16x8*)(lds + PG8_SB(b, h) + boff + n * 2048 + k * 1024); } while (0)
; #define PG8_MMA(ai, bj, At, Bt) do { __builtin_amdgcn_s_setprio(1); _Pragma("unroll") for (int m = 0; m < 4; ++m) _Pragma("unroll") for (int n = 0; n < 2; ++n) _Pragma("unroll") for (int k = 0; k < 2; ++k) \
;         acc[ai][bj][m][n] = __builtin_amdgcn_mfma_f32_16x16x32_bf16(Bt[n][k], At[m][k], acc[ai][bj][m][n], 0, 0, 0); __builtin_amdgcn_s_setprio(0); } while (0)
; #define PG8_WAIT_V(n) asm volatile("s_waitcnt vmcnt(" #n ")" ::: "memory")
; #define PG8_WAIT_L(n) asm volatile("s_waitcnt lgkmcnt(" #n ")" ::: "memory")
; #define PG8_BAR __builtin_amdgcn_s_barrier()
; #define PG8_SCHED __builtin_amdgcn_sched_barrier(0)
; template <class Epi, class Sched, bool ALIGN_EPI = false, bool SP2 = false>
; __device__ __forceinline__ void gemm_phase(LAS unsigned char* lds, const Gemm g, const Sched& S, const Epi& E) {
;     ...
;             PG8_LDB(B0, 0, 0); PG8_LDB(B1, 0, 1); PG8_SCHED; PG8_LDA(At, 0, 0); PG8_STAGE(PG8_SA(1, 1), a1 + hstep, voffA);
;             PG8_WAIT_V(8); PG8_WAIT_L(0); PG8_BAR; PG8_MMA(0, 0, At, B0); PG8_MMA(0, 1, At, B1); PG8_BAR; PG8_SCHED;
;             PG8_LDA(At, 0, 1); PG8_STAGE(PG8_SB(0, 0), b2, voffB); PG8_STAGE(PG8_SB(0, 1), b2 + hstepB, voffB); PG8_STAGE(PG8_SA(0, 0), a2, voffA);
;             PG8_WAIT_V(8); PG8_WAIT_L(0); PG8_BAR; PG8_MMA(1, 0, At, B0); PG8_MMA(1, 1, At, B1); PG8_BAR; PG8_SCHED;
.LBB0_1595:
	ds_read_b128 v[130:133], v196
	ds_read_b128 v[134:137], v196 offset:1024
	ds_read_b128 v[138:141], v196 offset:2048
	ds_read_b128 v[142:145], v196 offset:3072
	ds_read_b128 v[166:169], v197
	ds_read_b128 v[170:173], v197 offset:1024
	ds_read_b128 v[174:177], v197 offset:2048
	ds_read_b128 v[178:181], v197 offset:3072
	s_add_u32 s20, s16, 0x100
	s_addc_u32 s21, s17, 0
	s_cmpk_eq_i32 s25, 0x54
	s_cselect_b32 s47, s3, s21
	s_cselect_b32 s46, s2, s20
	s_cselect_b32 s23, s19, s24
	s_cselect_b32 s22, s18, s9
	v_lshl_add_u64 v[190:191], s[16:17], 0, v[158:159]
	s_add_i32 m0, s31, 0xc000
	ds_read_b128 v[182:185], v198
	ds_read_b128 v[186:189], v198 offset:1024
	ds_read_b128 v[202:205], v198 offset:2048
	ds_read_b128 v[206:209], v198 offset:3072
	ds_read_b128 v[210:213], v198 offset:4096
	ds_read_b128 v[214:217], v198 offset:5120
	ds_read_b128 v[218:221], v198 offset:6144
	ds_read_b128 v[222:225], v198 offset:7168
	global_load_lds_dwordx4 v[190:191], off
	v_lshl_add_u64 v[190:191], s[16:17], 0, v[160:161]
	s_add_i32 m0, s31, 0xe000
	s_nop 0
	global_load_lds_dwordx4 v[190:191], off
	s_waitcnt vmcnt(8)
	s_waitcnt lgkmcnt(0)
	s_barrier
	s_waitcnt lgkmcnt(0)
	v_mfma_f32_16x16x32_bf16 v[126:129], v[130:133], v[182:185], v[126:129]
	v_mfma_f32_16x16x32_bf16 v[122:125], v[138:141], v[182:185], v[122:125]
	v_mfma_f32_16x16x32_bf16 v[110:113], v[130:133], v[202:205], v[110:113]
	v_mfma_f32_16x16x32_bf16 v[106:109], v[138:141], v[202:205], v[106:109]
	v_mfma_f32_16x16x32_bf16 v[94:97], v[130:133], v[210:213], v[94:97]
	v_mfma_f32_16x16x32_bf16 v[90:93], v[138:141], v[210:213], v[90:93]
	v_mfma_f32_16x16x32_bf16 v[78:81], v[130:133], v[218:221], v[78:81]
	v_mfma_f32_16x16x32_bf16 v[74:77], v[138:141], v[218:221], v[74:77]
	v_mfma_f32_16x16x32_bf16 v[126:129], v[134:137], v[186:189], v[126:129]
	v_mfma_f32_16x16x32_bf16 v[122:125], v[142:145], v[186:189], v[122:125]
	v_mfma_f32_16x16x32_bf16 v[110:113], v[134:137], v[206:209], v[110:113]
	v_mfma_f32_16x16x32_bf16 v[106:109], v[142:145], v[206:209], v[106:109]
	v_mfma_f32_16x16x32_bf16 v[94:97], v[134:137], v[214:217], v[94:97]
	v_mfma_f32_16x16x32_bf16 v[90:93], v[142:145], v[214:217], v[90:93]
	v_mfma_f32_16x16x32_bf16 v[78:81], v[134:137], v[222:225], v[78:81]
	v_mfma_f32_16x16x32_bf16 v[74:77], v[142:145], v[222:225], v[74:77]
	v_mfma_f32_16x16x32_bf16 v[118:121], v[166:169], v[182:185], v[118:121]
	v_mfma_f32_16x16x32_bf16 v[114:117], v[174:177], v[182:185], v[114:117]
	v_mfma_f32_16x16x32_bf16 v[102:105], v[166:169], v[202:205], v[102:105]
	v_mfma_f32_16x16x32_bf16 v[98:101], v[174:177], v[202:205], v[98:101]
	v_mfma_f32_16x16x32_bf16 v[86:89], v[166:169], v[210:213], v[86:89]
	v_mfma_f32_16x16x32_bf16 v[82:85], v[174:177], v[210:213], v[82:85]
	v_mfma_f32_16x16x32_bf16 v[70:73], v[166:169], v[218:221], v[70:73]
	v_mfma_f32_16x16x32_bf16 v[66:69], v[174:177], v[218:221], v[66:69]
	v_mfma_f32_16x16x32_bf16 v[118:121], v[170:173], v[186:189], v[118:121]
	v_mfma_f32_16x16x32_bf16 v[114:117], v[178:181], v[186:189], v[114:117]
	v_mfma_f32_16x16x32_bf16 v[102:105], v[170:173], v[206:209], v[102:105]
	v_mfma_f32_16x16x32_bf16 v[98:101], v[178:181], v[206:209], v[98:101]
	v_mfma_f32_16x16x32_bf16 v[86:89], v[170:173], v[214:217], v[86:89]
	v_mfma_f32_16x16x32_bf16 v[82:85], v[178:181], v[214:217], v[82:85]
	v_mfma_f32_16x16x32_bf16 v[70:73], v[170:173], v[222:225], v[70:73]
	v_mfma_f32_16x16x32_bf16 v[66:69], v[178:181], v[222:225], v[66:69]
	s_barrier
	s_add_i32 s16, s52, s30
	s_mov_b32 m0, s16
	ds_read_b128 v[182:185], v198 offset:16384
	ds_read_b128 v[186:189], v198 offset:17408
	ds_read_b128 v[202:205], v198 offset:18432
	ds_read_b128 v[206:209], v198 offset:19456
	ds_read_b128 v[210:213], v198 offset:20480
	ds_read_b128 v[214:217], v198 offset:21504
	ds_read_b128 v[218:221], v198 offset:22528
	ds_read_b128 v[222:225], v198 offset:23552
	global_load_lds_dwordx4 v148, s[22:23]
	s_add_i32 m0, s16, 0x2000
	s_add_u32 s16, s22, 0x58000
	v_lshl_add_u64 v[226:227], s[22:23], 0, v[152:153]
	s_addc_u32 s17, s23, 0
	s_add_i32 s56, s53, s30
	global_load_lds_dwordx4 v152, s[22:23]
	s_mov_b32 m0, s56
	s_nop 0
	global_load_lds_dwordx4 v148, s[16:17]
	s_add_i32 m0, s56, 0x2000
	s_nop 0
	global_load_lds_dwordx4 v152, s[16:17]
	s_mov_b32 m0, s31
	s_nop 0
	global_load_lds_dwordx4 v146, s[46:47]
	s_mov_b32 m0, s33
	s_nop 0
	global_load_lds_dwordx4 v150, s[46:47]
	s_waitcnt vmcnt(8)
	s_waitcnt lgkmcnt(0)
	s_barrier
	s_waitcnt lgkmcnt(0)
	v_mfma_f32_16x16x32_bf16 v[62:65], v[130:133], v[182:185], v[62:65]
	v_mfma_f32_16x16x32_bf16 v[58:61], v[138:141], v[182:185], v[58:61]
	v_mfma_f32_16x16x32_bf16 v[46:49], v[130:133], v[202:205], v[46:49]
	v_mfma_f32_16x16x32_bf16 v[42:45], v[138:141], v[202:205], v[42:45]
	v_mfma_f32_16x16x32_bf16 v[30:33], v[130:133], v[210:213], v[30:33]
	v_mfma_f32_16x16x32_bf16 v[26:29], v[138:141], v[210:213], v[26:29]
	v_mfma_f32_16x16x32_bf16 v[14:17], v[130:133], v[218:221], v[14:17]
	v_mfma_f32_16x16x32_bf16 v[10:13], v[138:141], v[218:221], v[10:13]
	v_mfma_f32_16x16x32_bf16 v[62:65], v[134:137], v[186:189], v[62:65]
	v_mfma_f32_16x16x32_bf16 v[58:61], v[142:145], v[186:189], v[58:61]
	v_mfma_f32_16x16x32_bf16 v[46:49], v[134:137], v[206:209], v[46:49]
	v_mfma_f32_16x16x32_bf16 v[42:45], v[142:145], v[206:209], v[42:45]
	v_mfma_f32_16x16x32_bf16 v[30:33], v[134:137], v[214:217], v[30:33]
	v_mfma_f32_16x16x32_bf16 v[26:29], v[142:145], v[214:217], v[26:29]
	v_mfma_f32_16x16x32_bf16 v[14:17], v[134:137], v[222:225], v[14:17]
	v_mfma_f32_16x16x32_bf16 v[10:13], v[142:145], v[222:225], v[10:13]
	v_mfma_f32_16x16x32_bf16 v[54:57], v[166:169], v[182:185], v[54:57]
	v_mfma_f32_16x16x32_bf16 v[50:53], v[174:177], v[182:185], v[50:53]
	v_mfma_f32_16x16x32_bf16 v[38:41], v[166:169], v[202:205], v[38:41]
	v_mfma_f32_16x16x32_bf16 v[34:37], v[174:177], v[202:205], v[34:37]
	v_mfma_f32_16x16x32_bf16 v[22:25], v[166:169], v[210:213], v[22:25]
	v_mfma_f32_16x16x32_bf16 v[18:21], v[174:177], v[210:213], v[18:21]
	v_mfma_f32_16x16x32_bf16 v[6:9], v[166:169], v[218:221], v[6:9]
	v_mfma_f32_16x16x32_bf16 v[2:5], v[174:177], v[218:221], v[2:5]
	v_mfma_f32_16x16x32_bf16 v[54:57], v[170:173], v[186:189], v[54:57]
	v_mfma_f32_16x16x32_bf16 v[50:53], v[178:181], v[186:189], v[50:53]
	v_mfma_f32_16x16x32_bf16 v[38:41], v[170:173], v[206:209], v[38:41]
	v_mfma_f32_16x16x32_bf16 v[34:37], v[178:181], v[206:209], v[34:37]
	v_mfma_f32_16x16x32_bf16 v[22:25], v[170:173], v[214:217], v[22:25]
	v_mfma_f32_16x16x32_bf16 v[18:21], v[178:181], v[214:217], v[18:21]
	v_mfma_f32_16x16x32_bf16 v[6:9], v[170:173], v[222:225], v[6:9]
	v_mfma_f32_16x16x32_bf16 v[2:5], v[178:181], v[222:225], v[2:5]
	s_barrier
; #define PG8_STAGE(bufoff, gbase, voff) do { _Pragma("unroll") for (int _i = 0; _i < 2; ++_i) \
;         __builtin_amdgcn_global_load_lds((const unsigned*)((const char*)(gbase) + (voff)[_i]), (LAS unsigned*)(lds + (bufoff) + ldsw + _i * 8192), 16, 0, 0); } while (0)
; #define PG8_LDA(dst, b, h) do { _Pragma("unroll") for (int m = 0; m < 4; ++m) _Pragma("unroll") for (int k = 0; k < 2; ++k) dst[m][k] = *(const LAS bf16x8*)(lds + PG8_SA(b, h) + aoff + m * 2048 + k * 1024); } while (0)
; #define PG8_LDB(dst, b, h) do { _Pragma("unroll") for (int n = 0; n < 2; ++n) _Pragma("unroll") for (int k = 0; k < 2; ++k) dst[n][k] = *(const LAS bf16x8*)(lds + PG8_SB(b, h) + boff + n * 2048 + k * 1024); } while (0)
; #define PG8_MMA(ai, bj, At, Bt) do { __builtin_amdgcn_s_setprio(1); _Pragma("unroll") for (int m = 0; m < 4; ++m) _Pragma("unroll") for (int n = 0; n < 2; ++n) _Pragma("unroll") for (int k = 0; k < 2; ++k) \
;         acc[ai][bj][m][n] = __builtin_amdgcn_mfma_f32_16x16x32_bf16(Bt[n][k], At[m][k], acc[ai][bj][m][n], 0, 0, 0); __builtin_amdgcn_s_setprio(0); } while (0)
; #define PG8_WAIT_V(n) asm volatile("s_waitcnt vmcnt(" #n ")" ::: "memory")
; #define PG8_WAIT_L(n) asm volatile("s_waitcnt lgkmcnt(" #n ")" ::: "memory")
; #define PG8_BAR __builtin_amdgcn_s_barrier()
; #define PG8_SCHED __builtin_amdgcn_sched_barrier(0)
; template <class Epi, class Sched, bool ALIGN_EPI = false, bool SP2 = false>
; __device__ __forceinline__ void gemm_phase(LAS unsigned char* lds, const Gemm g, const Sched& S, const Epi& E) {
;     ...
;             PG8_LDB(B0, 1, 0); PG8_LDB(B1, 1, 1); PG8_SCHED; PG8_LDA(At, 1, 0); PG8_STAGE(PG8_SA(0, 1), a2 + hstep, voffA);
;             PG8_WAIT_V(8); PG8_WAIT_L(0); PG8_BAR; PG8_MMA(0, 0, At, B0); PG8_MMA(0, 1, At, B1); PG8_BAR; PG8_SCHED;
;             PG8_LDA(At, 1, 1); PG8_STAGE(PG8_SB(1, 0), b3, voffB); PG8_STAGE(PG8_SB(1, 1), b3 + hstepB, voffB); PG8_STAGE(PG8_SA(1, 0), a3, voffA);
;             PG8_WAIT_V(8); PG8_WAIT_L(0); PG8_BAR; PG8_MMA(1, 0, At, B0); PG8_MMA(1, 1, At, B1); PG8_BAR; PG8_SCHED;
;     ...
;         if constexpr (ALIGN_EPI) { if (wr == 0) PG8_BAR; }
	s_add_i32 s56, 0, 0x18000
	s_add_i32 s57, 0, 0x1c000
	v_add_u32_e32 v142, s56, v1
	v_add_u32_e32 v154, s57, v1
	ds_read_b128 v[130:133], v142
	ds_read_b128 v[134:137], v142 offset:1024
	ds_read_b128 v[138:141], v142 offset:2048
	ds_read_b128 v[142:145], v142 offset:3072
	ds_read_b128 v[166:169], v154
	ds_read_b128 v[170:173], v154 offset:1024
	ds_read_b128 v[174:177], v154 offset:2048
	ds_read_b128 v[178:181], v154 offset:3072
	s_add_u32 s16, s46, 0x160000
	s_addc_u32 s17, s47, 0
	s_mov_b32 m0, s34
	ds_read_b128 v[182:185], v198 offset:32768
	ds_read_b128 v[186:189], v198 offset:33792
	ds_read_b128 v[202:205], v198 offset:34816
	ds_read_b128 v[206:209], v198 offset:35840
	ds_read_b128 v[210:213], v198 offset:36864
	ds_read_b128 v[214:217], v198 offset:37888
	ds_read_b128 v[218:221], v198 offset:38912
	ds_read_b128 v[222:225], v198 offset:39936
	global_load_lds_dwordx4 v146, s[16:17]
	s_mov_b32 m0, s35
	s_nop 0
	global_load_lds_dwordx4 v150, s[16:17]
	s_waitcnt vmcnt(8)
	s_waitcnt lgkmcnt(0)
	s_barrier
	s_waitcnt lgkmcnt(0)
	v_mfma_f32_16x16x32_bf16 v[126:129], v[130:133], v[182:185], v[126:129]
	v_mfma_f32_16x16x32_bf16 v[122:125], v[138:141], v[182:185], v[122:125]
	v_mfma_f32_16x16x32_bf16 v[110:113], v[130:133], v[202:205], v[110:113]
	v_mfma_f32_16x16x32_bf16 v[106:109], v[138:141], v[202:205], v[106:109]
	v_mfma_f32_16x16x32_bf16 v[94:97], v[130:133], v[210:213], v[94:97]
	v_mfma_f32_16x16x32_bf16 v[90:93], v[138:141], v[210:213], v[90:93]
	v_mfma_f32_16x16x32_bf16 v[78:81], v[130:133], v[218:221], v[78:81]
	v_mfma_f32_16x16x32_bf16 v[74:77], v[138:141], v[218:221], v[74:77]
	v_mfma_f32_16x16x32_bf16 v[126:129], v[134:137], v[186:189], v[126:129]
	v_mfma_f32_16x16x32_bf16 v[122:125], v[142:145], v[186:189], v[122:125]
	v_mfma_f32_16x16x32_bf16 v[110:113], v[134:137], v[206:209], v[110:113]
	v_mfma_f32_16x16x32_bf16 v[106:109], v[142:145], v[206:209], v[106:109]
	v_mfma_f32_16x16x32_bf16 v[94:97], v[134:137], v[214:217], v[94:97]
	v_mfma_f32_16x16x32_bf16 v[90:93], v[142:145], v[214:217], v[90:93]
	v_mfma_f32_16x16x32_bf16 v[78:81], v[134:137], v[222:225], v[78:81]
	v_mfma_f32_16x16x32_bf16 v[74:77], v[142:145], v[222:225], v[74:77]
	v_mfma_f32_16x16x32_bf16 v[118:121], v[166:169], v[182:185], v[118:121]
	v_mfma_f32_16x16x32_bf16 v[114:117], v[174:177], v[182:185], v[114:117]
	v_mfma_f32_16x16x32_bf16 v[102:105], v[166:169], v[202:205], v[102:105]
	v_mfma_f32_16x16x32_bf16 v[98:101], v[174:177], v[202:205], v[98:101]
	v_mfma_f32_16x16x32_bf16 v[86:89], v[166:169], v[210:213], v[86:89]
	v_mfma_f32_16x16x32_bf16 v[82:85], v[174:177], v[210:213], v[82:85]
	v_mfma_f32_16x16x32_bf16 v[70:73], v[166:169], v[218:221], v[70:73]
	v_mfma_f32_16x16x32_bf16 v[66:69], v[174:177], v[218:221], v[66:69]
	v_mfma_f32_16x16x32_bf16 v[118:121], v[170:173], v[186:189], v[118:121]
	v_mfma_f32_16x16x32_bf16 v[114:117], v[178:181], v[186:189], v[114:117]
	v_mfma_f32_16x16x32_bf16 v[102:105], v[170:173], v[206:209], v[102:105]
	v_mfma_f32_16x16x32_bf16 v[98:101], v[178:181], v[206:209], v[98:101]
	v_mfma_f32_16x16x32_bf16 v[86:89], v[170:173], v[214:217], v[86:89]
	v_mfma_f32_16x16x32_bf16 v[82:85], v[178:181], v[214:217], v[82:85]
	v_mfma_f32_16x16x32_bf16 v[70:73], v[170:173], v[222:225], v[70:73]
	v_mfma_f32_16x16x32_bf16 v[66:69], v[178:181], v[222:225], v[66:69]
	s_barrier
	s_add_u32 s98, s22, 0x80
	s_addc_u32 s99, s23, 0
	s_add_u32 s100, s46, 0x80
	s_addc_u32 s101, s47, 0
	s_add_i32 s16, s56, s30
	s_mov_b32 m0, s16
	ds_read_b128 v[182:185], v198 offset:49152
	ds_read_b128 v[186:189], v198 offset:50176
	ds_read_b128 v[202:205], v198 offset:51200
	ds_read_b128 v[206:209], v198 offset:52224
	ds_read_b128 v[210:213], v198 offset:53248
	ds_read_b128 v[214:217], v198 offset:54272
	ds_read_b128 v[218:221], v198 offset:55296
	ds_read_b128 v[222:225], v198 offset:56320
	global_load_lds_dwordx4 v148, s[98:99]
	s_add_i32 m0, s16, 0x2000
	s_add_u32 s16, s22, 0x58080
	v_lshl_add_u64 v[190:191], v[226:227], 0, s[12:13]
	s_addc_u32 s17, s23, 0
	s_add_i32 s22, s57, s30
	global_load_lds_dwordx4 v[190:191], off
	s_mov_b32 m0, s22
	s_nop 0
	global_load_lds_dwordx4 v148, s[16:17]
	s_add_i32 m0, s22, 0x2000
	s_nop 0
	global_load_lds_dwordx4 v152, s[16:17]
	s_mov_b32 m0, s49
	s_nop 0
	global_load_lds_dwordx4 v146, s[100:101]
	s_mov_b32 m0, s50
	s_nop 0
	global_load_lds_dwordx4 v150, s[100:101]
	s_waitcnt vmcnt(8)
	s_waitcnt lgkmcnt(0)
	s_barrier
	s_waitcnt lgkmcnt(0)
	v_mfma_f32_16x16x32_bf16 v[62:65], v[130:133], v[182:185], v[62:65]
	v_mfma_f32_16x16x32_bf16 v[58:61], v[138:141], v[182:185], v[58:61]
	v_mfma_f32_16x16x32_bf16 v[46:49], v[130:133], v[202:205], v[46:49]
	v_mfma_f32_16x16x32_bf16 v[42:45], v[138:141], v[202:205], v[42:45]
	v_mfma_f32_16x16x32_bf16 v[30:33], v[130:133], v[210:213], v[30:33]
	v_mfma_f32_16x16x32_bf16 v[26:29], v[138:141], v[210:213], v[26:29]
	v_mfma_f32_16x16x32_bf16 v[14:17], v[130:133], v[218:221], v[14:17]
	v_mfma_f32_16x16x32_bf16 v[10:13], v[138:141], v[218:221], v[10:13]
	v_mfma_f32_16x16x32_bf16 v[62:65], v[134:137], v[186:189], v[62:65]
	v_mfma_f32_16x16x32_bf16 v[58:61], v[142:145], v[186:189], v[58:61]
	v_mfma_f32_16x16x32_bf16 v[46:49], v[134:137], v[206:209], v[46:49]
	v_mfma_f32_16x16x32_bf16 v[42:45], v[142:145], v[206:209], v[42:45]
	v_mfma_f32_16x16x32_bf16 v[30:33], v[134:137], v[214:217], v[30:33]
	v_mfma_f32_16x16x32_bf16 v[26:29], v[142:145], v[214:217], v[26:29]
	v_mfma_f32_16x16x32_bf16 v[14:17], v[134:137], v[222:225], v[14:17]
	v_mfma_f32_16x16x32_bf16 v[10:13], v[142:145], v[222:225], v[10:13]
	v_mfma_f32_16x16x32_bf16 v[54:57], v[166:169], v[182:185], v[54:57]
	v_mfma_f32_16x16x32_bf16 v[50:53], v[174:177], v[182:185], v[50:53]
	v_mfma_f32_16x16x32_bf16 v[38:41], v[166:169], v[202:205], v[38:41]
	v_mfma_f32_16x16x32_bf16 v[34:37], v[174:177], v[202:205], v[34:37]
	v_mfma_f32_16x16x32_bf16 v[22:25], v[166:169], v[210:213], v[22:25]
	v_mfma_f32_16x16x32_bf16 v[18:21], v[174:177], v[210:213], v[18:21]
	v_mfma_f32_16x16x32_bf16 v[6:9], v[166:169], v[218:221], v[6:9]
	v_mfma_f32_16x16x32_bf16 v[2:5], v[174:177], v[218:221], v[2:5]
	v_mfma_f32_16x16x32_bf16 v[54:57], v[170:173], v[186:189], v[54:57]
	v_mfma_f32_16x16x32_bf16 v[50:53], v[178:181], v[186:189], v[50:53]
	v_mfma_f32_16x16x32_bf16 v[38:41], v[170:173], v[206:209], v[38:41]
	v_mfma_f32_16x16x32_bf16 v[34:37], v[178:181], v[206:209], v[34:37]
	v_mfma_f32_16x16x32_bf16 v[22:25], v[170:173], v[214:217], v[22:25]
	v_mfma_f32_16x16x32_bf16 v[18:21], v[178:181], v[214:217], v[18:21]
	v_mfma_f32_16x16x32_bf16 v[6:9], v[170:173], v[222:225], v[6:9]
	v_mfma_f32_16x16x32_bf16 v[2:5], v[178:181], v[222:225], v[2:5]
	s_barrier
	s_add_i32 s25, s25, 2
	s_add_u32 s9, s9, 0x100
	s_addc_u32 s24, s24, 0
	s_cmpk_gt_u32 s25, 0x55
	s_mov_b64 s[16:17], s[20:21]
	s_cbranch_scc0 .LBB0_1595
	s_setprio 0
	s_and_b64 vcc, exec, s[14:15]
	s_cbranch_vccz .LBB0_1598
	s_barrier

; #define PG8_STAGE(bufoff, gbase, voff) do { _Pragma("unroll") for (int _i = 0; _i < 2; ++_i) \
;         __builtin_amdgcn_global_load_lds((const unsigned*)((const char*)(gbase) + (voff)[_i]), (LAS unsigned*)(lds + (bufoff) + ldsw + _i * 8192), 16, 0, 0); } while (0)
; #define PG8_LDA(dst, b, h) do { _Pragma("unroll") for (int m = 0; m < 4; ++m) _Pragma("unroll") for (int k = 0; k < 2; ++k) dst[m][k] = *(const LAS bf16x8*)(lds + PG8_SA(b, h) + aoff + m * 2048 + k * 1024); } while (0)
; #define PG8_LDB(dst, b, h) do { _Pragma("unroll") for (int n = 0; n < 2; ++n) _Pragma("unroll") for (int k = 0; k < 2; ++k) dst[n][k] = *(const LAS bf16x8*)(lds + PG8_SB(b, h) + boff + n * 2048 + k * 1024); } while (0)
; #define PG8_MMA(ai, bj, At, Bt) do { __builtin_amdgcn_s_setprio(1); _Pragma("unroll") for (int m = 0; m < 4; ++m) _Pragma("unroll") for (int n = 0; n < 2; ++n) _Pragma("unroll") for (int k = 0; k < 2; ++k) \
;         acc[ai][bj][m][n] = __builtin_amdgcn_mfma_f32_16x16x32_bf16(Bt[n][k], At[m][k], acc[ai][bj][m][n], 0, 0, 0); __builtin_amdgcn_s_setprio(0); } while (0)
; #define PG8_WAIT_V(n) asm volatile("s_waitcnt vmcnt(" #n ")" ::: "memory")
; #define PG8_WAIT_L(n) asm volatile("s_waitcnt lgkmcnt(" #n ")" ::: "memory")
; #define PG8_BAR __builtin_amdgcn_s_barrier()
; #define PG8_SCHED __builtin_amdgcn_sched_barrier(0)
; template <class Epi, class Sched, bool ALIGN_EPI = false, bool SP2 = false>
; __device__ __forceinline__ void gemm_phase(LAS unsigned char* lds, const Gemm g, const Sched& S, const Epi& E) {
;     ...
;             PG8_LDB(B0, 0, 0); PG8_LDB(B1, 0, 1); PG8_SCHED; PG8_LDA(At, 0, 0); PG8_STAGE(PG8_SA(1, 1), a1 + hstep, voffA);
;             PG8_WAIT_V(8); PG8_WAIT_L(0); PG8_BAR; PG8_MMA(0, 0, At, B0); PG8_MMA(0, 1, At, B1); PG8_BAR; PG8_SCHED;
;             PG8_LDA(At, 0, 1); PG8_STAGE(PG8_SB(0, 0), b2, voffB); PG8_STAGE(PG8_SB(0, 1), b2 + hstepB, voffB); PG8_STAGE(PG8_SA(0, 0), a2, voffA);
;             PG8_WAIT_V(8); PG8_WAIT_L(0); PG8_BAR; PG8_MMA(1, 0, At, B0); PG8_MMA(1, 1, At, B1); PG8_BAR; PG8_SCHED;
.Lprio_1926:
	ds_read_b128 v[130:133], v196
	ds_read_b128 v[134:137], v196 offset:1024
	ds_read_b128 v[138:141], v196 offset:2048
	ds_read_b128 v[142:145], v196 offset:3072
	ds_read_b128 v[166:169], v197
	ds_read_b128 v[170:173], v197 offset:1024
	ds_read_b128 v[174:177], v197 offset:2048
	ds_read_b128 v[178:181], v197 offset:3072
	s_add_u32 s20, s18, 0x100
	s_addc_u32 s21, s19, 0
	s_cmpk_eq_i32 s25, 0x54
	s_cselect_b32 s47, s17, s21
	s_cselect_b32 s46, s16, s20
	s_cselect_b32 s23, s3, s24
	s_cselect_b32 s22, s2, s5
	v_lshl_add_u64 v[190:191], s[18:19], 0, v[160:161]
	s_add_i32 m0, s27, 0xc000
	ds_read_b128 v[182:185], v198
	ds_read_b128 v[186:189], v198 offset:1024
	ds_read_b128 v[202:205], v198 offset:2048
	ds_read_b128 v[206:209], v198 offset:3072
	ds_read_b128 v[210:213], v198 offset:4096
	ds_read_b128 v[214:217], v198 offset:5120
	ds_read_b128 v[218:221], v198 offset:6144
	ds_read_b128 v[222:225], v198 offset:7168
	global_load_lds_dwordx4 v[190:191], off
	v_lshl_add_u64 v[190:191], s[18:19], 0, v[158:159]
	s_add_i32 m0, s27, 0xe000
	s_nop 0
	global_load_lds_dwordx4 v[190:191], off
	s_waitcnt lgkmcnt(0)
	s_barrier
	s_waitcnt lgkmcnt(0)
	v_mfma_f32_16x16x32_bf16 v[126:129], v[130:133], v[182:185], 0
	v_mfma_f32_16x16x32_bf16 v[122:125], v[138:141], v[182:185], 0
	v_mfma_f32_16x16x32_bf16 v[110:113], v[130:133], v[202:205], 0
	v_mfma_f32_16x16x32_bf16 v[106:109], v[138:141], v[202:205], 0
	v_mfma_f32_16x16x32_bf16 v[94:97], v[130:133], v[210:213], 0
	v_mfma_f32_16x16x32_bf16 v[90:93], v[138:141], v[210:213], 0
	v_mfma_f32_16x16x32_bf16 v[78:81], v[130:133], v[218:221], 0
	v_mfma_f32_16x16x32_bf16 v[74:77], v[138:141], v[218:221], 0
	v_mfma_f32_16x16x32_bf16 v[126:129], v[134:137], v[186:189], v[126:129]
	v_mfma_f32_16x16x32_bf16 v[122:125], v[142:145], v[186:189], v[122:125]
	v_mfma_f32_16x16x32_bf16 v[110:113], v[134:137], v[206:209], v[110:113]
	v_mfma_f32_16x16x32_bf16 v[106:109], v[142:145], v[206:209], v[106:109]
	v_mfma_f32_16x16x32_bf16 v[94:97], v[134:137], v[214:217], v[94:97]
	v_mfma_f32_16x16x32_bf16 v[90:93], v[142:145], v[214:217], v[90:93]
	v_mfma_f32_16x16x32_bf16 v[78:81], v[134:137], v[222:225], v[78:81]
	v_mfma_f32_16x16x32_bf16 v[74:77], v[142:145], v[222:225], v[74:77]
	v_mfma_f32_16x16x32_bf16 v[118:121], v[166:169], v[182:185], 0
	v_mfma_f32_16x16x32_bf16 v[114:117], v[174:177], v[182:185], 0
	v_mfma_f32_16x16x32_bf16 v[102:105], v[166:169], v[202:205], 0
	v_mfma_f32_16x16x32_bf16 v[98:101], v[174:177], v[202:205], 0
	v_mfma_f32_16x16x32_bf16 v[86:89], v[166:169], v[210:213], 0
	v_mfma_f32_16x16x32_bf16 v[82:85], v[174:177], v[210:213], 0
	v_mfma_f32_16x16x32_bf16 v[70:73], v[166:169], v[218:221], 0
	v_mfma_f32_16x16x32_bf16 v[66:69], v[174:177], v[218:221], 0
	v_mfma_f32_16x16x32_bf16 v[118:121], v[170:173], v[186:189], v[118:121]
	v_mfma_f32_16x16x32_bf16 v[114:117], v[178:181], v[186:189], v[114:117]
	v_mfma_f32_16x16x32_bf16 v[102:105], v[170:173], v[206:209], v[102:105]
	v_mfma_f32_16x16x32_bf16 v[98:101], v[178:181], v[206:209], v[98:101]
	v_mfma_f32_16x16x32_bf16 v[86:89], v[170:173], v[214:217], v[86:89]
	v_mfma_f32_16x16x32_bf16 v[82:85], v[178:181], v[214:217], v[82:85]
	v_mfma_f32_16x16x32_bf16 v[70:73], v[170:173], v[222:225], v[70:73]
	v_mfma_f32_16x16x32_bf16 v[66:69], v[178:181], v[222:225], v[66:69]
	s_barrier
	s_add_i32 s18, s50, s26
	s_mov_b32 m0, s18
	ds_read_b128 v[182:185], v198 offset:16384
	ds_read_b128 v[186:189], v198 offset:17408
	ds_read_b128 v[202:205], v198 offset:18432
	ds_read_b128 v[206:209], v198 offset:19456
	ds_read_b128 v[210:213], v198 offset:20480
	ds_read_b128 v[214:217], v198 offset:21504
	ds_read_b128 v[218:221], v198 offset:22528
	ds_read_b128 v[222:225], v198 offset:23552
	global_load_lds_dwordx4 v148, s[22:23]
	s_add_i32 m0, s18, 0x2000
	s_add_u32 s18, s22, 0x58000
	v_lshl_add_u64 v[226:227], s[22:23], 0, v[152:153]
	s_addc_u32 s19, s23, 0
	s_add_i32 s54, s51, s26
	global_load_lds_dwordx4 v152, s[22:23]
	s_mov_b32 m0, s54
	s_nop 0
	global_load_lds_dwordx4 v148, s[18:19]
	s_add_i32 m0, s54, 0x2000
	s_nop 0
	global_load_lds_dwordx4 v152, s[18:19]
	s_mov_b32 m0, s27
	s_nop 0
	global_load_lds_dwordx4 v146, s[46:47]
	s_mov_b32 m0, s28
	s_nop 0
	global_load_lds_dwordx4 v150, s[46:47]
	s_waitcnt lgkmcnt(0)
	s_barrier
	s_waitcnt lgkmcnt(0)
	v_mfma_f32_16x16x32_bf16 v[62:65], v[130:133], v[182:185], 0
	v_mfma_f32_16x16x32_bf16 v[58:61], v[138:141], v[182:185], 0
	v_mfma_f32_16x16x32_bf16 v[46:49], v[130:133], v[202:205], 0
	v_mfma_f32_16x16x32_bf16 v[42:45], v[138:141], v[202:205], 0
	v_mfma_f32_16x16x32_bf16 v[30:33], v[130:133], v[210:213], 0
	v_mfma_f32_16x16x32_bf16 v[26:29], v[138:141], v[210:213], 0
	v_mfma_f32_16x16x32_bf16 v[14:17], v[130:133], v[218:221], 0
	v_mfma_f32_16x16x32_bf16 v[10:13], v[138:141], v[218:221], 0
	v_mfma_f32_16x16x32_bf16 v[62:65], v[134:137], v[186:189], v[62:65]
	v_mfma_f32_16x16x32_bf16 v[58:61], v[142:145], v[186:189], v[58:61]
	v_mfma_f32_16x16x32_bf16 v[46:49], v[134:137], v[206:209], v[46:49]
	v_mfma_f32_16x16x32_bf16 v[42:45], v[142:145], v[206:209], v[42:45]
	v_mfma_f32_16x16x32_bf16 v[30:33], v[134:137], v[214:217], v[30:33]
	v_mfma_f32_16x16x32_bf16 v[26:29], v[142:145], v[214:217], v[26:29]
	v_mfma_f32_16x16x32_bf16 v[14:17], v[134:137], v[222:225], v[14:17]
	v_mfma_f32_16x16x32_bf16 v[10:13], v[142:145], v[222:225], v[10:13]
	v_mfma_f32_16x16x32_bf16 v[54:57], v[166:169], v[182:185], 0
	v_mfma_f32_16x16x32_bf16 v[50:53], v[174:177], v[182:185], 0
	v_mfma_f32_16x16x32_bf16 v[38:41], v[166:169], v[202:205], 0
	v_mfma_f32_16x16x32_bf16 v[34:37], v[174:177], v[202:205], 0
	v_mfma_f32_16x16x32_bf16 v[22:25], v[166:169], v[210:213], 0
	v_mfma_f32_16x16x32_bf16 v[18:21], v[174:177], v[210:213], 0
	v_mfma_f32_16x16x32_bf16 v[6:9], v[166:169], v[218:221], 0
	v_mfma_f32_16x16x32_bf16 v[2:5], v[174:177], v[218:221], 0
	v_mfma_f32_16x16x32_bf16 v[54:57], v[170:173], v[186:189], v[54:57]
	v_mfma_f32_16x16x32_bf16 v[50:53], v[178:181], v[186:189], v[50:53]
	v_mfma_f32_16x16x32_bf16 v[38:41], v[170:173], v[206:209], v[38:41]
	v_mfma_f32_16x16x32_bf16 v[34:37], v[178:181], v[206:209], v[34:37]
	v_mfma_f32_16x16x32_bf16 v[22:25], v[170:173], v[214:217], v[22:25]
	v_mfma_f32_16x16x32_bf16 v[18:21], v[178:181], v[214:217], v[18:21]
	v_mfma_f32_16x16x32_bf16 v[6:9], v[170:173], v[222:225], v[6:9]
	v_mfma_f32_16x16x32_bf16 v[2:5], v[178:181], v[222:225], v[2:5]
	s_barrier
; #define PG8_STAGE(bufoff, gbase, voff) do { _Pragma("unroll") for (int _i = 0; _i < 2; ++_i) \
;         __builtin_amdgcn_global_load_lds((const unsigned*)((const char*)(gbase) + (voff)[_i]), (LAS unsigned*)(lds + (bufoff) + ldsw + _i * 8192), 16, 0, 0); } while (0)
; #define PG8_LDA(dst, b, h) do { _Pragma("unroll") for (int m = 0; m < 4; ++m) _Pragma("unroll") for (int k = 0; k < 2; ++k) dst[m][k] = *(const LAS bf16x8*)(lds + PG8_SA(b, h) + aoff + m * 2048 + k * 1024); } while (0)
; #define PG8_LDB(dst, b, h) do { _Pragma("unroll") for (int n = 0; n < 2; ++n) _Pragma("unroll") for (int k = 0; k < 2; ++k) dst[n][k] = *(const LAS bf16x8*)(lds + PG8_SB(b, h) + boff + n * 2048 + k * 1024); } while (0)
; #define PG8_MMA(ai, bj, At, Bt) do { __builtin_amdgcn_s_setprio(1); _Pragma("unroll") for (int m = 0; m < 4; ++m) _Pragma("unroll") for (int n = 0; n < 2; ++n) _Pragma("unroll") for (int k = 0; k < 2; ++k) \
;         acc[ai][bj][m][n] = __builtin_amdgcn_mfma_f32_16x16x32_bf16(Bt[n][k], At[m][k], acc[ai][bj][m][n], 0, 0, 0); __builtin_amdgcn_s_setprio(0); } while (0)
; #define PG8_WAIT_V(n) asm volatile("s_waitcnt vmcnt(" #n ")" ::: "memory")
; #define PG8_WAIT_L(n) asm volatile("s_waitcnt lgkmcnt(" #n ")" ::: "memory")
; #define PG8_BAR __builtin_amdgcn_s_barrier()
; #define PG8_SCHED __builtin_amdgcn_sched_barrier(0)
; template <class Epi, class Sched, bool ALIGN_EPI = false, bool SP2 = false>
; __device__ __forceinline__ void gemm_phase(LAS unsigned char* lds, const Gemm g, const Sched& S, const Epi& E) {
;     ...
;             PG8_LDB(B0, 1, 0); PG8_LDB(B1, 1, 1); PG8_SCHED; PG8_LDA(At, 1, 0); PG8_STAGE(PG8_SA(0, 1), a2 + hstep, voffA);
;             PG8_WAIT_V(8); PG8_WAIT_L(0); PG8_BAR; PG8_MMA(0, 0, At, B0); PG8_MMA(0, 1, At, B1); PG8_BAR; PG8_SCHED;
;             PG8_LDA(At, 1, 1); PG8_STAGE(PG8_SB(1, 0), b3, voffB); PG8_STAGE(PG8_SB(1, 1), b3 + hstepB, voffB); PG8_STAGE(PG8_SA(1, 0), a3, voffA);
;             PG8_WAIT_V(8); PG8_WAIT_L(0); PG8_BAR; PG8_MMA(1, 0, At, B0); PG8_MMA(1, 1, At, B1); PG8_BAR; PG8_SCHED;
	s_add_i32 s54, 0, 0x18000
	s_add_i32 s55, 0, 0x1c000
	v_add_u32_e32 v142, s54, v1
	v_add_u32_e32 v154, s55, v1
	ds_read_b128 v[130:133], v142
	ds_read_b128 v[134:137], v142 offset:1024
	ds_read_b128 v[138:141], v142 offset:2048
	ds_read_b128 v[142:145], v142 offset:3072
	ds_read_b128 v[166:169], v154
	ds_read_b128 v[170:173], v154 offset:1024
	ds_read_b128 v[174:177], v154 offset:2048
	ds_read_b128 v[178:181], v154 offset:3072
	s_add_u32 s18, s46, 0x160000
	s_addc_u32 s19, s47, 0
	s_mov_b32 m0, s29
	ds_read_b128 v[182:185], v198 offset:32768
	ds_read_b128 v[186:189], v198 offset:33792
	ds_read_b128 v[202:205], v198 offset:34816
	ds_read_b128 v[206:209], v198 offset:35840
	ds_read_b128 v[210:213], v198 offset:36864
	ds_read_b128 v[214:217], v198 offset:37888
	ds_read_b128 v[218:221], v198 offset:38912
	ds_read_b128 v[222:225], v198 offset:39936
	global_load_lds_dwordx4 v146, s[18:19]
	s_mov_b32 m0, s30
	s_nop 0
	global_load_lds_dwordx4 v150, s[18:19]
	s_waitcnt vmcnt(8)
	s_waitcnt lgkmcnt(0)
	s_barrier
	s_waitcnt lgkmcnt(0)
	v_mfma_f32_16x16x32_bf16 v[126:129], v[130:133], v[182:185], v[126:129]
	v_mfma_f32_16x16x32_bf16 v[122:125], v[138:141], v[182:185], v[122:125]
	v_mfma_f32_16x16x32_bf16 v[110:113], v[130:133], v[202:205], v[110:113]
	v_mfma_f32_16x16x32_bf16 v[106:109], v[138:141], v[202:205], v[106:109]
	v_mfma_f32_16x16x32_bf16 v[94:97], v[130:133], v[210:213], v[94:97]
	v_mfma_f32_16x16x32_bf16 v[90:93], v[138:141], v[210:213], v[90:93]
	v_mfma_f32_16x16x32_bf16 v[78:81], v[130:133], v[218:221], v[78:81]
	v_mfma_f32_16x16x32_bf16 v[74:77], v[138:141], v[218:221], v[74:77]
	v_mfma_f32_16x16x32_bf16 v[126:129], v[134:137], v[186:189], v[126:129]
	v_mfma_f32_16x16x32_bf16 v[122:125], v[142:145], v[186:189], v[122:125]
	v_mfma_f32_16x16x32_bf16 v[110:113], v[134:137], v[206:209], v[110:113]
	v_mfma_f32_16x16x32_bf16 v[106:109], v[142:145], v[206:209], v[106:109]
	v_mfma_f32_16x16x32_bf16 v[94:97], v[134:137], v[214:217], v[94:97]
	v_mfma_f32_16x16x32_bf16 v[90:93], v[142:145], v[214:217], v[90:93]
	v_mfma_f32_16x16x32_bf16 v[78:81], v[134:137], v[222:225], v[78:81]
	v_mfma_f32_16x16x32_bf16 v[74:77], v[142:145], v[222:225], v[74:77]
	v_mfma_f32_16x16x32_bf16 v[118:121], v[166:169], v[182:185], v[118:121]
	v_mfma_f32_16x16x32_bf16 v[114:117], v[174:177], v[182:185], v[114:117]
	v_mfma_f32_16x16x32_bf16 v[102:105], v[166:169], v[202:205], v[102:105]
	v_mfma_f32_16x16x32_bf16 v[98:101], v[174:177], v[202:205], v[98:101]
	v_mfma_f32_16x16x32_bf16 v[86:89], v[166:169], v[210:213], v[86:89]
	v_mfma_f32_16x16x32_bf16 v[82:85], v[174:177], v[210:213], v[82:85]
	v_mfma_f32_16x16x32_bf16 v[70:73], v[166:169], v[218:221], v[70:73]
	v_mfma_f32_16x16x32_bf16 v[66:69], v[174:177], v[218:221], v[66:69]
	v_mfma_f32_16x16x32_bf16 v[118:121], v[170:173], v[186:189], v[118:121]
	v_mfma_f32_16x16x32_bf16 v[114:117], v[178:181], v[186:189], v[114:117]
	v_mfma_f32_16x16x32_bf16 v[102:105], v[170:173], v[206:209], v[102:105]
	v_mfma_f32_16x16x32_bf16 v[98:101], v[178:181], v[206:209], v[98:101]
	v_mfma_f32_16x16x32_bf16 v[86:89], v[170:173], v[214:217], v[86:89]
	v_mfma_f32_16x16x32_bf16 v[82:85], v[178:181], v[214:217], v[82:85]
	v_mfma_f32_16x16x32_bf16 v[70:73], v[170:173], v[222:225], v[70:73]
	v_mfma_f32_16x16x32_bf16 v[66:69], v[178:181], v[222:225], v[66:69]
	s_barrier
	s_add_u32 s98, s22, 0x80
	s_addc_u32 s99, s23, 0
	s_add_u32 s100, s46, 0x80
	s_addc_u32 s101, s47, 0
	s_add_i32 s18, s54, s26
	s_mov_b32 m0, s18
	ds_read_b128 v[182:185], v198 offset:49152
	ds_read_b128 v[186:189], v198 offset:50176
	ds_read_b128 v[202:205], v198 offset:51200
	ds_read_b128 v[206:209], v198 offset:52224
	ds_read_b128 v[210:213], v198 offset:53248
	ds_read_b128 v[214:217], v198 offset:54272
	ds_read_b128 v[218:221], v198 offset:55296
	ds_read_b128 v[222:225], v198 offset:56320
	global_load_lds_dwordx4 v148, s[98:99]
	s_add_i32 m0, s18, 0x2000
	s_add_u32 s18, s22, 0x58080
	v_lshl_add_u64 v[190:191], v[226:227], 0, s[12:13]
	s_addc_u32 s19, s23, 0
	s_add_i32 s22, s55, s26
	global_load_lds_dwordx4 v[190:191], off
	s_mov_b32 m0, s22
	s_nop 0
	global_load_lds_dwordx4 v148, s[18:19]
	s_add_i32 m0, s22, 0x2000
	s_nop 0
	global_load_lds_dwordx4 v152, s[18:19]
	s_mov_b32 m0, s37
	s_nop 0
	global_load_lds_dwordx4 v146, s[100:101]
	s_mov_b32 m0, s48
	s_nop 0
	global_load_lds_dwordx4 v150, s[100:101]
	s_waitcnt vmcnt(8)
	s_waitcnt lgkmcnt(0)
	s_barrier
	s_waitcnt lgkmcnt(0)
	v_mfma_f32_16x16x32_bf16 v[62:65], v[130:133], v[182:185], v[62:65]
	v_mfma_f32_16x16x32_bf16 v[58:61], v[138:141], v[182:185], v[58:61]
	v_mfma_f32_16x16x32_bf16 v[46:49], v[130:133], v[202:205], v[46:49]
	v_mfma_f32_16x16x32_bf16 v[42:45], v[138:141], v[202:205], v[42:45]
	v_mfma_f32_16x16x32_bf16 v[30:33], v[130:133], v[210:213], v[30:33]
	v_mfma_f32_16x16x32_bf16 v[26:29], v[138:141], v[210:213], v[26:29]
	v_mfma_f32_16x16x32_bf16 v[14:17], v[130:133], v[218:221], v[14:17]
	v_mfma_f32_16x16x32_bf16 v[10:13], v[138:141], v[218:221], v[10:13]
	v_mfma_f32_16x16x32_bf16 v[62:65], v[134:137], v[186:189], v[62:65]
	v_mfma_f32_16x16x32_bf16 v[58:61], v[142:145], v[186:189], v[58:61]
	v_mfma_f32_16x16x32_bf16 v[46:49], v[134:137], v[206:209], v[46:49]
	v_mfma_f32_16x16x32_bf16 v[42:45], v[142:145], v[206:209], v[42:45]
	v_mfma_f32_16x16x32_bf16 v[30:33], v[134:137], v[214:217], v[30:33]
	v_mfma_f32_16x16x32_bf16 v[26:29], v[142:145], v[214:217], v[26:29]
	v_mfma_f32_16x16x32_bf16 v[14:17], v[134:137], v[222:225], v[14:17]
	v_mfma_f32_16x16x32_bf16 v[10:13], v[142:145], v[222:225], v[10:13]
	v_mfma_f32_16x16x32_bf16 v[54:57], v[166:169], v[182:185], v[54:57]
	v_mfma_f32_16x16x32_bf16 v[50:53], v[174:177], v[182:185], v[50:53]
	v_mfma_f32_16x16x32_bf16 v[38:41], v[166:169], v[202:205], v[38:41]
	v_mfma_f32_16x16x32_bf16 v[34:37], v[174:177], v[202:205], v[34:37]
	v_mfma_f32_16x16x32_bf16 v[22:25], v[166:169], v[210:213], v[22:25]
	v_mfma_f32_16x16x32_bf16 v[18:21], v[174:177], v[210:213], v[18:21]
	v_mfma_f32_16x16x32_bf16 v[6:9], v[166:169], v[218:221], v[6:9]
	v_mfma_f32_16x16x32_bf16 v[2:5], v[174:177], v[218:221], v[2:5]
	v_mfma_f32_16x16x32_bf16 v[54:57], v[170:173], v[186:189], v[54:57]
	v_mfma_f32_16x16x32_bf16 v[50:53], v[178:181], v[186:189], v[50:53]
	v_mfma_f32_16x16x32_bf16 v[38:41], v[170:173], v[206:209], v[38:41]
	v_mfma_f32_16x16x32_bf16 v[34:37], v[178:181], v[206:209], v[34:37]
	v_mfma_f32_16x16x32_bf16 v[22:25], v[170:173], v[214:217], v[22:25]
	v_mfma_f32_16x16x32_bf16 v[18:21], v[178:181], v[214:217], v[18:21]
	v_mfma_f32_16x16x32_bf16 v[6:9], v[170:173], v[222:225], v[6:9]
	v_mfma_f32_16x16x32_bf16 v[2:5], v[178:181], v[222:225], v[2:5]
	s_barrier
	s_add_i32 s25, s25, 2
	s_add_u32 s5, s5, 0x100
	s_addc_u32 s24, s24, 0
	s_cmpk_lt_u32 s25, 0x56
	s_mov_b64 s[18:19], s[20:21]
; #define PG8_STAGE(bufoff, gbase, voff) do { _Pragma("unroll") for (int _i = 0; _i < 2; ++_i) \
;         __builtin_amdgcn_global_load_lds((const unsigned*)((const char*)(gbase) + (voff)[_i]), (LAS unsigned*)(lds + (bufoff) + ldsw + _i * 8192), 16, 0, 0); } while (0)
; #define PG8_LDA(dst, b, h) do { _Pragma("unroll") for (int m = 0; m < 4; ++m) _Pragma("unroll") for (int k = 0; k < 2; ++k) dst[m][k] = *(const LAS bf16x8*)(lds + PG8_SA(b, h) + aoff + m * 2048 + k * 1024); } while (0)
; #define PG8_LDB(dst, b, h) do { _Pragma("unroll") for (int n = 0; n < 2; ++n) _Pragma("unroll") for (int k = 0; k < 2; ++k) dst[n][k] = *(const LAS bf16x8*)(lds + PG8_SB(b, h) + boff + n * 2048 + k * 1024); } while (0)
; #define PG8_MMA(ai, bj, At, Bt) do { __builtin_amdgcn_s_setprio(1); _Pragma("unroll") for (int m = 0; m < 4; ++m) _Pragma("unroll") for (int n = 0; n < 2; ++n) _Pragma("unroll") for (int k = 0; k < 2; ++k) \
;         acc[ai][bj][m][n] = __builtin_amdgcn_mfma_f32_16x16x32_bf16(Bt[n][k], At[m][k], acc[ai][bj][m][n], 0, 0, 0); __builtin_amdgcn_s_setprio(0); } while (0)
; #define PG8_WAIT_V(n) asm volatile("s_waitcnt vmcnt(" #n ")" ::: "memory")
; #define PG8_WAIT_L(n) asm volatile("s_waitcnt lgkmcnt(" #n ")" ::: "memory")
; #define PG8_BAR __builtin_amdgcn_s_barrier()
; #define PG8_SCHED __builtin_amdgcn_sched_barrier(0)
; template <class Epi, class Sched, bool ALIGN_EPI = false, bool SP2 = false>
; __device__ __forceinline__ void gemm_phase(LAS unsigned char* lds, const Gemm g, const Sched& S, const Epi& E) {
;     ...
;             PG8_LDB(B0, 0, 0); PG8_LDB(B1, 0, 1); PG8_SCHED; PG8_LDA(At, 0, 0); PG8_STAGE(PG8_SA(1, 1), a1 + hstep, voffA);
;             PG8_WAIT_V(8); PG8_WAIT_L(0); PG8_BAR; PG8_MMA(0, 0, At, B0); PG8_MMA(0, 1, At, B1); PG8_BAR; PG8_SCHED;
;             PG8_LDA(At, 0, 1); PG8_STAGE(PG8_SB(0, 0), b2, voffB); PG8_STAGE(PG8_SB(0, 1), b2 + hstepB, voffB); PG8_STAGE(PG8_SA(0, 0), a2, voffA);
;             PG8_WAIT_V(8); PG8_WAIT_L(0); PG8_BAR; PG8_MMA(1, 0, At, B0); PG8_MMA(1, 1, At, B1); PG8_BAR; PG8_SCHED;
.LBB0_1926:
	ds_read_b128 v[130:133], v196
	ds_read_b128 v[134:137], v196 offset:1024
	ds_read_b128 v[138:141], v196 offset:2048
	ds_read_b128 v[142:145], v196 offset:3072
	ds_read_b128 v[166:169], v197
	ds_read_b128 v[170:173], v197 offset:1024
	ds_read_b128 v[174:177], v197 offset:2048
	ds_read_b128 v[178:181], v197 offset:3072
	s_add_u32 s20, s18, 0x100
	s_addc_u32 s21, s19, 0
	s_cmpk_eq_i32 s25, 0x54
	s_cselect_b32 s47, s17, s21
	s_cselect_b32 s46, s16, s20
	s_cselect_b32 s23, s3, s24
	s_cselect_b32 s22, s2, s5
	v_lshl_add_u64 v[190:191], s[18:19], 0, v[160:161]
	s_add_i32 m0, s27, 0xc000
	ds_read_b128 v[182:185], v198
	ds_read_b128 v[186:189], v198 offset:1024
	ds_read_b128 v[202:205], v198 offset:2048
	ds_read_b128 v[206:209], v198 offset:3072
	ds_read_b128 v[210:213], v198 offset:4096
	ds_read_b128 v[214:217], v198 offset:5120
	ds_read_b128 v[218:221], v198 offset:6144
	ds_read_b128 v[222:225], v198 offset:7168
	global_load_lds_dwordx4 v[190:191], off
	v_lshl_add_u64 v[190:191], s[18:19], 0, v[158:159]
	s_add_i32 m0, s27, 0xe000
	s_nop 0
	global_load_lds_dwordx4 v[190:191], off
	s_waitcnt vmcnt(8)
	s_waitcnt lgkmcnt(0)
	s_barrier
	s_waitcnt lgkmcnt(0)
	v_mfma_f32_16x16x32_bf16 v[126:129], v[130:133], v[182:185], v[126:129]
	v_mfma_f32_16x16x32_bf16 v[122:125], v[138:141], v[182:185], v[122:125]
	v_mfma_f32_16x16x32_bf16 v[110:113], v[130:133], v[202:205], v[110:113]
	v_mfma_f32_16x16x32_bf16 v[106:109], v[138:141], v[202:205], v[106:109]
	v_mfma_f32_16x16x32_bf16 v[94:97], v[130:133], v[210:213], v[94:97]
	v_mfma_f32_16x16x32_bf16 v[90:93], v[138:141], v[210:213], v[90:93]
	v_mfma_f32_16x16x32_bf16 v[78:81], v[130:133], v[218:221], v[78:81]
	v_mfma_f32_16x16x32_bf16 v[74:77], v[138:141], v[218:221], v[74:77]
	v_mfma_f32_16x16x32_bf16 v[126:129], v[134:137], v[186:189], v[126:129]
	v_mfma_f32_16x16x32_bf16 v[122:125], v[142:145], v[186:189], v[122:125]
	v_mfma_f32_16x16x32_bf16 v[110:113], v[134:137], v[206:209], v[110:113]
	v_mfma_f32_16x16x32_bf16 v[106:109], v[142:145], v[206:209], v[106:109]
	v_mfma_f32_16x16x32_bf16 v[94:97], v[134:137], v[214:217], v[94:97]
	v_mfma_f32_16x16x32_bf16 v[90:93], v[142:145], v[214:217], v[90:93]
	v_mfma_f32_16x16x32_bf16 v[78:81], v[134:137], v[222:225], v[78:81]
	v_mfma_f32_16x16x32_bf16 v[74:77], v[142:145], v[222:225], v[74:77]
	v_mfma_f32_16x16x32_bf16 v[118:121], v[166:169], v[182:185], v[118:121]
	v_mfma_f32_16x16x32_bf16 v[114:117], v[174:177], v[182:185], v[114:117]
	v_mfma_f32_16x16x32_bf16 v[102:105], v[166:169], v[202:205], v[102:105]
	v_mfma_f32_16x16x32_bf16 v[98:101], v[174:177], v[202:205], v[98:101]
	v_mfma_f32_16x16x32_bf16 v[86:89], v[166:169], v[210:213], v[86:89]
	v_mfma_f32_16x16x32_bf16 v[82:85], v[174:177], v[210:213], v[82:85]
	v_mfma_f32_16x16x32_bf16 v[70:73], v[166:169], v[218:221], v[70:73]
	v_mfma_f32_16x16x32_bf16 v[66:69], v[174:177], v[218:221], v[66:69]
	v_mfma_f32_16x16x32_bf16 v[118:121], v[170:173], v[186:189], v[118:121]
	v_mfma_f32_16x16x32_bf16 v[114:117], v[178:181], v[186:189], v[114:117]
	v_mfma_f32_16x16x32_bf16 v[102:105], v[170:173], v[206:209], v[102:105]
	v_mfma_f32_16x16x32_bf16 v[98:101], v[178:181], v[206:209], v[98:101]
	v_mfma_f32_16x16x32_bf16 v[86:89], v[170:173], v[214:217], v[86:89]
	v_mfma_f32_16x16x32_bf16 v[82:85], v[178:181], v[214:217], v[82:85]
	v_mfma_f32_16x16x32_bf16 v[70:73], v[170:173], v[222:225], v[70:73]
	v_mfma_f32_16x16x32_bf16 v[66:69], v[178:181], v[222:225], v[66:69]
	s_barrier
	s_add_i32 s18, s50, s26
	s_mov_b32 m0, s18
	ds_read_b128 v[182:185], v198 offset:16384
	ds_read_b128 v[186:189], v198 offset:17408
	ds_read_b128 v[202:205], v198 offset:18432
	ds_read_b128 v[206:209], v198 offset:19456
	ds_read_b128 v[210:213], v198 offset:20480
	ds_read_b128 v[214:217], v198 offset:21504
	ds_read_b128 v[218:221], v198 offset:22528
	ds_read_b128 v[222:225], v198 offset:23552
	global_load_lds_dwordx4 v148, s[22:23]
	s_add_i32 m0, s18, 0x2000
	s_add_u32 s18, s22, 0x58000
	v_lshl_add_u64 v[226:227], s[22:23], 0, v[152:153]
	s_addc_u32 s19, s23, 0
	s_add_i32 s54, s51, s26
	global_load_lds_dwordx4 v152, s[22:23]
	s_mov_b32 m0, s54
	s_nop 0
	global_load_lds_dwordx4 v148, s[18:19]
	s_add_i32 m0, s54, 0x2000
	s_nop 0
	global_load_lds_dwordx4 v152, s[18:19]
	s_mov_b32 m0, s27
	s_nop 0
	global_load_lds_dwordx4 v146, s[46:47]
	s_mov_b32 m0, s28
	s_nop 0
	global_load_lds_dwordx4 v150, s[46:47]
	s_waitcnt vmcnt(8)
	s_waitcnt lgkmcnt(0)
	s_barrier
	s_waitcnt lgkmcnt(0)
	v_mfma_f32_16x16x32_bf16 v[62:65], v[130:133], v[182:185], v[62:65]
	v_mfma_f32_16x16x32_bf16 v[58:61], v[138:141], v[182:185], v[58:61]
	v_mfma_f32_16x16x32_bf16 v[46:49], v[130:133], v[202:205], v[46:49]
	v_mfma_f32_16x16x32_bf16 v[42:45], v[138:141], v[202:205], v[42:45]
	v_mfma_f32_16x16x32_bf16 v[30:33], v[130:133], v[210:213], v[30:33]
	v_mfma_f32_16x16x32_bf16 v[26:29], v[138:141], v[210:213], v[26:29]
	v_mfma_f32_16x16x32_bf16 v[14:17], v[130:133], v[218:221], v[14:17]
	v_mfma_f32_16x16x32_bf16 v[10:13], v[138:141], v[218:221], v[10:13]
	v_mfma_f32_16x16x32_bf16 v[62:65], v[134:137], v[186:189], v[62:65]
	v_mfma_f32_16x16x32_bf16 v[58:61], v[142:145], v[186:189], v[58:61]
	v_mfma_f32_16x16x32_bf16 v[46:49], v[134:137], v[206:209], v[46:49]
	v_mfma_f32_16x16x32_bf16 v[42:45], v[142:145], v[206:209], v[42:45]
	v_mfma_f32_16x16x32_bf16 v[30:33], v[134:137], v[214:217], v[30:33]
	v_mfma_f32_16x16x32_bf16 v[26:29], v[142:145], v[214:217], v[26:29]
	v_mfma_f32_16x16x32_bf16 v[14:17], v[134:137], v[222:225], v[14:17]
	v_mfma_f32_16x16x32_bf16 v[10:13], v[142:145], v[222:225], v[10:13]
	v_mfma_f32_16x16x32_bf16 v[54:57], v[166:169], v[182:185], v[54:57]
	v_mfma_f32_16x16x32_bf16 v[50:53], v[174:177], v[182:185], v[50:53]
	v_mfma_f32_16x16x32_bf16 v[38:41], v[166:169], v[202:205], v[38:41]
	v_mfma_f32_16x16x32_bf16 v[34:37], v[174:177], v[202:205], v[34:37]
	v_mfma_f32_16x16x32_bf16 v[22:25], v[166:169], v[210:213], v[22:25]
	v_mfma_f32_16x16x32_bf16 v[18:21], v[174:177], v[210:213], v[18:21]
	v_mfma_f32_16x16x32_bf16 v[6:9], v[166:169], v[218:221], v[6:9]
	v_mfma_f32_16x16x32_bf16 v[2:5], v[174:177], v[218:221], v[2:5]
	v_mfma_f32_16x16x32_bf16 v[54:57], v[170:173], v[186:189], v[54:57]
	v_mfma_f32_16x16x32_bf16 v[50:53], v[178:181], v[186:189], v[50:53]
	v_mfma_f32_16x16x32_bf16 v[38:41], v[170:173], v[206:209], v[38:41]
	v_mfma_f32_16x16x32_bf16 v[34:37], v[178:181], v[206:209], v[34:37]
	v_mfma_f32_16x16x32_bf16 v[22:25], v[170:173], v[214:217], v[22:25]
	v_mfma_f32_16x16x32_bf16 v[18:21], v[178:181], v[214:217], v[18:21]
	v_mfma_f32_16x16x32_bf16 v[6:9], v[170:173], v[222:225], v[6:9]
	v_mfma_f32_16x16x32_bf16 v[2:5], v[178:181], v[222:225], v[2:5]
	s_barrier
; #define PG8_STAGE(bufoff, gbase, voff) do { _Pragma("unroll") for (int _i = 0; _i < 2; ++_i) \
;         __builtin_amdgcn_global_load_lds((const unsigned*)((const char*)(gbase) + (voff)[_i]), (LAS unsigned*)(lds + (bufoff) + ldsw + _i * 8192), 16, 0, 0); } while (0)
; #define PG8_LDA(dst, b, h) do { _Pragma("unroll") for (int m = 0; m < 4; ++m) _Pragma("unroll") for (int k = 0; k < 2; ++k) dst[m][k] = *(const LAS bf16x8*)(lds + PG8_SA(b, h) + aoff + m * 2048 + k * 1024); } while (0)
; #define PG8_LDB(dst, b, h) do { _Pragma("unroll") for (int n = 0; n < 2; ++n) _Pragma("unroll") for (int k = 0; k < 2; ++k) dst[n][k] = *(const LAS bf16x8*)(lds + PG8_SB(b, h) + boff + n * 2048 + k * 1024); } while (0)
; #define PG8_MMA(ai, bj, At, Bt) do { __builtin_amdgcn_s_setprio(1); _Pragma("unroll") for (int m = 0; m < 4; ++m) _Pragma("unroll") for (int n = 0; n < 2; ++n) _Pragma("unroll") for (int k = 0; k < 2; ++k) \
;         acc[ai][bj][m][n] = __builtin_amdgcn_mfma_f32_16x16x32_bf16(Bt[n][k], At[m][k], acc[ai][bj][m][n], 0, 0, 0); __builtin_amdgcn_s_setprio(0); } while (0)
; #define PG8_WAIT_V(n) asm volatile("s_waitcnt vmcnt(" #n ")" ::: "memory")
; #define PG8_WAIT_L(n) asm volatile("s_waitcnt lgkmcnt(" #n ")" ::: "memory")
; #define PG8_BAR __builtin_amdgcn_s_barrier()
; #define PG8_SCHED __builtin_amdgcn_sched_barrier(0)
; template <class Epi, class Sched, bool ALIGN_EPI = false, bool SP2 = false>
; __device__ __forceinline__ void gemm_phase(LAS unsigned char* lds, const Gemm g, const Sched& S, const Epi& E) {
;     ...
;             PG8_LDB(B0, 1, 0); PG8_LDB(B1, 1, 1); PG8_SCHED; PG8_LDA(At, 1, 0); PG8_STAGE(PG8_SA(0, 1), a2 + hstep, voffA);
;             PG8_WAIT_V(8); PG8_WAIT_L(0); PG8_BAR; PG8_MMA(0, 0, At, B0); PG8_MMA(0, 1, At, B1); PG8_BAR; PG8_SCHED;
;             PG8_LDA(At, 1, 1); PG8_STAGE(PG8_SB(1, 0), b3, voffB); PG8_STAGE(PG8_SB(1, 1), b3 + hstepB, voffB); PG8_STAGE(PG8_SA(1, 0), a3, voffA);
;             PG8_WAIT_V(8); PG8_WAIT_L(0); PG8_BAR; PG8_MMA(1, 0, At, B0); PG8_MMA(1, 1, At, B1); PG8_BAR; PG8_SCHED;
;     ...
;         if constexpr (ALIGN_EPI) { if (wr == 0) PG8_BAR; }
	s_add_i32 s54, 0, 0x18000
	s_add_i32 s55, 0, 0x1c000
	v_add_u32_e32 v142, s54, v1
	v_add_u32_e32 v154, s55, v1
	ds_read_b128 v[130:133], v142
	ds_read_b128 v[134:137], v142 offset:1024
	ds_read_b128 v[138:141], v142 offset:2048
	ds_read_b128 v[142:145], v142 offset:3072
	ds_read_b128 v[166:169], v154
	ds_read_b128 v[170:173], v154 offset:1024
	ds_read_b128 v[174:177], v154 offset:2048
	ds_read_b128 v[178:181], v154 offset:3072
	s_add_u32 s18, s46, 0x160000
	s_addc_u32 s19, s47, 0
	s_mov_b32 m0, s29
	ds_read_b128 v[182:185], v198 offset:32768
	ds_read_b128 v[186:189], v198 offset:33792
	ds_read_b128 v[202:205], v198 offset:34816
	ds_read_b128 v[206:209], v198 offset:35840
	ds_read_b128 v[210:213], v198 offset:36864
	ds_read_b128 v[214:217], v198 offset:37888
	ds_read_b128 v[218:221], v198 offset:38912
	ds_read_b128 v[222:225], v198 offset:39936
	global_load_lds_dwordx4 v146, s[18:19]
	s_mov_b32 m0, s30
	s_nop 0
	global_load_lds_dwordx4 v150, s[18:19]
	s_waitcnt vmcnt(8)
	s_waitcnt lgkmcnt(0)
	s_barrier
	s_waitcnt lgkmcnt(0)
	v_mfma_f32_16x16x32_bf16 v[126:129], v[130:133], v[182:185], v[126:129]
	v_mfma_f32_16x16x32_bf16 v[122:125], v[138:141], v[182:185], v[122:125]
	v_mfma_f32_16x16x32_bf16 v[110:113], v[130:133], v[202:205], v[110:113]
	v_mfma_f32_16x16x32_bf16 v[106:109], v[138:141], v[202:205], v[106:109]
	v_mfma_f32_16x16x32_bf16 v[94:97], v[130:133], v[210:213], v[94:97]
	v_mfma_f32_16x16x32_bf16 v[90:93], v[138:141], v[210:213], v[90:93]
	v_mfma_f32_16x16x32_bf16 v[78:81], v[130:133], v[218:221], v[78:81]
	v_mfma_f32_16x16x32_bf16 v[74:77], v[138:141], v[218:221], v[74:77]
	v_mfma_f32_16x16x32_bf16 v[126:129], v[134:137], v[186:189], v[126:129]
	v_mfma_f32_16x16x32_bf16 v[122:125], v[142:145], v[186:189], v[122:125]
	v_mfma_f32_16x16x32_bf16 v[110:113], v[134:137], v[206:209], v[110:113]
	v_mfma_f32_16x16x32_bf16 v[106:109], v[142:145], v[206:209], v[106:109]
	v_mfma_f32_16x16x32_bf16 v[94:97], v[134:137], v[214:217], v[94:97]
	v_mfma_f32_16x16x32_bf16 v[90:93], v[142:145], v[214:217], v[90:93]
	v_mfma_f32_16x16x32_bf16 v[78:81], v[134:137], v[222:225], v[78:81]
	v_mfma_f32_16x16x32_bf16 v[74:77], v[142:145], v[222:225], v[74:77]
	v_mfma_f32_16x16x32_bf16 v[118:121], v[166:169], v[182:185], v[118:121]
	v_mfma_f32_16x16x32_bf16 v[114:117], v[174:177], v[182:185], v[114:117]
	v_mfma_f32_16x16x32_bf16 v[102:105], v[166:169], v[202:205], v[102:105]
	v_mfma_f32_16x16x32_bf16 v[98:101], v[174:177], v[202:205], v[98:101]
	v_mfma_f32_16x16x32_bf16 v[86:89], v[166:169], v[210:213], v[86:89]
	v_mfma_f32_16x16x32_bf16 v[82:85], v[174:177], v[210:213], v[82:85]
	v_mfma_f32_16x16x32_bf16 v[70:73], v[166:169], v[218:221], v[70:73]
	v_mfma_f32_16x16x32_bf16 v[66:69], v[174:177], v[218:221], v[66:69]
	v_mfma_f32_16x16x32_bf16 v[118:121], v[170:173], v[186:189], v[118:121]
	v_mfma_f32_16x16x32_bf16 v[114:117], v[178:181], v[186:189], v[114:117]
	v_mfma_f32_16x16x32_bf16 v[102:105], v[170:173], v[206:209], v[102:105]
	v_mfma_f32_16x16x32_bf16 v[98:101], v[178:181], v[206:209], v[98:101]
	v_mfma_f32_16x16x32_bf16 v[86:89], v[170:173], v[214:217], v[86:89]
	v_mfma_f32_16x16x32_bf16 v[82:85], v[178:181], v[214:217], v[82:85]
	v_mfma_f32_16x16x32_bf16 v[70:73], v[170:173], v[222:225], v[70:73]
	v_mfma_f32_16x16x32_bf16 v[66:69], v[178:181], v[222:225], v[66:69]
	s_barrier
	s_add_u32 s98, s22, 0x80
	s_addc_u32 s99, s23, 0
	s_add_u32 s100, s46, 0x80
	s_addc_u32 s101, s47, 0
	s_add_i32 s18, s54, s26
	s_mov_b32 m0, s18
	ds_read_b128 v[182:185], v198 offset:49152
	ds_read_b128 v[186:189], v198 offset:50176
	ds_read_b128 v[202:205], v198 offset:51200
	ds_read_b128 v[206:209], v198 offset:52224
	ds_read_b128 v[210:213], v198 offset:53248
	ds_read_b128 v[214:217], v198 offset:54272
	ds_read_b128 v[218:221], v198 offset:55296
	ds_read_b128 v[222:225], v198 offset:56320
	global_load_lds_dwordx4 v148, s[98:99]
	s_add_i32 m0, s18, 0x2000
	s_add_u32 s18, s22, 0x58080
	v_lshl_add_u64 v[190:191], v[226:227], 0, s[12:13]
	s_addc_u32 s19, s23, 0
	s_add_i32 s22, s55, s26
	global_load_lds_dwordx4 v[190:191], off
	s_mov_b32 m0, s22
	s_nop 0
	global_load_lds_dwordx4 v148, s[18:19]
	s_add_i32 m0, s22, 0x2000
	s_nop 0
	global_load_lds_dwordx4 v152, s[18:19]
	s_mov_b32 m0, s37
	s_nop 0
	global_load_lds_dwordx4 v146, s[100:101]
	s_mov_b32 m0, s48
	s_nop 0
	global_load_lds_dwordx4 v150, s[100:101]
	s_waitcnt vmcnt(8)
	s_waitcnt lgkmcnt(0)
	s_barrier
	s_waitcnt lgkmcnt(0)
	v_mfma_f32_16x16x32_bf16 v[62:65], v[130:133], v[182:185], v[62:65]
	v_mfma_f32_16x16x32_bf16 v[58:61], v[138:141], v[182:185], v[58:61]
	v_mfma_f32_16x16x32_bf16 v[46:49], v[130:133], v[202:205], v[46:49]
	v_mfma_f32_16x16x32_bf16 v[42:45], v[138:141], v[202:205], v[42:45]
	v_mfma_f32_16x16x32_bf16 v[30:33], v[130:133], v[210:213], v[30:33]
	v_mfma_f32_16x16x32_bf16 v[26:29], v[138:141], v[210:213], v[26:29]
	v_mfma_f32_16x16x32_bf16 v[14:17], v[130:133], v[218:221], v[14:17]
	v_mfma_f32_16x16x32_bf16 v[10:13], v[138:141], v[218:221], v[10:13]
	v_mfma_f32_16x16x32_bf16 v[62:65], v[134:137], v[186:189], v[62:65]
	v_mfma_f32_16x16x32_bf16 v[58:61], v[142:145], v[186:189], v[58:61]
	v_mfma_f32_16x16x32_bf16 v[46:49], v[134:137], v[206:209], v[46:49]
	v_mfma_f32_16x16x32_bf16 v[42:45], v[142:145], v[206:209], v[42:45]
	v_mfma_f32_16x16x32_bf16 v[30:33], v[134:137], v[214:217], v[30:33]
	v_mfma_f32_16x16x32_bf16 v[26:29], v[142:145], v[214:217], v[26:29]
	v_mfma_f32_16x16x32_bf16 v[14:17], v[134:137], v[222:225], v[14:17]
	v_mfma_f32_16x16x32_bf16 v[10:13], v[142:145], v[222:225], v[10:13]
	v_mfma_f32_16x16x32_bf16 v[54:57], v[166:169], v[182:185], v[54:57]
	v_mfma_f32_16x16x32_bf16 v[50:53], v[174:177], v[182:185], v[50:53]
	v_mfma_f32_16x16x32_bf16 v[38:41], v[166:169], v[202:205], v[38:41]
	v_mfma_f32_16x16x32_bf16 v[34:37], v[174:177], v[202:205], v[34:37]
	v_mfma_f32_16x16x32_bf16 v[22:25], v[166:169], v[210:213], v[22:25]
	v_mfma_f32_16x16x32_bf16 v[18:21], v[174:177], v[210:213], v[18:21]
	v_mfma_f32_16x16x32_bf16 v[6:9], v[166:169], v[218:221], v[6:9]
	v_mfma_f32_16x16x32_bf16 v[2:5], v[174:177], v[218:221], v[2:5]
	v_mfma_f32_16x16x32_bf16 v[54:57], v[170:173], v[186:189], v[54:57]
	v_mfma_f32_16x16x32_bf16 v[50:53], v[178:181], v[186:189], v[50:53]
	v_mfma_f32_16x16x32_bf16 v[38:41], v[170:173], v[206:209], v[38:41]
	v_mfma_f32_16x16x32_bf16 v[34:37], v[178:181], v[206:209], v[34:37]
	v_mfma_f32_16x16x32_bf16 v[22:25], v[170:173], v[214:217], v[22:25]
	v_mfma_f32_16x16x32_bf16 v[18:21], v[178:181], v[214:217], v[18:21]
	v_mfma_f32_16x16x32_bf16 v[6:9], v[170:173], v[222:225], v[6:9]
	v_mfma_f32_16x16x32_bf16 v[2:5], v[178:181], v[222:225], v[2:5]
	s_barrier
	s_add_i32 s25, s25, 2
	s_add_u32 s5, s5, 0x100
	s_addc_u32 s24, s24, 0
	s_cmpk_lt_u32 s25, 0x56
	s_mov_b64 s[18:19], s[20:21]
	s_cbranch_scc1 .LBB0_1926
	s_setprio 0
	s_andn2_b64 vcc, exec, s[14:15]
	s_cbranch_vccnz .LBB0_1929
	s_barrier

; #define PG8_STAGE(bufoff, gbase, voff) do { _Pragma("unroll") for (int _i = 0; _i < 2; ++_i) \
;         __builtin_amdgcn_global_load_lds((const unsigned*)((const char*)(gbase) + (voff)[_i]), (LAS unsigned*)(lds + (bufoff) + ldsw + _i * 8192), 16, 0, 0); } while (0)
; #define PG8_LDA(dst, b, h) do { _Pragma("unroll") for (int m = 0; m < 4; ++m) _Pragma("unroll") for (int k = 0; k < 2; ++k) dst[m][k] = *(const LAS bf16x8*)(lds + PG8_SA(b, h) + aoff + m * 2048 + k * 1024); } while (0)
; #define PG8_LDB(dst, b, h) do { _Pragma("unroll") for (int n = 0; n < 2; ++n) _Pragma("unroll") for (int k = 0; k < 2; ++k) dst[n][k] = *(const LAS bf16x8*)(lds + PG8_SB(b, h) + boff + n * 2048 + k * 1024); } while (0)
; #define PG8_MMA(ai, bj, At, Bt) do { __builtin_amdgcn_s_setprio(1); _Pragma("unroll") for (int m = 0; m < 4; ++m) _Pragma("unroll") for (int n = 0; n < 2; ++n) _Pragma("unroll") for (int k = 0; k < 2; ++k) \
;         acc[ai][bj][m][n] = __builtin_amdgcn_mfma_f32_16x16x32_bf16(Bt[n][k], At[m][k], acc[ai][bj][m][n], 0, 0, 0); __builtin_amdgcn_s_setprio(0); } while (0)
; #define PG8_WAIT_V(n) asm volatile("s_waitcnt vmcnt(" #n ")" ::: "memory")
; #define PG8_WAIT_L(n) asm volatile("s_waitcnt lgkmcnt(" #n ")" ::: "memory")
; #define PG8_BAR __builtin_amdgcn_s_barrier()
; #define PG8_SCHED __builtin_amdgcn_sched_barrier(0)
; template <class Epi, class Sched, bool ALIGN_EPI = false, bool SP2 = false>
; __device__ __forceinline__ void gemm_phase(LAS unsigned char* lds, const Gemm g, const Sched& S, const Epi& E) {
;     ...
;             PG8_LDB(B0, 0, 0); PG8_LDB(B1, 0, 1); PG8_SCHED; PG8_LDA(At, 0, 0); PG8_STAGE(PG8_SA(1, 1), a1 + hstep, voffA);
;             PG8_WAIT_V(8); PG8_WAIT_L(0); PG8_BAR; PG8_MMA(0, 0, At, B0); PG8_MMA(0, 1, At, B1); PG8_BAR; PG8_SCHED;
;             PG8_LDA(At, 0, 1); PG8_STAGE(PG8_SB(0, 0), b2, voffB); PG8_STAGE(PG8_SB(0, 1), b2 + hstepB, voffB); PG8_STAGE(PG8_SA(0, 0), a2, voffA);
;             PG8_WAIT_V(8); PG8_WAIT_L(0); PG8_BAR; PG8_MMA(1, 0, At, B0); PG8_MMA(1, 1, At, B1); PG8_BAR; PG8_SCHED;
.Lprio_3002:
	ds_read_b128 v[152:155], v147
	ds_read_b128 v[156:159], v147 offset:1024
	ds_read_b128 v[160:163], v147 offset:2048
	ds_read_b128 v[164:167], v147 offset:3072
	ds_read_b128 v[168:171], v148
	ds_read_b128 v[172:175], v148 offset:1024
	ds_read_b128 v[176:179], v148 offset:2048
	ds_read_b128 v[180:183], v148 offset:3072
	s_add_u32 s16, s14, 0x100
	s_addc_u32 s17, s15, 0
	s_cmpk_eq_i32 s40, 0x54
	s_cselect_b32 s21, s11, s17
	s_cselect_b32 s20, s10, s16
	s_cselect_b32 s19, s3, s39
	s_cselect_b32 s18, s2, s13
	v_lshl_add_u64 v[216:217], s[14:15], 0, v[138:139]
	s_add_i32 m0, s24, 0xc000
	ds_read_b128 v[184:187], v149
	ds_read_b128 v[188:191], v149 offset:1024
	ds_read_b128 v[192:195], v149 offset:2048
	ds_read_b128 v[196:199], v149 offset:3072
	ds_read_b128 v[200:203], v149 offset:4096
	ds_read_b128 v[204:207], v149 offset:5120
	ds_read_b128 v[208:211], v149 offset:6144
	ds_read_b128 v[212:215], v149 offset:7168
	global_load_lds_dwordx4 v[216:217], off
	v_lshl_add_u64 v[216:217], s[14:15], 0, v[136:137]
	s_add_i32 m0, s24, 0xe000
	s_nop 0
	global_load_lds_dwordx4 v[216:217], off
	s_waitcnt lgkmcnt(0)
	s_barrier
	s_waitcnt lgkmcnt(0)
	v_mfma_f32_16x16x32_bf16 v[124:127], v[152:155], v[184:187], 0
	v_mfma_f32_16x16x32_bf16 v[120:123], v[160:163], v[184:187], 0
	v_mfma_f32_16x16x32_bf16 v[112:115], v[152:155], v[192:195], 0
	v_mfma_f32_16x16x32_bf16 v[104:107], v[160:163], v[192:195], 0
	v_mfma_f32_16x16x32_bf16 v[92:95], v[152:155], v[200:203], 0
	v_mfma_f32_16x16x32_bf16 v[88:91], v[160:163], v[200:203], 0
	v_mfma_f32_16x16x32_bf16 v[76:79], v[152:155], v[208:211], 0
	v_mfma_f32_16x16x32_bf16 v[72:75], v[160:163], v[208:211], 0
	v_mfma_f32_16x16x32_bf16 v[124:127], v[156:159], v[188:191], v[124:127]
	v_mfma_f32_16x16x32_bf16 v[120:123], v[164:167], v[188:191], v[120:123]
	v_mfma_f32_16x16x32_bf16 v[112:115], v[156:159], v[196:199], v[112:115]
	v_mfma_f32_16x16x32_bf16 v[104:107], v[164:167], v[196:199], v[104:107]
	v_mfma_f32_16x16x32_bf16 v[92:95], v[156:159], v[204:207], v[92:95]
	v_mfma_f32_16x16x32_bf16 v[88:91], v[164:167], v[204:207], v[88:91]
	v_mfma_f32_16x16x32_bf16 v[76:79], v[156:159], v[212:215], v[76:79]
	v_mfma_f32_16x16x32_bf16 v[72:75], v[164:167], v[212:215], v[72:75]
	v_mfma_f32_16x16x32_bf16 v[116:119], v[168:171], v[184:187], 0
	v_mfma_f32_16x16x32_bf16 v[108:111], v[176:179], v[184:187], 0
	v_mfma_f32_16x16x32_bf16 v[100:103], v[168:171], v[192:195], 0
	v_mfma_f32_16x16x32_bf16 v[96:99], v[176:179], v[192:195], 0
	v_mfma_f32_16x16x32_bf16 v[84:87], v[168:171], v[200:203], 0
	v_mfma_f32_16x16x32_bf16 v[80:83], v[176:179], v[200:203], 0
	v_mfma_f32_16x16x32_bf16 v[68:71], v[168:171], v[208:211], 0
	v_mfma_f32_16x16x32_bf16 v[64:67], v[176:179], v[208:211], 0
	v_mfma_f32_16x16x32_bf16 v[116:119], v[172:175], v[188:191], v[116:119]
	v_mfma_f32_16x16x32_bf16 v[108:111], v[180:183], v[188:191], v[108:111]
	v_mfma_f32_16x16x32_bf16 v[100:103], v[172:175], v[196:199], v[100:103]
	v_mfma_f32_16x16x32_bf16 v[96:99], v[180:183], v[196:199], v[96:99]
	v_mfma_f32_16x16x32_bf16 v[84:87], v[172:175], v[204:207], v[84:87]
	v_mfma_f32_16x16x32_bf16 v[80:83], v[180:183], v[204:207], v[80:83]
	v_mfma_f32_16x16x32_bf16 v[68:71], v[172:175], v[212:215], v[68:71]
	v_mfma_f32_16x16x32_bf16 v[64:67], v[180:183], v[212:215], v[64:67]
	s_barrier
	s_add_i32 s14, s34, s23
	s_mov_b32 m0, s14
	ds_read_b128 v[184:187], v149 offset:16384
	ds_read_b128 v[188:191], v149 offset:17408
	ds_read_b128 v[192:195], v149 offset:18432
	ds_read_b128 v[196:199], v149 offset:19456
	ds_read_b128 v[200:203], v149 offset:20480
	ds_read_b128 v[204:207], v149 offset:21504
	ds_read_b128 v[208:211], v149 offset:22528
	ds_read_b128 v[212:215], v149 offset:23552
	global_load_lds_dwordx4 v130, s[18:19]
	s_add_i32 m0, s14, 0x2000
	s_add_u32 s14, s18, 0x58000
	v_lshl_add_u64 v[218:219], s[18:19], 0, v[134:135]
	s_addc_u32 s15, s19, 0
	s_add_i32 s41, s35, s23
	global_load_lds_dwordx4 v134, s[18:19]
	s_mov_b32 m0, s41
	s_nop 0
	global_load_lds_dwordx4 v130, s[14:15]
	s_add_i32 m0, s41, 0x2000
	s_nop 0
	global_load_lds_dwordx4 v134, s[14:15]
	s_mov_b32 m0, s24
	s_nop 0
	global_load_lds_dwordx4 v128, s[20:21]
	s_mov_b32 m0, s25
	s_nop 0
	global_load_lds_dwordx4 v132, s[20:21]
	s_waitcnt lgkmcnt(0)
	s_barrier
	s_waitcnt lgkmcnt(0)
	v_mfma_f32_16x16x32_bf16 v[60:63], v[152:155], v[184:187], 0
	v_mfma_f32_16x16x32_bf16 v[56:59], v[160:163], v[184:187], 0
	v_mfma_f32_16x16x32_bf16 v[44:47], v[152:155], v[192:195], 0
	v_mfma_f32_16x16x32_bf16 v[40:43], v[160:163], v[192:195], 0
	v_mfma_f32_16x16x32_bf16 v[28:31], v[152:155], v[200:203], 0
	v_mfma_f32_16x16x32_bf16 v[24:27], v[160:163], v[200:203], 0
	v_mfma_f32_16x16x32_bf16 v[12:15], v[152:155], v[208:211], 0
	v_mfma_f32_16x16x32_bf16 v[8:11], v[160:163], v[208:211], 0
	v_mfma_f32_16x16x32_bf16 v[60:63], v[156:159], v[188:191], v[60:63]
	v_mfma_f32_16x16x32_bf16 v[56:59], v[164:167], v[188:191], v[56:59]
	v_mfma_f32_16x16x32_bf16 v[44:47], v[156:159], v[196:199], v[44:47]
	v_mfma_f32_16x16x32_bf16 v[40:43], v[164:167], v[196:199], v[40:43]
	v_mfma_f32_16x16x32_bf16 v[28:31], v[156:159], v[204:207], v[28:31]
	v_mfma_f32_16x16x32_bf16 v[24:27], v[164:167], v[204:207], v[24:27]
	v_mfma_f32_16x16x32_bf16 v[12:15], v[156:159], v[212:215], v[12:15]
	v_mfma_f32_16x16x32_bf16 v[8:11], v[164:167], v[212:215], v[8:11]
	v_mfma_f32_16x16x32_bf16 v[52:55], v[168:171], v[184:187], 0
	v_mfma_f32_16x16x32_bf16 v[48:51], v[176:179], v[184:187], 0
	v_mfma_f32_16x16x32_bf16 v[36:39], v[168:171], v[192:195], 0
	v_mfma_f32_16x16x32_bf16 v[32:35], v[176:179], v[192:195], 0
	v_mfma_f32_16x16x32_bf16 v[20:23], v[168:171], v[200:203], 0
	v_mfma_f32_16x16x32_bf16 v[16:19], v[176:179], v[200:203], 0
	v_mfma_f32_16x16x32_bf16 v[4:7], v[168:171], v[208:211], 0
	v_mfma_f32_16x16x32_bf16 v[0:3], v[176:179], v[208:211], 0
	v_mfma_f32_16x16x32_bf16 v[52:55], v[172:175], v[188:191], v[52:55]
	v_mfma_f32_16x16x32_bf16 v[48:51], v[180:183], v[188:191], v[48:51]
	v_mfma_f32_16x16x32_bf16 v[36:39], v[172:175], v[196:199], v[36:39]
	v_mfma_f32_16x16x32_bf16 v[32:35], v[180:183], v[196:199], v[32:35]
	v_mfma_f32_16x16x32_bf16 v[20:23], v[172:175], v[204:207], v[20:23]
	v_mfma_f32_16x16x32_bf16 v[16:19], v[180:183], v[204:207], v[16:19]
	v_mfma_f32_16x16x32_bf16 v[4:7], v[172:175], v[212:215], v[4:7]
	v_mfma_f32_16x16x32_bf16 v[0:3], v[180:183], v[212:215], v[0:3]
	s_barrier
; #define PG8_STAGE(bufoff, gbase, voff) do { _Pragma("unroll") for (int _i = 0; _i < 2; ++_i) \
;         __builtin_amdgcn_global_load_lds((const unsigned*)((const char*)(gbase) + (voff)[_i]), (LAS unsigned*)(lds + (bufoff) + ldsw + _i * 8192), 16, 0, 0); } while (0)
; #define PG8_LDA(dst, b, h) do { _Pragma("unroll") for (int m = 0; m < 4; ++m) _Pragma("unroll") for (int k = 0; k < 2; ++k) dst[m][k] = *(const LAS bf16x8*)(lds + PG8_SA(b, h) + aoff + m * 2048 + k * 1024); } while (0)
; #define PG8_LDB(dst, b, h) do { _Pragma("unroll") for (int n = 0; n < 2; ++n) _Pragma("unroll") for (int k = 0; k < 2; ++k) dst[n][k] = *(const LAS bf16x8*)(lds + PG8_SB(b, h) + boff + n * 2048 + k * 1024); } while (0)
; #define PG8_MMA(ai, bj, At, Bt) do { __builtin_amdgcn_s_setprio(1); _Pragma("unroll") for (int m = 0; m < 4; ++m) _Pragma("unroll") for (int n = 0; n < 2; ++n) _Pragma("unroll") for (int k = 0; k < 2; ++k) \
;         acc[ai][bj][m][n] = __builtin_amdgcn_mfma_f32_16x16x32_bf16(Bt[n][k], At[m][k], acc[ai][bj][m][n], 0, 0, 0); __builtin_amdgcn_s_setprio(0); } while (0)
; #define PG8_WAIT_V(n) asm volatile("s_waitcnt vmcnt(" #n ")" ::: "memory")
; #define PG8_WAIT_L(n) asm volatile("s_waitcnt lgkmcnt(" #n ")" ::: "memory")
; #define PG8_BAR __builtin_amdgcn_s_barrier()
; #define PG8_SCHED __builtin_amdgcn_sched_barrier(0)
; template <class Epi, class Sched, bool ALIGN_EPI = false, bool SP2 = false>
; __device__ __forceinline__ void gemm_phase(LAS unsigned char* lds, const Gemm g, const Sched& S, const Epi& E) {
;     ...
;             PG8_LDB(B0, 1, 0); PG8_LDB(B1, 1, 1); PG8_SCHED; PG8_LDA(At, 1, 0); PG8_STAGE(PG8_SA(0, 1), a2 + hstep, voffA);
;             PG8_WAIT_V(8); PG8_WAIT_L(0); PG8_BAR; PG8_MMA(0, 0, At, B0); PG8_MMA(0, 1, At, B1); PG8_BAR; PG8_SCHED;
;             PG8_LDA(At, 1, 1); PG8_STAGE(PG8_SB(1, 0), b3, voffB); PG8_STAGE(PG8_SB(1, 1), b3 + hstepB, voffB); PG8_STAGE(PG8_SA(1, 0), a3, voffA);
;             PG8_WAIT_V(8); PG8_WAIT_L(0); PG8_BAR; PG8_MMA(1, 0, At, B0); PG8_MMA(1, 1, At, B1); PG8_BAR; PG8_SCHED;
	s_add_i32 s41, 0, 0x18000
	s_add_i32 s42, 0, 0x1c000
	v_add_u32_e32 v164, s41, v144
	v_add_u32_e32 v180, s42, v144
	ds_read_b128 v[152:155], v164
	ds_read_b128 v[156:159], v164 offset:1024
	ds_read_b128 v[160:163], v164 offset:2048
	ds_read_b128 v[164:167], v164 offset:3072
	ds_read_b128 v[168:171], v180
	ds_read_b128 v[172:175], v180 offset:1024
	ds_read_b128 v[176:179], v180 offset:2048
	ds_read_b128 v[180:183], v180 offset:3072
	s_add_u32 s14, s20, 0x160000
	s_addc_u32 s15, s21, 0
	s_mov_b32 m0, s26
	ds_read_b128 v[184:187], v149 offset:32768
	ds_read_b128 v[188:191], v149 offset:33792
	ds_read_b128 v[192:195], v149 offset:34816
	ds_read_b128 v[196:199], v149 offset:35840
	ds_read_b128 v[200:203], v149 offset:36864
	ds_read_b128 v[204:207], v149 offset:37888
	ds_read_b128 v[208:211], v149 offset:38912
	ds_read_b128 v[212:215], v149 offset:39936
	global_load_lds_dwordx4 v128, s[14:15]
	s_mov_b32 m0, s27
	s_nop 0
	global_load_lds_dwordx4 v132, s[14:15]
	s_waitcnt vmcnt(8)
	s_waitcnt lgkmcnt(0)
	s_barrier
	s_waitcnt lgkmcnt(0)
	v_mfma_f32_16x16x32_bf16 v[124:127], v[152:155], v[184:187], v[124:127]
	v_mfma_f32_16x16x32_bf16 v[120:123], v[160:163], v[184:187], v[120:123]
	v_mfma_f32_16x16x32_bf16 v[112:115], v[152:155], v[192:195], v[112:115]
	v_mfma_f32_16x16x32_bf16 v[104:107], v[160:163], v[192:195], v[104:107]
	v_mfma_f32_16x16x32_bf16 v[92:95], v[152:155], v[200:203], v[92:95]
	v_mfma_f32_16x16x32_bf16 v[88:91], v[160:163], v[200:203], v[88:91]
	v_mfma_f32_16x16x32_bf16 v[76:79], v[152:155], v[208:211], v[76:79]
	v_mfma_f32_16x16x32_bf16 v[72:75], v[160:163], v[208:211], v[72:75]
	v_mfma_f32_16x16x32_bf16 v[124:127], v[156:159], v[188:191], v[124:127]
	v_mfma_f32_16x16x32_bf16 v[120:123], v[164:167], v[188:191], v[120:123]
	v_mfma_f32_16x16x32_bf16 v[112:115], v[156:159], v[196:199], v[112:115]
	v_mfma_f32_16x16x32_bf16 v[104:107], v[164:167], v[196:199], v[104:107]
	v_mfma_f32_16x16x32_bf16 v[92:95], v[156:159], v[204:207], v[92:95]
	v_mfma_f32_16x16x32_bf16 v[88:91], v[164:167], v[204:207], v[88:91]
	v_mfma_f32_16x16x32_bf16 v[76:79], v[156:159], v[212:215], v[76:79]
	v_mfma_f32_16x16x32_bf16 v[72:75], v[164:167], v[212:215], v[72:75]
	v_mfma_f32_16x16x32_bf16 v[116:119], v[168:171], v[184:187], v[116:119]
	v_mfma_f32_16x16x32_bf16 v[108:111], v[176:179], v[184:187], v[108:111]
	v_mfma_f32_16x16x32_bf16 v[100:103], v[168:171], v[192:195], v[100:103]
	v_mfma_f32_16x16x32_bf16 v[96:99], v[176:179], v[192:195], v[96:99]
	v_mfma_f32_16x16x32_bf16 v[84:87], v[168:171], v[200:203], v[84:87]
	v_mfma_f32_16x16x32_bf16 v[80:83], v[176:179], v[200:203], v[80:83]
	v_mfma_f32_16x16x32_bf16 v[68:71], v[168:171], v[208:211], v[68:71]
	v_mfma_f32_16x16x32_bf16 v[64:67], v[176:179], v[208:211], v[64:67]
	v_mfma_f32_16x16x32_bf16 v[116:119], v[172:175], v[188:191], v[116:119]
	v_mfma_f32_16x16x32_bf16 v[108:111], v[180:183], v[188:191], v[108:111]
	v_mfma_f32_16x16x32_bf16 v[100:103], v[172:175], v[196:199], v[100:103]
	v_mfma_f32_16x16x32_bf16 v[96:99], v[180:183], v[196:199], v[96:99]
	v_mfma_f32_16x16x32_bf16 v[84:87], v[172:175], v[204:207], v[84:87]
	v_mfma_f32_16x16x32_bf16 v[80:83], v[180:183], v[204:207], v[80:83]
	v_mfma_f32_16x16x32_bf16 v[68:71], v[172:175], v[212:215], v[68:71]
	v_mfma_f32_16x16x32_bf16 v[64:67], v[180:183], v[212:215], v[64:67]
	s_barrier
	s_add_u32 s98, s18, 0x80
	s_addc_u32 s99, s19, 0
	s_add_u32 s100, s20, 0x80
	s_addc_u32 s101, s21, 0
	s_add_i32 s14, s41, s23
	s_mov_b32 m0, s14
	ds_read_b128 v[184:187], v149 offset:49152
	ds_read_b128 v[188:191], v149 offset:50176
	ds_read_b128 v[192:195], v149 offset:51200
	ds_read_b128 v[196:199], v149 offset:52224
	ds_read_b128 v[200:203], v149 offset:53248
	ds_read_b128 v[204:207], v149 offset:54272
	ds_read_b128 v[208:211], v149 offset:55296
	ds_read_b128 v[212:215], v149 offset:56320
	global_load_lds_dwordx4 v130, s[98:99]
	s_add_i32 m0, s14, 0x2000
	s_add_u32 s14, s18, 0x58080
	v_lshl_add_u64 v[216:217], v[218:219], 0, s[6:7]
	s_addc_u32 s15, s19, 0
	s_add_i32 s18, s42, s23
	global_load_lds_dwordx4 v[216:217], off
	s_mov_b32 m0, s18
	s_nop 0
	global_load_lds_dwordx4 v130, s[14:15]
	s_add_i32 m0, s18, 0x2000
	s_nop 0
	global_load_lds_dwordx4 v134, s[14:15]
	s_mov_b32 m0, s31
	s_nop 0
	global_load_lds_dwordx4 v128, s[100:101]
	s_mov_b32 m0, s33
	s_nop 0
	global_load_lds_dwordx4 v132, s[100:101]
	s_waitcnt vmcnt(8)
	s_waitcnt lgkmcnt(0)
	s_barrier
	s_waitcnt lgkmcnt(0)
	v_mfma_f32_16x16x32_bf16 v[60:63], v[152:155], v[184:187], v[60:63]
	v_mfma_f32_16x16x32_bf16 v[56:59], v[160:163], v[184:187], v[56:59]
	v_mfma_f32_16x16x32_bf16 v[44:47], v[152:155], v[192:195], v[44:47]
	v_mfma_f32_16x16x32_bf16 v[40:43], v[160:163], v[192:195], v[40:43]
	v_mfma_f32_16x16x32_bf16 v[28:31], v[152:155], v[200:203], v[28:31]
	v_mfma_f32_16x16x32_bf16 v[24:27], v[160:163], v[200:203], v[24:27]
	v_mfma_f32_16x16x32_bf16 v[12:15], v[152:155], v[208:211], v[12:15]
	v_mfma_f32_16x16x32_bf16 v[8:11], v[160:163], v[208:211], v[8:11]
	v_mfma_f32_16x16x32_bf16 v[60:63], v[156:159], v[188:191], v[60:63]
	v_mfma_f32_16x16x32_bf16 v[56:59], v[164:167], v[188:191], v[56:59]
	v_mfma_f32_16x16x32_bf16 v[44:47], v[156:159], v[196:199], v[44:47]
	v_mfma_f32_16x16x32_bf16 v[40:43], v[164:167], v[196:199], v[40:43]
	v_mfma_f32_16x16x32_bf16 v[28:31], v[156:159], v[204:207], v[28:31]
	v_mfma_f32_16x16x32_bf16 v[24:27], v[164:167], v[204:207], v[24:27]
	v_mfma_f32_16x16x32_bf16 v[12:15], v[156:159], v[212:215], v[12:15]
	v_mfma_f32_16x16x32_bf16 v[8:11], v[164:167], v[212:215], v[8:11]
	v_mfma_f32_16x16x32_bf16 v[52:55], v[168:171], v[184:187], v[52:55]
	v_mfma_f32_16x16x32_bf16 v[48:51], v[176:179], v[184:187], v[48:51]
	v_mfma_f32_16x16x32_bf16 v[36:39], v[168:171], v[192:195], v[36:39]
	v_mfma_f32_16x16x32_bf16 v[32:35], v[176:179], v[192:195], v[32:35]
	v_mfma_f32_16x16x32_bf16 v[20:23], v[168:171], v[200:203], v[20:23]
	v_mfma_f32_16x16x32_bf16 v[16:19], v[176:179], v[200:203], v[16:19]
	v_mfma_f32_16x16x32_bf16 v[4:7], v[168:171], v[208:211], v[4:7]
	v_mfma_f32_16x16x32_bf16 v[0:3], v[176:179], v[208:211], v[0:3]
	v_mfma_f32_16x16x32_bf16 v[52:55], v[172:175], v[188:191], v[52:55]
	v_mfma_f32_16x16x32_bf16 v[48:51], v[180:183], v[188:191], v[48:51]
	v_mfma_f32_16x16x32_bf16 v[36:39], v[172:175], v[196:199], v[36:39]
	v_mfma_f32_16x16x32_bf16 v[32:35], v[180:183], v[196:199], v[32:35]
	v_mfma_f32_16x16x32_bf16 v[20:23], v[172:175], v[204:207], v[20:23]
	v_mfma_f32_16x16x32_bf16 v[16:19], v[180:183], v[204:207], v[16:19]
	v_mfma_f32_16x16x32_bf16 v[4:7], v[172:175], v[212:215], v[4:7]
	v_mfma_f32_16x16x32_bf16 v[0:3], v[180:183], v[212:215], v[0:3]
	s_barrier
	s_add_i32 s40, s40, 2
	s_add_u32 s13, s13, 0x100
	s_addc_u32 s39, s39, 0
	s_cmpk_lt_u32 s40, 0x56
	s_mov_b64 s[14:15], s[16:17]
; #define PG8_STAGE(bufoff, gbase, voff) do { _Pragma("unroll") for (int _i = 0; _i < 2; ++_i) \
;         __builtin_amdgcn_global_load_lds((const unsigned*)((const char*)(gbase) + (voff)[_i]), (LAS unsigned*)(lds + (bufoff) + ldsw + _i * 8192), 16, 0, 0); } while (0)
; #define PG8_LDA(dst, b, h) do { _Pragma("unroll") for (int m = 0; m < 4; ++m) _Pragma("unroll") for (int k = 0; k < 2; ++k) dst[m][k] = *(const LAS bf16x8*)(lds + PG8_SA(b, h) + aoff + m * 2048 + k * 1024); } while (0)
; #define PG8_LDB(dst, b, h) do { _Pragma("unroll") for (int n = 0; n < 2; ++n) _Pragma("unroll") for (int k = 0; k < 2; ++k) dst[n][k] = *(const LAS bf16x8*)(lds + PG8_SB(b, h) + boff + n * 2048 + k * 1024); } while (0)
; #define PG8_MMA(ai, bj, At, Bt) do { __builtin_amdgcn_s_setprio(1); _Pragma("unroll") for (int m = 0; m < 4; ++m) _Pragma("unroll") for (int n = 0; n < 2; ++n) _Pragma("unroll") for (int k = 0; k < 2; ++k) \
;         acc[ai][bj][m][n] = __builtin_amdgcn_mfma_f32_16x16x32_bf16(Bt[n][k], At[m][k], acc[ai][bj][m][n], 0, 0, 0); __builtin_amdgcn_s_setprio(0); } while (0)
; #define PG8_WAIT_V(n) asm volatile("s_waitcnt vmcnt(" #n ")" ::: "memory")
; #define PG8_WAIT_L(n) asm volatile("s_waitcnt lgkmcnt(" #n ")" ::: "memory")
; #define PG8_BAR __builtin_amdgcn_s_barrier()
; #define PG8_SCHED __builtin_amdgcn_sched_barrier(0)
; template <class Epi, class Sched, bool ALIGN_EPI = false, bool SP2 = false>
; __device__ __forceinline__ void gemm_phase(LAS unsigned char* lds, const Gemm g, const Sched& S, const Epi& E) {
;     ...
;             PG8_LDB(B0, 0, 0); PG8_LDB(B1, 0, 1); PG8_SCHED; PG8_LDA(At, 0, 0); PG8_STAGE(PG8_SA(1, 1), a1 + hstep, voffA);
;             PG8_WAIT_V(8); PG8_WAIT_L(0); PG8_BAR; PG8_MMA(0, 0, At, B0); PG8_MMA(0, 1, At, B1); PG8_BAR; PG8_SCHED;
;             PG8_LDA(At, 0, 1); PG8_STAGE(PG8_SB(0, 0), b2, voffB); PG8_STAGE(PG8_SB(0, 1), b2 + hstepB, voffB); PG8_STAGE(PG8_SA(0, 0), a2, voffA);
;             PG8_WAIT_V(8); PG8_WAIT_L(0); PG8_BAR; PG8_MMA(1, 0, At, B0); PG8_MMA(1, 1, At, B1); PG8_BAR; PG8_SCHED;
.LBB0_3002:
	ds_read_b128 v[152:155], v147
	ds_read_b128 v[156:159], v147 offset:1024
	ds_read_b128 v[160:163], v147 offset:2048
	ds_read_b128 v[164:167], v147 offset:3072
	ds_read_b128 v[168:171], v148
	ds_read_b128 v[172:175], v148 offset:1024
	ds_read_b128 v[176:179], v148 offset:2048
	ds_read_b128 v[180:183], v148 offset:3072
	s_add_u32 s16, s14, 0x100
	s_addc_u32 s17, s15, 0
	s_cmpk_eq_i32 s40, 0x54
	s_cselect_b32 s21, s11, s17
	s_cselect_b32 s20, s10, s16
	s_cselect_b32 s19, s3, s39
	s_cselect_b32 s18, s2, s13
	v_lshl_add_u64 v[216:217], s[14:15], 0, v[138:139]
	s_add_i32 m0, s24, 0xc000
	ds_read_b128 v[184:187], v149
	ds_read_b128 v[188:191], v149 offset:1024
	ds_read_b128 v[192:195], v149 offset:2048
	ds_read_b128 v[196:199], v149 offset:3072
	ds_read_b128 v[200:203], v149 offset:4096
	ds_read_b128 v[204:207], v149 offset:5120
	ds_read_b128 v[208:211], v149 offset:6144
	ds_read_b128 v[212:215], v149 offset:7168
	global_load_lds_dwordx4 v[216:217], off
	v_lshl_add_u64 v[216:217], s[14:15], 0, v[136:137]
	s_add_i32 m0, s24, 0xe000
	s_nop 0
	global_load_lds_dwordx4 v[216:217], off
	s_waitcnt vmcnt(8)
	s_waitcnt lgkmcnt(0)
	s_barrier
	s_waitcnt lgkmcnt(0)
	v_mfma_f32_16x16x32_bf16 v[124:127], v[152:155], v[184:187], v[124:127]
	v_mfma_f32_16x16x32_bf16 v[120:123], v[160:163], v[184:187], v[120:123]
	v_mfma_f32_16x16x32_bf16 v[112:115], v[152:155], v[192:195], v[112:115]
	v_mfma_f32_16x16x32_bf16 v[104:107], v[160:163], v[192:195], v[104:107]
	v_mfma_f32_16x16x32_bf16 v[92:95], v[152:155], v[200:203], v[92:95]
	v_mfma_f32_16x16x32_bf16 v[88:91], v[160:163], v[200:203], v[88:91]
	v_mfma_f32_16x16x32_bf16 v[76:79], v[152:155], v[208:211], v[76:79]
	v_mfma_f32_16x16x32_bf16 v[72:75], v[160:163], v[208:211], v[72:75]
	v_mfma_f32_16x16x32_bf16 v[124:127], v[156:159], v[188:191], v[124:127]
	v_mfma_f32_16x16x32_bf16 v[120:123], v[164:167], v[188:191], v[120:123]
	v_mfma_f32_16x16x32_bf16 v[112:115], v[156:159], v[196:199], v[112:115]
	v_mfma_f32_16x16x32_bf16 v[104:107], v[164:167], v[196:199], v[104:107]
	v_mfma_f32_16x16x32_bf16 v[92:95], v[156:159], v[204:207], v[92:95]
	v_mfma_f32_16x16x32_bf16 v[88:91], v[164:167], v[204:207], v[88:91]
	v_mfma_f32_16x16x32_bf16 v[76:79], v[156:159], v[212:215], v[76:79]
	v_mfma_f32_16x16x32_bf16 v[72:75], v[164:167], v[212:215], v[72:75]
	v_mfma_f32_16x16x32_bf16 v[116:119], v[168:171], v[184:187], v[116:119]
	v_mfma_f32_16x16x32_bf16 v[108:111], v[176:179], v[184:187], v[108:111]
	v_mfma_f32_16x16x32_bf16 v[100:103], v[168:171], v[192:195], v[100:103]
	v_mfma_f32_16x16x32_bf16 v[96:99], v[176:179], v[192:195], v[96:99]
	v_mfma_f32_16x16x32_bf16 v[84:87], v[168:171], v[200:203], v[84:87]
	v_mfma_f32_16x16x32_bf16 v[80:83], v[176:179], v[200:203], v[80:83]
	v_mfma_f32_16x16x32_bf16 v[68:71], v[168:171], v[208:211], v[68:71]
	v_mfma_f32_16x16x32_bf16 v[64:67], v[176:179], v[208:211], v[64:67]
	v_mfma_f32_16x16x32_bf16 v[116:119], v[172:175], v[188:191], v[116:119]
	v_mfma_f32_16x16x32_bf16 v[108:111], v[180:183], v[188:191], v[108:111]
	v_mfma_f32_16x16x32_bf16 v[100:103], v[172:175], v[196:199], v[100:103]
	v_mfma_f32_16x16x32_bf16 v[96:99], v[180:183], v[196:199], v[96:99]
	v_mfma_f32_16x16x32_bf16 v[84:87], v[172:175], v[204:207], v[84:87]
	v_mfma_f32_16x16x32_bf16 v[80:83], v[180:183], v[204:207], v[80:83]
	v_mfma_f32_16x16x32_bf16 v[68:71], v[172:175], v[212:215], v[68:71]
	v_mfma_f32_16x16x32_bf16 v[64:67], v[180:183], v[212:215], v[64:67]
	s_barrier
	s_add_i32 s14, s34, s23
	s_mov_b32 m0, s14
	ds_read_b128 v[184:187], v149 offset:16384
	ds_read_b128 v[188:191], v149 offset:17408
	ds_read_b128 v[192:195], v149 offset:18432
	ds_read_b128 v[196:199], v149 offset:19456
	ds_read_b128 v[200:203], v149 offset:20480
	ds_read_b128 v[204:207], v149 offset:21504
	ds_read_b128 v[208:211], v149 offset:22528
	ds_read_b128 v[212:215], v149 offset:23552
	global_load_lds_dwordx4 v130, s[18:19]
	s_add_i32 m0, s14, 0x2000
	s_add_u32 s14, s18, 0x58000
	v_lshl_add_u64 v[218:219], s[18:19], 0, v[134:135]
	s_addc_u32 s15, s19, 0
	s_add_i32 s41, s35, s23
	global_load_lds_dwordx4 v134, s[18:19]
	s_mov_b32 m0, s41
	s_nop 0
	global_load_lds_dwordx4 v130, s[14:15]
	s_add_i32 m0, s41, 0x2000
	s_nop 0
	global_load_lds_dwordx4 v134, s[14:15]
	s_mov_b32 m0, s24
	s_nop 0
	global_load_lds_dwordx4 v128, s[20:21]
	s_mov_b32 m0, s25
	s_nop 0
	global_load_lds_dwordx4 v132, s[20:21]
	s_waitcnt vmcnt(8)
	s_waitcnt lgkmcnt(0)
	s_barrier
	s_waitcnt lgkmcnt(0)
	v_mfma_f32_16x16x32_bf16 v[60:63], v[152:155], v[184:187], v[60:63]
	v_mfma_f32_16x16x32_bf16 v[56:59], v[160:163], v[184:187], v[56:59]
	v_mfma_f32_16x16x32_bf16 v[44:47], v[152:155], v[192:195], v[44:47]
	v_mfma_f32_16x16x32_bf16 v[40:43], v[160:163], v[192:195], v[40:43]
	v_mfma_f32_16x16x32_bf16 v[28:31], v[152:155], v[200:203], v[28:31]
	v_mfma_f32_16x16x32_bf16 v[24:27], v[160:163], v[200:203], v[24:27]
	v_mfma_f32_16x16x32_bf16 v[12:15], v[152:155], v[208:211], v[12:15]
	v_mfma_f32_16x16x32_bf16 v[8:11], v[160:163], v[208:211], v[8:11]
	v_mfma_f32_16x16x32_bf16 v[60:63], v[156:159], v[188:191], v[60:63]
	v_mfma_f32_16x16x32_bf16 v[56:59], v[164:167], v[188:191], v[56:59]
	v_mfma_f32_16x16x32_bf16 v[44:47], v[156:159], v[196:199], v[44:47]
	v_mfma_f32_16x16x32_bf16 v[40:43], v[164:167], v[196:199], v[40:43]
	v_mfma_f32_16x16x32_bf16 v[28:31], v[156:159], v[204:207], v[28:31]
	v_mfma_f32_16x16x32_bf16 v[24:27], v[164:167], v[204:207], v[24:27]
	v_mfma_f32_16x16x32_bf16 v[12:15], v[156:159], v[212:215], v[12:15]
	v_mfma_f32_16x16x32_bf16 v[8:11], v[164:167], v[212:215], v[8:11]
	v_mfma_f32_16x16x32_bf16 v[52:55], v[168:171], v[184:187], v[52:55]
	v_mfma_f32_16x16x32_bf16 v[48:51], v[176:179], v[184:187], v[48:51]
	v_mfma_f32_16x16x32_bf16 v[36:39], v[168:171], v[192:195], v[36:39]
	v_mfma_f32_16x16x32_bf16 v[32:35], v[176:179], v[192:195], v[32:35]
	v_mfma_f32_16x16x32_bf16 v[20:23], v[168:171], v[200:203], v[20:23]
	v_mfma_f32_16x16x32_bf16 v[16:19], v[176:179], v[200:203], v[16:19]
	v_mfma_f32_16x16x32_bf16 v[4:7], v[168:171], v[208:211], v[4:7]
	v_mfma_f32_16x16x32_bf16 v[0:3], v[176:179], v[208:211], v[0:3]
	v_mfma_f32_16x16x32_bf16 v[52:55], v[172:175], v[188:191], v[52:55]
	v_mfma_f32_16x16x32_bf16 v[48:51], v[180:183], v[188:191], v[48:51]
	v_mfma_f32_16x16x32_bf16 v[36:39], v[172:175], v[196:199], v[36:39]
	v_mfma_f32_16x16x32_bf16 v[32:35], v[180:183], v[196:199], v[32:35]
	v_mfma_f32_16x16x32_bf16 v[20:23], v[172:175], v[204:207], v[20:23]
	v_mfma_f32_16x16x32_bf16 v[16:19], v[180:183], v[204:207], v[16:19]
	v_mfma_f32_16x16x32_bf16 v[4:7], v[172:175], v[212:215], v[4:7]
	v_mfma_f32_16x16x32_bf16 v[0:3], v[180:183], v[212:215], v[0:3]
	s_barrier
; #define PG8_STAGE(bufoff, gbase, voff) do { _Pragma("unroll") for (int _i = 0; _i < 2; ++_i) \
;         __builtin_amdgcn_global_load_lds((const unsigned*)((const char*)(gbase) + (voff)[_i]), (LAS unsigned*)(lds + (bufoff) + ldsw + _i * 8192), 16, 0, 0); } while (0)
; #define PG8_LDA(dst, b, h) do { _Pragma("unroll") for (int m = 0; m < 4; ++m) _Pragma("unroll") for (int k = 0; k < 2; ++k) dst[m][k] = *(const LAS bf16x8*)(lds + PG8_SA(b, h) + aoff + m * 2048 + k * 1024); } while (0)
; #define PG8_LDB(dst, b, h) do { _Pragma("unroll") for (int n = 0; n < 2; ++n) _Pragma("unroll") for (int k = 0; k < 2; ++k) dst[n][k] = *(const LAS bf16x8*)(lds + PG8_SB(b, h) + boff + n * 2048 + k * 1024); } while (0)
; #define PG8_MMA(ai, bj, At, Bt) do { __builtin_amdgcn_s_setprio(1); _Pragma("unroll") for (int m = 0; m < 4; ++m) _Pragma("unroll") for (int n = 0; n < 2; ++n) _Pragma("unroll") for (int k = 0; k < 2; ++k) \
;         acc[ai][bj][m][n] = __builtin_amdgcn_mfma_f32_16x16x32_bf16(Bt[n][k], At[m][k], acc[ai][bj][m][n], 0, 0, 0); __builtin_amdgcn_s_setprio(0); } while (0)
; #define PG8_WAIT_V(n) asm volatile("s_waitcnt vmcnt(" #n ")" ::: "memory")
; #define PG8_WAIT_L(n) asm volatile("s_waitcnt lgkmcnt(" #n ")" ::: "memory")
; #define PG8_BAR __builtin_amdgcn_s_barrier()
; #define PG8_SCHED __builtin_amdgcn_sched_barrier(0)
; template <class Epi, class Sched, bool ALIGN_EPI = false, bool SP2 = false>
; __device__ __forceinline__ void gemm_phase(LAS unsigned char* lds, const Gemm g, const Sched& S, const Epi& E) {
;     ...
;             PG8_LDB(B0, 1, 0); PG8_LDB(B1, 1, 1); PG8_SCHED; PG8_LDA(At, 1, 0); PG8_STAGE(PG8_SA(0, 1), a2 + hstep, voffA);
;             PG8_WAIT_V(8); PG8_WAIT_L(0); PG8_BAR; PG8_MMA(0, 0, At, B0); PG8_MMA(0, 1, At, B1); PG8_BAR; PG8_SCHED;
;             PG8_LDA(At, 1, 1); PG8_STAGE(PG8_SB(1, 0), b3, voffB); PG8_STAGE(PG8_SB(1, 1), b3 + hstepB, voffB); PG8_STAGE(PG8_SA(1, 0), a3, voffA);
;             PG8_WAIT_V(8); PG8_WAIT_L(0); PG8_BAR; PG8_MMA(1, 0, At, B0); PG8_MMA(1, 1, At, B1); PG8_BAR; PG8_SCHED;
;     ...
;         if constexpr (ALIGN_EPI) { if (wr == 0) PG8_BAR; }
	s_add_i32 s41, 0, 0x18000
	s_add_i32 s42, 0, 0x1c000
	v_add_u32_e32 v164, s41, v144
	v_add_u32_e32 v180, s42, v144
	ds_read_b128 v[152:155], v164
	ds_read_b128 v[156:159], v164 offset:1024
	ds_read_b128 v[160:163], v164 offset:2048
	ds_read_b128 v[164:167], v164 offset:3072
	ds_read_b128 v[168:171], v180
	ds_read_b128 v[172:175], v180 offset:1024
	ds_read_b128 v[176:179], v180 offset:2048
	ds_read_b128 v[180:183], v180 offset:3072
	s_add_u32 s14, s20, 0x160000
	s_addc_u32 s15, s21, 0
	s_mov_b32 m0, s26
	ds_read_b128 v[184:187], v149 offset:32768
	ds_read_b128 v[188:191], v149 offset:33792
	ds_read_b128 v[192:195], v149 offset:34816
	ds_read_b128 v[196:199], v149 offset:35840
	ds_read_b128 v[200:203], v149 offset:36864
	ds_read_b128 v[204:207], v149 offset:37888
	ds_read_b128 v[208:211], v149 offset:38912
	ds_read_b128 v[212:215], v149 offset:39936
	global_load_lds_dwordx4 v128, s[14:15]
	s_mov_b32 m0, s27
	s_nop 0
	global_load_lds_dwordx4 v132, s[14:15]
	s_waitcnt vmcnt(8)
	s_waitcnt lgkmcnt(0)
	s_barrier
	s_waitcnt lgkmcnt(0)
	v_mfma_f32_16x16x32_bf16 v[124:127], v[152:155], v[184:187], v[124:127]
	v_mfma_f32_16x16x32_bf16 v[120:123], v[160:163], v[184:187], v[120:123]
	v_mfma_f32_16x16x32_bf16 v[112:115], v[152:155], v[192:195], v[112:115]
	v_mfma_f32_16x16x32_bf16 v[104:107], v[160:163], v[192:195], v[104:107]
	v_mfma_f32_16x16x32_bf16 v[92:95], v[152:155], v[200:203], v[92:95]
	v_mfma_f32_16x16x32_bf16 v[88:91], v[160:163], v[200:203], v[88:91]
	v_mfma_f32_16x16x32_bf16 v[76:79], v[152:155], v[208:211], v[76:79]
	v_mfma_f32_16x16x32_bf16 v[72:75], v[160:163], v[208:211], v[72:75]
	v_mfma_f32_16x16x32_bf16 v[124:127], v[156:159], v[188:191], v[124:127]
	v_mfma_f32_16x16x32_bf16 v[120:123], v[164:167], v[188:191], v[120:123]
	v_mfma_f32_16x16x32_bf16 v[112:115], v[156:159], v[196:199], v[112:115]
	v_mfma_f32_16x16x32_bf16 v[104:107], v[164:167], v[196:199], v[104:107]
	v_mfma_f32_16x16x32_bf16 v[92:95], v[156:159], v[204:207], v[92:95]
	v_mfma_f32_16x16x32_bf16 v[88:91], v[164:167], v[204:207], v[88:91]
	v_mfma_f32_16x16x32_bf16 v[76:79], v[156:159], v[212:215], v[76:79]
	v_mfma_f32_16x16x32_bf16 v[72:75], v[164:167], v[212:215], v[72:75]
	v_mfma_f32_16x16x32_bf16 v[116:119], v[168:171], v[184:187], v[116:119]
	v_mfma_f32_16x16x32_bf16 v[108:111], v[176:179], v[184:187], v[108:111]
	v_mfma_f32_16x16x32_bf16 v[100:103], v[168:171], v[192:195], v[100:103]
	v_mfma_f32_16x16x32_bf16 v[96:99], v[176:179], v[192:195], v[96:99]
	v_mfma_f32_16x16x32_bf16 v[84:87], v[168:171], v[200:203], v[84:87]
	v_mfma_f32_16x16x32_bf16 v[80:83], v[176:179], v[200:203], v[80:83]
	v_mfma_f32_16x16x32_bf16 v[68:71], v[168:171], v[208:211], v[68:71]
	v_mfma_f32_16x16x32_bf16 v[64:67], v[176:179], v[208:211], v[64:67]
	v_mfma_f32_16x16x32_bf16 v[116:119], v[172:175], v[188:191], v[116:119]
	v_mfma_f32_16x16x32_bf16 v[108:111], v[180:183], v[188:191], v[108:111]
	v_mfma_f32_16x16x32_bf16 v[100:103], v[172:175], v[196:199], v[100:103]
	v_mfma_f32_16x16x32_bf16 v[96:99], v[180:183], v[196:199], v[96:99]
	v_mfma_f32_16x16x32_bf16 v[84:87], v[172:175], v[204:207], v[84:87]
	v_mfma_f32_16x16x32_bf16 v[80:83], v[180:183], v[204:207], v[80:83]
	v_mfma_f32_16x16x32_bf16 v[68:71], v[172:175], v[212:215], v[68:71]
	v_mfma_f32_16x16x32_bf16 v[64:67], v[180:183], v[212:215], v[64:67]
	s_barrier
	s_add_u32 s98, s18, 0x80
	s_addc_u32 s99, s19, 0
	s_add_u32 s100, s20, 0x80
	s_addc_u32 s101, s21, 0
	s_add_i32 s14, s41, s23
	s_mov_b32 m0, s14
	ds_read_b128 v[184:187], v149 offset:49152
	ds_read_b128 v[188:191], v149 offset:50176
	ds_read_b128 v[192:195], v149 offset:51200
	ds_read_b128 v[196:199], v149 offset:52224
	ds_read_b128 v[200:203], v149 offset:53248
	ds_read_b128 v[204:207], v149 offset:54272
	ds_read_b128 v[208:211], v149 offset:55296
	ds_read_b128 v[212:215], v149 offset:56320
	global_load_lds_dwordx4 v130, s[98:99]
	s_add_i32 m0, s14, 0x2000
	s_add_u32 s14, s18, 0x58080
	v_lshl_add_u64 v[216:217], v[218:219], 0, s[6:7]
	s_addc_u32 s15, s19, 0
	s_add_i32 s18, s42, s23
	global_load_lds_dwordx4 v[216:217], off
	s_mov_b32 m0, s18
	s_nop 0
	global_load_lds_dwordx4 v130, s[14:15]
	s_add_i32 m0, s18, 0x2000
	s_nop 0
	global_load_lds_dwordx4 v134, s[14:15]
	s_mov_b32 m0, s31
	s_nop 0
	global_load_lds_dwordx4 v128, s[100:101]
	s_mov_b32 m0, s33
	s_nop 0
	global_load_lds_dwordx4 v132, s[100:101]
	s_waitcnt vmcnt(8)
	s_waitcnt lgkmcnt(0)
	s_barrier
	s_waitcnt lgkmcnt(0)
	v_mfma_f32_16x16x32_bf16 v[60:63], v[152:155], v[184:187], v[60:63]
	v_mfma_f32_16x16x32_bf16 v[56:59], v[160:163], v[184:187], v[56:59]
	v_mfma_f32_16x16x32_bf16 v[44:47], v[152:155], v[192:195], v[44:47]
	v_mfma_f32_16x16x32_bf16 v[40:43], v[160:163], v[192:195], v[40:43]
	v_mfma_f32_16x16x32_bf16 v[28:31], v[152:155], v[200:203], v[28:31]
	v_mfma_f32_16x16x32_bf16 v[24:27], v[160:163], v[200:203], v[24:27]
	v_mfma_f32_16x16x32_bf16 v[12:15], v[152:155], v[208:211], v[12:15]
	v_mfma_f32_16x16x32_bf16 v[8:11], v[160:163], v[208:211], v[8:11]
	v_mfma_f32_16x16x32_bf16 v[60:63], v[156:159], v[188:191], v[60:63]
	v_mfma_f32_16x16x32_bf16 v[56:59], v[164:167], v[188:191], v[56:59]
	v_mfma_f32_16x16x32_bf16 v[44:47], v[156:159], v[196:199], v[44:47]
	v_mfma_f32_16x16x32_bf16 v[40:43], v[164:167], v[196:199], v[40:43]
	v_mfma_f32_16x16x32_bf16 v[28:31], v[156:159], v[204:207], v[28:31]
	v_mfma_f32_16x16x32_bf16 v[24:27], v[164:167], v[204:207], v[24:27]
	v_mfma_f32_16x16x32_bf16 v[12:15], v[156:159], v[212:215], v[12:15]
	v_mfma_f32_16x16x32_bf16 v[8:11], v[164:167], v[212:215], v[8:11]
	v_mfma_f32_16x16x32_bf16 v[52:55], v[168:171], v[184:187], v[52:55]
	v_mfma_f32_16x16x32_bf16 v[48:51], v[176:179], v[184:187], v[48:51]
	v_mfma_f32_16x16x32_bf16 v[36:39], v[168:171], v[192:195], v[36:39]
	v_mfma_f32_16x16x32_bf16 v[32:35], v[176:179], v[192:195], v[32:35]
	v_mfma_f32_16x16x32_bf16 v[20:23], v[168:171], v[200:203], v[20:23]
	v_mfma_f32_16x16x32_bf16 v[16:19], v[176:179], v[200:203], v[16:19]
	v_mfma_f32_16x16x32_bf16 v[4:7], v[168:171], v[208:211], v[4:7]
	v_mfma_f32_16x16x32_bf16 v[0:3], v[176:179], v[208:211], v[0:3]
	v_mfma_f32_16x16x32_bf16 v[52:55], v[172:175], v[188:191], v[52:55]
	v_mfma_f32_16x16x32_bf16 v[48:51], v[180:183], v[188:191], v[48:51]
	v_mfma_f32_16x16x32_bf16 v[36:39], v[172:175], v[196:199], v[36:39]
	v_mfma_f32_16x16x32_bf16 v[32:35], v[180:183], v[196:199], v[32:35]
	v_mfma_f32_16x16x32_bf16 v[20:23], v[172:175], v[204:207], v[20:23]
	v_mfma_f32_16x16x32_bf16 v[16:19], v[180:183], v[204:207], v[16:19]
	v_mfma_f32_16x16x32_bf16 v[4:7], v[172:175], v[212:215], v[4:7]
	v_mfma_f32_16x16x32_bf16 v[0:3], v[180:183], v[212:215], v[0:3]
	s_barrier
	s_add_i32 s40, s40, 2
	s_add_u32 s13, s13, 0x100
	s_addc_u32 s39, s39, 0
	s_cmpk_lt_u32 s40, 0x56
	s_mov_b64 s[14:15], s[16:17]
	s_cbranch_scc1 .LBB0_3002
	s_setprio 0
	s_andn2_b64 vcc, exec, s[8:9]
	s_cbranch_vccnz .LBB0_3005
	s_barrier
